# speedup vs baseline: 1.0030x; 1.0030x over previous
; #define WAIT_V(n) asm volatile("s_waitcnt vmcnt(" #n ")" ::: "memory")
; #define WAIT_L(n) asm volatile("s_waitcnt lgkmcnt(" #n ")" ::: "memory")
; #define BAR __builtin_amdgcn_s_barrier()
; #define SCHED __builtin_amdgcn_sched_barrier(0)
; #define STG_A(b, h, kt) stage_half_s(lds0 + ((b) * 2 + (h)) * HT_B, ((h) ? A1 : Ap) + (kt) * BK, off0, off1)
; #define STG_A(b, h, kt) stage_half_s(lds0 + ((b) * 2 + (h)) * HT_B, ((h) ? A1 : Ap) + (kt) * BK, off0, off1)
; #define LDA8(b, h) _Pragma("unroll") for (int m = 0; m < 4; ++m) _Pragma("unroll") for (int k = 0; k < 2; ++k) \
;     At[m][k] = *(const bf16x8*)(SA_(shm, b, h) + abase + (m * 2 + k) * 1024)
; #define LDB8(dst, b, h) _Pragma("unroll") for (int n = 0; n < 2; ++n) _Pragma("unroll") for (int k = 0; k < 2; ++k) \
;     dst[n][k] = *(const bf16x8*)(SB_(shm, b, h) + bbase + (n * 2 + k) * 1024)
; template <bool HS>
; __device__ __forceinline__ void gemm_tile8(const u16* __restrict__ Ap, const u16* __restrict__ Bp, int K,
;                                            f32x4 (&acc)[2][2][4][2], char* shm, const int tid, const float* hsr = nullptr) {
;   const int wid = tid >> 6, lane = tid & 63, wr = wid >> 2, wc = wid & 3, fr = lane & 15, fq = lane >> 4;
;   int r0, c0, r1, c1;
;   stage_rc(tid * 16, r0, c0);
;   stage_rc(tid * 16 + 8192, r1, c1);
;   const unsigned off0 = (unsigned)(r0 * K + c0) * 2u, off1 = (unsigned)(r1 * K + c1) * 2u;
;   const int wvoff = __builtin_amdgcn_readfirstlane(tid >> 6) * 1024;
;   const u16* A1 = Ap + (size_t)128 * K;
;   const u16* B1p = Bp + (size_t)128 * K;
; #pragma unroll
;   for (int a = 0; a < 2; ++a)
; #pragma unroll
;     for (int b = 0; b < 2; ++b)
; #pragma unroll
;       for (int m = 0; m < 4; ++m)
; #pragma unroll
;         for (int n = 0; n < 2; ++n) acc[a][b][m][n] = f32x4{0.f, 0.f, 0.f, 0.f};
;   const int abase = lds_byte(wr * 64 + fr, fq * 8), bbase = lds_byte(wc * 32 + fr, fq * 8);
;   bf16x8 At[4][2], B0[2][2], B1[2][2];
;   const unsigned lds0 = (unsigned)(size_t)(__attribute__((address_space(3))) char*)shm + (unsigned)wvoff;
;     ...
;   const int nt = K / BK;
;   WAIT_V(0);
;   if (wr == 1) BAR;
;   BAR;
;     ...
;     LDB8(B0, 0, 0); SCHED; LDA8(0, 0); STG_A(1, 1, t + 1);
;     WAIT_L(8); BAR; WAIT_L(0); MMA8(0, 0, B0); BAR; SCHED;
.LBB0_98:
	s_or_b64 exec, exec, s[2:3]
	v_mov_b32_e32 v4, s14
	v_bfe_i32 v4, v4, 0, 8
	v_ashrrev_i32_e32 v5, 31, v4
	v_lshlrev_b64 v[4:5], 19, v[4:5]
	v_bfe_i32 v6, v0, 27, 1
	v_lshl_add_u64 v[130:131], s[0:1], 0, v[4:5]
	v_lshlrev_b32_e32 v4, 4, v0
	v_lshrrev_b32_e32 v6, 22, v6
	v_add_u32_e32 v6, v4, v6
	v_and_b32_e32 v6, 0xfffffc00, v6
	v_ashrrev_i32_e32 v5, 31, v0
	v_sub_u32_e32 v6, v4, v6
	v_lshrrev_b32_e32 v5, 26, v5
	v_lshrrev_b32_e32 v7, 4, v6
	v_add_u32_e32 v5, v0, v5
	v_bitop3_b32 v7, v7, v6, 32 bitop3:0x6c
	v_ashrrev_i32_e32 v6, 31, v6
	v_ashrrev_i32_e32 v5, 6, v5
	v_lshrrev_b32_e32 v6, 26, v6
	v_lshlrev_b32_e32 v8, 3, v5
	v_add_u32_e32 v6, v7, v6
	v_and_b32_e32 v8, 0x1ffff0, v8
	v_ashrrev_i32_e32 v6, 6, v6
	v_add_u32_e32 v8, v6, v8
	v_mul_i32_i24_e32 v6, 64, v6
	v_add_u32_e32 v4, 0x2000, v4
	v_sub_u32_e32 v6, v7, v6
	v_ashrrev_i32_e32 v7, 31, v4
	v_lshrrev_b32_e32 v7, 22, v7
	v_add_u32_e32 v7, v4, v7
	v_ashrrev_i32_e32 v7, 10, v7
	v_mul_i32_i24_e32 v9, 0x400, v7
	v_sub_u32_e32 v4, v4, v9
	v_lshrrev_b32_e32 v9, 4, v4
	v_bitop3_b32 v4, v9, v4, 32 bitop3:0x6c
	v_ashrrev_i32_e32 v10, 31, v4
	v_lshrrev_b32_e32 v10, 26, v10
	v_add_u32_e32 v10, v4, v10
	v_lshlrev_b32_e32 v9, 3, v7
	v_lshrrev_b32_e32 v11, 6, v10
	v_and_b32_e32 v10, 0xc0, v10
	s_ashr_i32 s5, s4, 31
	v_and_b32_e32 v9, 0x1ffff0, v9
	v_lshlrev_b32_e32 v7, 5, v7
	v_sub_u32_e32 v4, v4, v10
	s_lshl_b64 s[10:11], s[4:5], 11
	v_readlane_b32 s2, v253, 63
	v_lshlrev_b32_e32 v5, 5, v5
	v_add_u32_e32 v9, v11, v9
	v_and_b32_e32 v7, 32, v7
	v_ashrrev_i16_sdwa v4, v178, sext(v4) dst_sel:DWORD dst_unused:UNUSED_PAD src0_sel:DWORD src1_sel:BYTE_0
	v_readlane_b32 s3, v254, 0
	s_add_u32 s9, s2, s10
	v_and_b32_e32 v5, 32, v5
	v_ashrrev_i16_sdwa v6, v178, sext(v6) dst_sel:DWORD dst_unused:UNUSED_PAD src0_sel:DWORD src1_sel:BYTE_0
	v_bfe_i32 v4, v4, 0, 16
	v_lshl_or_b32 v7, v9, 10, v7
	s_addc_u32 s12, s3, s11
	v_bfe_i32 v6, v6, 0, 16
	v_lshl_or_b32 v5, v8, 10, v5
	v_and_b32_e32 v8, 15, v0
	v_add_lshl_u32 v135, v7, v4, 1
	s_lshl_b32 s13, s13, 10
	v_lshlrev_b32_e32 v7, 2, v0
	v_add_lshl_u32 v136, v5, v6, 1
	s_mov_b64 s[2:3], 0x40000
	v_and_b32_e32 v4, 48, v0
	v_lshlrev_b32_e32 v5, 6, v8
	v_and_b32_e32 v7, 32, v7
	s_add_i32 s14, s13, 0
	v_lshl_add_u64 v[132:133], v[130:131], 0, s[2:3]
	v_or_b32_e32 v6, v5, v4
	v_bitop3_b32 v4, v5, v7, v4 bitop3:0x36
	v_lshlrev_b32_e32 v2, 12, v2
	s_movk_i32 s2, 0x3000
	s_add_u32 s15, s9, 0x40100
	v_lshlrev_b32_e32 v3, 13, v3
	v_and_or_b32 v137, v2, s2, v4
	s_addc_u32 s16, s12, 0
	v_readlane_b32 s2, v254, 32
	v_bitop3_b32 v3, v6, v3, v7 bitop3:0xde
	s_add_u32 s17, s2, s10
	v_readlane_b32 s2, v254, 33
	v_mov_b32_e32 v2, 0
	s_addc_u32 s18, s2, s11
	s_mov_b32 s19, -2
	s_mov_b64 s[2:3], 0
	v_add_u32_e32 v134, 0, v3
	s_waitcnt lgkmcnt(0)
	v_readfirstlane_b32 s24, v130
	v_readfirstlane_b32 s25, v131
	v_readfirstlane_b32 s26, v132
	v_readfirstlane_b32 s27, v133
	s_barrier
	s_barrier
	v_add_u32_e32 v158, 0x10000, v137
	ds_read_b128 v[138:141], v158
	ds_read_b128 v[142:145], v158 offset:1024
	ds_read_b128 v[154:157], v158 offset:2048
	ds_read_b128 v[158:161], v158 offset:3072
	ds_read_b128 v[162:165], v134
	ds_read_b128 v[166:169], v134 offset:1024
	ds_read_b128 v[170:173], v134 offset:2048
	ds_read_b128 v[174:177], v134 offset:3072
	ds_read_b128 v[180:183], v134 offset:4096
	ds_read_b128 v[184:187], v134 offset:5120
	ds_read_b128 v[188:191], v134 offset:6144
	ds_read_b128 v[192:195], v134 offset:7168
	v_add_u32_e32 v208, 0x14000, v137
	ds_read_b128 v[196:199], v208
	ds_read_b128 v[200:203], v208 offset:1024
	ds_read_b128 v[204:207], v208 offset:2048
	ds_read_b128 v[208:211], v208 offset:3072
	s_add_u32 s22, s17, s2
	s_addc_u32 s23, s18, s3
	s_add_u32 s22, s22, 0x80
	s_addc_u32 s23, s23, 0
	s_add_i32 s36, s14, 0xc000
	s_mov_b32 m0, s36
	s_nop 0
	global_load_lds_dwordx4 v136, s[22:23]
	s_add_i32 s36, s14, 0xe000
	s_mov_b32 m0, s36
	s_nop 0
	global_load_lds_dwordx4 v135, s[22:23]
	s_waitcnt vmcnt(8) lgkmcnt(0)
	s_barrier
	s_setprio 1
	v_mfma_f32_16x16x32_bf16 v[126:129], v[162:165], v[138:141], 0
	v_mfma_f32_16x16x32_bf16 v[122:125], v[162:165], v[154:157], 0
	v_mfma_f32_16x16x32_bf16 v[118:121], v[170:173], v[138:141], 0
	v_mfma_f32_16x16x32_bf16 v[114:117], v[170:173], v[154:157], 0
	v_mfma_f32_16x16x32_bf16 v[110:113], v[180:183], v[138:141], 0
	v_mfma_f32_16x16x32_bf16 v[106:109], v[180:183], v[154:157], 0
	v_mfma_f32_16x16x32_bf16 v[102:105], v[188:191], v[138:141], 0
	v_mfma_f32_16x16x32_bf16 v[98:101], v[188:191], v[154:157], 0
	v_mfma_f32_16x16x32_bf16 v[126:129], v[166:169], v[142:145], v[126:129]
	v_mfma_f32_16x16x32_bf16 v[122:125], v[166:169], v[158:161], v[122:125]
	v_mfma_f32_16x16x32_bf16 v[118:121], v[174:177], v[142:145], v[118:121]
	v_mfma_f32_16x16x32_bf16 v[114:117], v[174:177], v[158:161], v[114:117]
	v_mfma_f32_16x16x32_bf16 v[110:113], v[184:187], v[142:145], v[110:113]
	v_mfma_f32_16x16x32_bf16 v[106:109], v[184:187], v[158:161], v[106:109]
	v_mfma_f32_16x16x32_bf16 v[102:105], v[192:195], v[142:145], v[102:105]
	v_mfma_f32_16x16x32_bf16 v[98:101], v[192:195], v[158:161], v[98:101]
	v_mfma_f32_16x16x32_bf16 v[94:97], v[162:165], v[196:199], 0
	v_mfma_f32_16x16x32_bf16 v[90:93], v[162:165], v[204:207], 0
	v_mfma_f32_16x16x32_bf16 v[86:89], v[170:173], v[196:199], 0
	v_mfma_f32_16x16x32_bf16 v[82:85], v[170:173], v[204:207], 0
	v_mfma_f32_16x16x32_bf16 v[78:81], v[180:183], v[196:199], 0
	v_mfma_f32_16x16x32_bf16 v[74:77], v[180:183], v[204:207], 0
	v_mfma_f32_16x16x32_bf16 v[70:73], v[188:191], v[196:199], 0
	v_mfma_f32_16x16x32_bf16 v[66:69], v[188:191], v[204:207], 0
	v_mfma_f32_16x16x32_bf16 v[94:97], v[166:169], v[200:203], v[94:97]
	v_mfma_f32_16x16x32_bf16 v[90:93], v[166:169], v[208:211], v[90:93]
	v_mfma_f32_16x16x32_bf16 v[86:89], v[174:177], v[200:203], v[86:89]
	v_mfma_f32_16x16x32_bf16 v[82:85], v[174:177], v[208:211], v[82:85]
	v_mfma_f32_16x16x32_bf16 v[78:81], v[184:187], v[200:203], v[78:81]
	v_mfma_f32_16x16x32_bf16 v[74:77], v[184:187], v[208:211], v[74:77]
	v_mfma_f32_16x16x32_bf16 v[70:73], v[192:195], v[200:203], v[70:73]
	v_mfma_f32_16x16x32_bf16 v[66:69], v[192:195], v[208:211], v[66:69]
	s_setprio 0
	s_barrier
; #define WAIT_V(n) asm volatile("s_waitcnt vmcnt(" #n ")" ::: "memory")
; #define WAIT_L(n) asm volatile("s_waitcnt lgkmcnt(" #n ")" ::: "memory")
; #define BAR __builtin_amdgcn_s_barrier()
; #define SCHED __builtin_amdgcn_sched_barrier(0)
; #define STG_A(b, h, kt) stage_half_s(lds0 + ((b) * 2 + (h)) * HT_B, ((h) ? A1 : Ap) + (kt) * BK, off0, off1)
; #define STG_B(b, h, kt) stage_half_s(lds0 + (4 + (b) * 2 + (h)) * HT_B, ((h) ? B1p : Bp) + (kt) * BK, off0, off1)
; #define STG_A(b, h, kt) stage_half_s(lds0 + ((b) * 2 + (h)) * HT_B, ((h) ? A1 : Ap) + (kt) * BK, off0, off1)
; #define STG_B(b, h, kt) stage_half_s(lds0 + (4 + (b) * 2 + (h)) * HT_B, ((h) ? B1p : Bp) + (kt) * BK, off0, off1)
; #define LDA8(b, h) _Pragma("unroll") for (int m = 0; m < 4; ++m) _Pragma("unroll") for (int k = 0; k < 2; ++k) \
;     At[m][k] = *(const bf16x8*)(SA_(shm, b, h) + abase + (m * 2 + k) * 1024)
; #define LDB8(dst, b, h) _Pragma("unroll") for (int n = 0; n < 2; ++n) _Pragma("unroll") for (int k = 0; k < 2; ++k) \
;     dst[n][k] = *(const bf16x8*)(SB_(shm, b, h) + bbase + (n * 2 + k) * 1024)
; #define MMA8(ai, bj, Bx) do { __builtin_amdgcn_s_setprio(1); \
;     _Pragma("unroll") for (int m = 0; m < 4; ++m) _Pragma("unroll") for (int n = 0; n < 2; ++n) _Pragma("unroll") for (int k = 0; k < 2; ++k) \
;       acc[ai][bj][m][n] = __builtin_amdgcn_mfma_f32_16x16x32_bf16(At[m][k], Bx[n][k], acc[ai][bj][m][n], 0, 0, 0); \
;     __builtin_amdgcn_s_setprio(0); } while (0)
; template <bool HS>
; __device__ __forceinline__ void gemm_tile8(const u16* __restrict__ Ap, const u16* __restrict__ Bp, int K,
;                                            f32x4 (&acc)[2][2][4][2], char* shm, const int tid, const float* hsr = nullptr) {
;     ...
;     LDA8(0, 1); STG_A(0, 0, t + 2);
;     BAR; WAIT_L(0); MMA8(1, 0, B0); BAR; SCHED;
;     STG_B(0, 1, t + 2);
;     WAIT_V(6); BAR; MMA8(1, 1, B1); BAR;
;     LDB8(B0, 1, 0); SCHED; LDA8(1, 0); STG_A(0, 1, t + 2);
;     WAIT_L(8); BAR; WAIT_L(0); MMA8(0, 0, B0); BAR; SCHED;
;     LDB8(B1, 1, 1); STG_B(1, 0, t + 3);
;     BAR; WAIT_L(0); MMA8(0, 1, B1); BAR;
	ds_read_b128 v[162:165], v134 offset:16384
	ds_read_b128 v[166:169], v134 offset:17408
	ds_read_b128 v[170:173], v134 offset:18432
	ds_read_b128 v[174:177], v134 offset:19456
	ds_read_b128 v[180:183], v134 offset:20480
	ds_read_b128 v[184:187], v134 offset:21504
	ds_read_b128 v[188:191], v134 offset:22528
	ds_read_b128 v[192:195], v134 offset:23552
	s_add_u32 s22, s24, s2
	s_addc_u32 s23, s25, s3
	s_add_u32 s22, s22, 0x100
	s_addc_u32 s23, s23, 0
	s_add_i32 s36, s14, 0x10000
	s_mov_b32 m0, s36
	s_nop 0
	global_load_lds_dwordx4 v136, s[22:23]
	s_add_i32 s36, s14, 0x12000
	s_mov_b32 m0, s36
	s_nop 0
	global_load_lds_dwordx4 v135, s[22:23]
	s_add_u32 s22, s9, s2
	s_addc_u32 s23, s12, s3
	s_add_u32 s22, s22, 0x100
	s_addc_u32 s23, s23, 0
	s_mov_b32 m0, s14
	s_nop 0
	global_load_lds_dwordx4 v136, s[22:23]
	s_add_i32 s36, s14, 0x2000
	s_mov_b32 m0, s36
	s_nop 0
	global_load_lds_dwordx4 v135, s[22:23]
	s_add_u32 s22, s26, s2
	s_addc_u32 s23, s27, s3
	s_add_u32 s22, s22, 0x100
	s_addc_u32 s23, s23, 0
	s_add_i32 s36, s14, 0x14000
	s_mov_b32 m0, s36
	s_nop 0
	global_load_lds_dwordx4 v136, s[22:23]
	s_add_i32 s36, s14, 0x16000
	s_mov_b32 m0, s36
	s_nop 0
	global_load_lds_dwordx4 v135, s[22:23]
	s_waitcnt vmcnt(8) lgkmcnt(0)
	s_barrier
	s_setprio 1
	v_mfma_f32_16x16x32_bf16 v[62:65], v[162:165], v[138:141], 0
	v_mfma_f32_16x16x32_bf16 v[58:61], v[162:165], v[154:157], 0
	v_mfma_f32_16x16x32_bf16 v[54:57], v[170:173], v[138:141], 0
	v_mfma_f32_16x16x32_bf16 v[50:53], v[170:173], v[154:157], 0
	v_mfma_f32_16x16x32_bf16 v[46:49], v[180:183], v[138:141], 0
	v_mfma_f32_16x16x32_bf16 v[42:45], v[180:183], v[154:157], 0
	v_mfma_f32_16x16x32_bf16 v[38:41], v[188:191], v[138:141], 0
	v_mfma_f32_16x16x32_bf16 v[34:37], v[188:191], v[154:157], 0
	v_mfma_f32_16x16x32_bf16 v[62:65], v[166:169], v[142:145], v[62:65]
	v_mfma_f32_16x16x32_bf16 v[58:61], v[166:169], v[158:161], v[58:61]
	v_mfma_f32_16x16x32_bf16 v[54:57], v[174:177], v[142:145], v[54:57]
	v_mfma_f32_16x16x32_bf16 v[50:53], v[174:177], v[158:161], v[50:53]
	v_mfma_f32_16x16x32_bf16 v[46:49], v[184:187], v[142:145], v[46:49]
	v_mfma_f32_16x16x32_bf16 v[42:45], v[184:187], v[158:161], v[42:45]
	v_mfma_f32_16x16x32_bf16 v[38:41], v[192:195], v[142:145], v[38:41]
	v_mfma_f32_16x16x32_bf16 v[34:37], v[192:195], v[158:161], v[34:37]
	v_mfma_f32_16x16x32_bf16 v[30:33], v[162:165], v[196:199], 0
	v_mfma_f32_16x16x32_bf16 v[26:29], v[162:165], v[204:207], 0
	v_mfma_f32_16x16x32_bf16 v[22:25], v[170:173], v[196:199], 0
	v_mfma_f32_16x16x32_bf16 v[18:21], v[170:173], v[204:207], 0
	v_mfma_f32_16x16x32_bf16 v[14:17], v[180:183], v[196:199], 0
	v_mfma_f32_16x16x32_bf16 v[10:13], v[180:183], v[204:207], 0
	v_mfma_f32_16x16x32_bf16 v[6:9], v[188:191], v[196:199], 0
	v_mfma_f32_16x16x32_bf16 v[2:5], v[188:191], v[204:207], 0
	v_mfma_f32_16x16x32_bf16 v[30:33], v[166:169], v[200:203], v[30:33]
	v_mfma_f32_16x16x32_bf16 v[26:29], v[166:169], v[208:211], v[26:29]
	v_mfma_f32_16x16x32_bf16 v[22:25], v[174:177], v[200:203], v[22:25]
	v_mfma_f32_16x16x32_bf16 v[18:21], v[174:177], v[208:211], v[18:21]
	v_mfma_f32_16x16x32_bf16 v[14:17], v[184:187], v[200:203], v[14:17]
	v_mfma_f32_16x16x32_bf16 v[10:13], v[184:187], v[208:211], v[10:13]
	v_mfma_f32_16x16x32_bf16 v[6:9], v[192:195], v[200:203], v[6:9]
	v_mfma_f32_16x16x32_bf16 v[2:5], v[192:195], v[208:211], v[2:5]
	s_setprio 0
	s_barrier
	v_add_u32_e32 v158, 0x18000, v137
	ds_read_b128 v[138:141], v158
	ds_read_b128 v[142:145], v158 offset:1024
	ds_read_b128 v[154:157], v158 offset:2048
	ds_read_b128 v[158:161], v158 offset:3072
	ds_read_b128 v[162:165], v134 offset:32768
	ds_read_b128 v[166:169], v134 offset:33792
	ds_read_b128 v[170:173], v134 offset:34816
	ds_read_b128 v[174:177], v134 offset:35840
	ds_read_b128 v[180:183], v134 offset:36864
	ds_read_b128 v[184:187], v134 offset:37888
	ds_read_b128 v[188:191], v134 offset:38912
	ds_read_b128 v[192:195], v134 offset:39936
	v_add_u32_e32 v208, 0x1c000, v137
	ds_read_b128 v[196:199], v208
	ds_read_b128 v[200:203], v208 offset:1024
	ds_read_b128 v[204:207], v208 offset:2048
	ds_read_b128 v[208:211], v208 offset:3072
	s_add_u32 s22, s17, s2
	s_addc_u32 s23, s18, s3
	s_add_u32 s22, s22, 0x100
	s_addc_u32 s23, s23, 0
	s_add_i32 s36, s14, 0x4000
	s_mov_b32 m0, s36
	s_nop 0
	global_load_lds_dwordx4 v136, s[22:23]
	s_add_i32 s36, s14, 0x6000
	s_mov_b32 m0, s36
	s_nop 0
	global_load_lds_dwordx4 v135, s[22:23]
	s_waitcnt vmcnt(8) lgkmcnt(0)
	s_barrier
	s_setprio 1
	v_mfma_f32_16x16x32_bf16 v[126:129], v[162:165], v[138:141], v[126:129]
	v_mfma_f32_16x16x32_bf16 v[122:125], v[162:165], v[154:157], v[122:125]
	v_mfma_f32_16x16x32_bf16 v[118:121], v[170:173], v[138:141], v[118:121]
	v_mfma_f32_16x16x32_bf16 v[114:117], v[170:173], v[154:157], v[114:117]
	v_mfma_f32_16x16x32_bf16 v[110:113], v[180:183], v[138:141], v[110:113]
	v_mfma_f32_16x16x32_bf16 v[106:109], v[180:183], v[154:157], v[106:109]
	v_mfma_f32_16x16x32_bf16 v[102:105], v[188:191], v[138:141], v[102:105]
	v_mfma_f32_16x16x32_bf16 v[98:101], v[188:191], v[154:157], v[98:101]
	v_mfma_f32_16x16x32_bf16 v[126:129], v[166:169], v[142:145], v[126:129]
	v_mfma_f32_16x16x32_bf16 v[122:125], v[166:169], v[158:161], v[122:125]
	v_mfma_f32_16x16x32_bf16 v[118:121], v[174:177], v[142:145], v[118:121]
	v_mfma_f32_16x16x32_bf16 v[114:117], v[174:177], v[158:161], v[114:117]
	v_mfma_f32_16x16x32_bf16 v[110:113], v[184:187], v[142:145], v[110:113]
	v_mfma_f32_16x16x32_bf16 v[106:109], v[184:187], v[158:161], v[106:109]
	v_mfma_f32_16x16x32_bf16 v[102:105], v[192:195], v[142:145], v[102:105]
	v_mfma_f32_16x16x32_bf16 v[98:101], v[192:195], v[158:161], v[98:101]
	v_mfma_f32_16x16x32_bf16 v[94:97], v[162:165], v[196:199], v[94:97]
	v_mfma_f32_16x16x32_bf16 v[90:93], v[162:165], v[204:207], v[90:93]
	v_mfma_f32_16x16x32_bf16 v[86:89], v[170:173], v[196:199], v[86:89]
	v_mfma_f32_16x16x32_bf16 v[82:85], v[170:173], v[204:207], v[82:85]
	v_mfma_f32_16x16x32_bf16 v[78:81], v[180:183], v[196:199], v[78:81]
	v_mfma_f32_16x16x32_bf16 v[74:77], v[180:183], v[204:207], v[74:77]
	v_mfma_f32_16x16x32_bf16 v[70:73], v[188:191], v[196:199], v[70:73]
	v_mfma_f32_16x16x32_bf16 v[66:69], v[188:191], v[204:207], v[66:69]
	v_mfma_f32_16x16x32_bf16 v[94:97], v[166:169], v[200:203], v[94:97]
	v_mfma_f32_16x16x32_bf16 v[90:93], v[166:169], v[208:211], v[90:93]
	v_mfma_f32_16x16x32_bf16 v[86:89], v[174:177], v[200:203], v[86:89]
	v_mfma_f32_16x16x32_bf16 v[82:85], v[174:177], v[208:211], v[82:85]
	v_mfma_f32_16x16x32_bf16 v[78:81], v[184:187], v[200:203], v[78:81]
	v_mfma_f32_16x16x32_bf16 v[74:77], v[184:187], v[208:211], v[74:77]
	v_mfma_f32_16x16x32_bf16 v[70:73], v[192:195], v[200:203], v[70:73]
	v_mfma_f32_16x16x32_bf16 v[66:69], v[192:195], v[208:211], v[66:69]
	s_setprio 0
	s_barrier
; #define WAIT_V(n) asm volatile("s_waitcnt vmcnt(" #n ")" ::: "memory")
; #define WAIT_L(n) asm volatile("s_waitcnt lgkmcnt(" #n ")" ::: "memory")
; #define BAR __builtin_amdgcn_s_barrier()
; #define SCHED __builtin_amdgcn_sched_barrier(0)
; #define STG_A(b, h, kt) stage_half_s(lds0 + ((b) * 2 + (h)) * HT_B, ((h) ? A1 : Ap) + (kt) * BK, off0, off1)
; #define STG_B(b, h, kt) stage_half_s(lds0 + (4 + (b) * 2 + (h)) * HT_B, ((h) ? B1p : Bp) + (kt) * BK, off0, off1)
; #define STG_A(b, h, kt) stage_half_s(lds0 + ((b) * 2 + (h)) * HT_B, ((h) ? A1 : Ap) + (kt) * BK, off0, off1)
; #define STG_B(b, h, kt) stage_half_s(lds0 + (4 + (b) * 2 + (h)) * HT_B, ((h) ? B1p : Bp) + (kt) * BK, off0, off1)
; #define LDA8(b, h) _Pragma("unroll") for (int m = 0; m < 4; ++m) _Pragma("unroll") for (int k = 0; k < 2; ++k) \
;     At[m][k] = *(const bf16x8*)(SA_(shm, b, h) + abase + (m * 2 + k) * 1024)
; #define LDB8(dst, b, h) _Pragma("unroll") for (int n = 0; n < 2; ++n) _Pragma("unroll") for (int k = 0; k < 2; ++k) \
;     dst[n][k] = *(const bf16x8*)(SB_(shm, b, h) + bbase + (n * 2 + k) * 1024)
; #define MMA8(ai, bj, Bx) do { __builtin_amdgcn_s_setprio(1); \
;     _Pragma("unroll") for (int m = 0; m < 4; ++m) _Pragma("unroll") for (int n = 0; n < 2; ++n) _Pragma("unroll") for (int k = 0; k < 2; ++k) \
;       acc[ai][bj][m][n] = __builtin_amdgcn_mfma_f32_16x16x32_bf16(At[m][k], Bx[n][k], acc[ai][bj][m][n], 0, 0, 0); \
;     __builtin_amdgcn_s_setprio(0); } while (0)
; template <bool HS>
; __device__ __forceinline__ void gemm_tile8(const u16* __restrict__ Ap, const u16* __restrict__ Bp, int K,
;                                            f32x4 (&acc)[2][2][4][2], char* shm, const int tid, const float* hsr = nullptr) {
;     ...
;     LDB8(B0, 0, 0); SCHED; LDA8(0, 0); STG_A(1, 1, t + 1);
;     WAIT_L(8); BAR; WAIT_L(0); MMA8(0, 0, B0); BAR; SCHED;
;     ...
;     LDA8(1, 1); STG_A(1, 0, t + 3);
;     BAR; WAIT_L(0); MMA8(1, 0, B0); BAR; SCHED;
;     STG_B(1, 1, t + 3);
;     WAIT_V(6); BAR; MMA8(1, 1, B1); BAR;
;   }
	ds_read_b128 v[162:165], v134 offset:49152
	ds_read_b128 v[166:169], v134 offset:50176
	ds_read_b128 v[170:173], v134 offset:51200
	ds_read_b128 v[174:177], v134 offset:52224
	ds_read_b128 v[180:183], v134 offset:53248
	ds_read_b128 v[184:187], v134 offset:54272
	ds_read_b128 v[188:191], v134 offset:55296
	ds_read_b128 v[192:195], v134 offset:56320
	s_add_u32 s22, s24, s2
	s_addc_u32 s23, s25, s3
	s_add_u32 s22, s22, 0x180
	s_addc_u32 s23, s23, 0
	s_add_i32 s36, s14, 0x18000
	s_mov_b32 m0, s36
	s_nop 0
	global_load_lds_dwordx4 v136, s[22:23]
	s_add_i32 s36, s14, 0x1a000
	s_mov_b32 m0, s36
	s_nop 0
	global_load_lds_dwordx4 v135, s[22:23]
	s_add_u32 s22, s9, s2
	s_addc_u32 s23, s12, s3
	s_add_u32 s22, s22, 0x180
	s_addc_u32 s23, s23, 0
	s_add_i32 s36, s14, 0x8000
	s_mov_b32 m0, s36
	s_nop 0
	global_load_lds_dwordx4 v136, s[22:23]
	s_add_i32 s36, s14, 0xa000
	s_mov_b32 m0, s36
	s_nop 0
	global_load_lds_dwordx4 v135, s[22:23]
	s_add_u32 s22, s26, s2
	s_addc_u32 s23, s27, s3
	s_add_u32 s22, s22, 0x180
	s_addc_u32 s23, s23, 0
	s_add_i32 s36, s14, 0x1c000
	s_mov_b32 m0, s36
	s_nop 0
	global_load_lds_dwordx4 v136, s[22:23]
	s_add_i32 s36, s14, 0x1e000
	s_mov_b32 m0, s36
	s_nop 0
	global_load_lds_dwordx4 v135, s[22:23]
	s_waitcnt vmcnt(8) lgkmcnt(0)
	s_barrier
	s_setprio 1
	v_mfma_f32_16x16x32_bf16 v[62:65], v[162:165], v[138:141], v[62:65]
	v_mfma_f32_16x16x32_bf16 v[58:61], v[162:165], v[154:157], v[58:61]
	v_mfma_f32_16x16x32_bf16 v[54:57], v[170:173], v[138:141], v[54:57]
	v_mfma_f32_16x16x32_bf16 v[50:53], v[170:173], v[154:157], v[50:53]
	v_mfma_f32_16x16x32_bf16 v[46:49], v[180:183], v[138:141], v[46:49]
	v_mfma_f32_16x16x32_bf16 v[42:45], v[180:183], v[154:157], v[42:45]
	v_mfma_f32_16x16x32_bf16 v[38:41], v[188:191], v[138:141], v[38:41]
	v_mfma_f32_16x16x32_bf16 v[34:37], v[188:191], v[154:157], v[34:37]
	v_mfma_f32_16x16x32_bf16 v[62:65], v[166:169], v[142:145], v[62:65]
	v_mfma_f32_16x16x32_bf16 v[58:61], v[166:169], v[158:161], v[58:61]
	v_mfma_f32_16x16x32_bf16 v[54:57], v[174:177], v[142:145], v[54:57]
	v_mfma_f32_16x16x32_bf16 v[50:53], v[174:177], v[158:161], v[50:53]
	v_mfma_f32_16x16x32_bf16 v[46:49], v[184:187], v[142:145], v[46:49]
	v_mfma_f32_16x16x32_bf16 v[42:45], v[184:187], v[158:161], v[42:45]
	v_mfma_f32_16x16x32_bf16 v[38:41], v[192:195], v[142:145], v[38:41]
	v_mfma_f32_16x16x32_bf16 v[34:37], v[192:195], v[158:161], v[34:37]
	v_mfma_f32_16x16x32_bf16 v[30:33], v[162:165], v[196:199], v[30:33]
	v_mfma_f32_16x16x32_bf16 v[26:29], v[162:165], v[204:207], v[26:29]
	v_mfma_f32_16x16x32_bf16 v[22:25], v[170:173], v[196:199], v[22:25]
	v_mfma_f32_16x16x32_bf16 v[18:21], v[170:173], v[204:207], v[18:21]
	v_mfma_f32_16x16x32_bf16 v[14:17], v[180:183], v[196:199], v[14:17]
	v_mfma_f32_16x16x32_bf16 v[10:13], v[180:183], v[204:207], v[10:13]
	v_mfma_f32_16x16x32_bf16 v[6:9], v[188:191], v[196:199], v[6:9]
	v_mfma_f32_16x16x32_bf16 v[2:5], v[188:191], v[204:207], v[2:5]
	v_mfma_f32_16x16x32_bf16 v[30:33], v[166:169], v[200:203], v[30:33]
	v_mfma_f32_16x16x32_bf16 v[26:29], v[166:169], v[208:211], v[26:29]
	v_mfma_f32_16x16x32_bf16 v[22:25], v[174:177], v[200:203], v[22:25]
	v_mfma_f32_16x16x32_bf16 v[18:21], v[174:177], v[208:211], v[18:21]
	v_mfma_f32_16x16x32_bf16 v[14:17], v[184:187], v[200:203], v[14:17]
	v_mfma_f32_16x16x32_bf16 v[10:13], v[184:187], v[208:211], v[10:13]
	v_mfma_f32_16x16x32_bf16 v[6:9], v[192:195], v[200:203], v[6:9]
	v_mfma_f32_16x16x32_bf16 v[2:5], v[192:195], v[208:211], v[2:5]
	s_setprio 0
	s_barrier
	s_add_i32 s19, s19, 2
	s_add_u32 s2, s2, 0x100
	s_addc_u32 s3, s3, 0
	s_cmp_lt_u32 s19, 12
	s_cbranch_scc0 .Lk_conv_out_exit
.Lk_conv_out:
	v_add_u32_e32 v158, 0x10000, v137
	ds_read_b128 v[138:141], v158
	ds_read_b128 v[142:145], v158 offset:1024
	ds_read_b128 v[154:157], v158 offset:2048
	ds_read_b128 v[158:161], v158 offset:3072
	ds_read_b128 v[162:165], v134
	ds_read_b128 v[166:169], v134 offset:1024
	ds_read_b128 v[170:173], v134 offset:2048
	ds_read_b128 v[174:177], v134 offset:3072
	ds_read_b128 v[180:183], v134 offset:4096
	ds_read_b128 v[184:187], v134 offset:5120
	ds_read_b128 v[188:191], v134 offset:6144
	ds_read_b128 v[192:195], v134 offset:7168
	v_add_u32_e32 v208, 0x14000, v137
	ds_read_b128 v[196:199], v208
	ds_read_b128 v[200:203], v208 offset:1024
	ds_read_b128 v[204:207], v208 offset:2048
	ds_read_b128 v[208:211], v208 offset:3072
	s_add_u32 s22, s17, s2
	s_addc_u32 s23, s18, s3
	s_add_u32 s22, s22, 0x80
	s_addc_u32 s23, s23, 0
	s_add_i32 s36, s14, 0xc000
	s_mov_b32 m0, s36
	s_nop 0
	global_load_lds_dwordx4 v136, s[22:23]
	s_add_i32 s36, s14, 0xe000
	s_mov_b32 m0, s36
	s_nop 0
	global_load_lds_dwordx4 v135, s[22:23]
	s_waitcnt vmcnt(8) lgkmcnt(0)
	s_barrier
; #define WAIT_V(n) asm volatile("s_waitcnt vmcnt(" #n ")" ::: "memory")
; #define WAIT_L(n) asm volatile("s_waitcnt lgkmcnt(" #n ")" ::: "memory")
; #define BAR __builtin_amdgcn_s_barrier()
; #define SCHED __builtin_amdgcn_sched_barrier(0)
; #define STG_A(b, h, kt) stage_half_s(lds0 + ((b) * 2 + (h)) * HT_B, ((h) ? A1 : Ap) + (kt) * BK, off0, off1)
; #define STG_B(b, h, kt) stage_half_s(lds0 + (4 + (b) * 2 + (h)) * HT_B, ((h) ? B1p : Bp) + (kt) * BK, off0, off1)
; #define STG_A(b, h, kt) stage_half_s(lds0 + ((b) * 2 + (h)) * HT_B, ((h) ? A1 : Ap) + (kt) * BK, off0, off1)
; #define STG_B(b, h, kt) stage_half_s(lds0 + (4 + (b) * 2 + (h)) * HT_B, ((h) ? B1p : Bp) + (kt) * BK, off0, off1)
; #define LDA8(b, h) _Pragma("unroll") for (int m = 0; m < 4; ++m) _Pragma("unroll") for (int k = 0; k < 2; ++k) \
;     At[m][k] = *(const bf16x8*)(SA_(shm, b, h) + abase + (m * 2 + k) * 1024)
; #define LDB8(dst, b, h) _Pragma("unroll") for (int n = 0; n < 2; ++n) _Pragma("unroll") for (int k = 0; k < 2; ++k) \
;     dst[n][k] = *(const bf16x8*)(SB_(shm, b, h) + bbase + (n * 2 + k) * 1024)
; #define MMA8(ai, bj, Bx) do { __builtin_amdgcn_s_setprio(1); \
;     _Pragma("unroll") for (int m = 0; m < 4; ++m) _Pragma("unroll") for (int n = 0; n < 2; ++n) _Pragma("unroll") for (int k = 0; k < 2; ++k) \
;       acc[ai][bj][m][n] = __builtin_amdgcn_mfma_f32_16x16x32_bf16(At[m][k], Bx[n][k], acc[ai][bj][m][n], 0, 0, 0); \
;     __builtin_amdgcn_s_setprio(0); } while (0)
; template <bool HS>
; __device__ __forceinline__ void gemm_tile8(const u16* __restrict__ Ap, const u16* __restrict__ Bp, int K,
;                                            f32x4 (&acc)[2][2][4][2], char* shm, const int tid, const float* hsr = nullptr) {
;     ...
;     WAIT_L(8); BAR; WAIT_L(0); MMA8(0, 0, B0); BAR; SCHED;
;     LDB8(B1, 0, 1); STG_B(0, 0, t + 2);
;     BAR; WAIT_L(0); MMA8(0, 1, B1); BAR;
;     LDA8(0, 1); STG_A(0, 0, t + 2);
;     BAR; WAIT_L(0); MMA8(1, 0, B0); BAR; SCHED;
;     STG_B(0, 1, t + 2);
;     WAIT_V(6); BAR; MMA8(1, 1, B1); BAR;
	s_setprio 1
	v_mfma_f32_16x16x32_bf16 v[126:129], v[162:165], v[138:141], v[126:129]
	v_mfma_f32_16x16x32_bf16 v[122:125], v[162:165], v[154:157], v[122:125]
	v_mfma_f32_16x16x32_bf16 v[118:121], v[170:173], v[138:141], v[118:121]
	v_mfma_f32_16x16x32_bf16 v[114:117], v[170:173], v[154:157], v[114:117]
	v_mfma_f32_16x16x32_bf16 v[110:113], v[180:183], v[138:141], v[110:113]
	v_mfma_f32_16x16x32_bf16 v[106:109], v[180:183], v[154:157], v[106:109]
	v_mfma_f32_16x16x32_bf16 v[102:105], v[188:191], v[138:141], v[102:105]
	v_mfma_f32_16x16x32_bf16 v[98:101], v[188:191], v[154:157], v[98:101]
	v_mfma_f32_16x16x32_bf16 v[126:129], v[166:169], v[142:145], v[126:129]
	v_mfma_f32_16x16x32_bf16 v[122:125], v[166:169], v[158:161], v[122:125]
	v_mfma_f32_16x16x32_bf16 v[118:121], v[174:177], v[142:145], v[118:121]
	v_mfma_f32_16x16x32_bf16 v[114:117], v[174:177], v[158:161], v[114:117]
	v_mfma_f32_16x16x32_bf16 v[110:113], v[184:187], v[142:145], v[110:113]
	v_mfma_f32_16x16x32_bf16 v[106:109], v[184:187], v[158:161], v[106:109]
	v_mfma_f32_16x16x32_bf16 v[102:105], v[192:195], v[142:145], v[102:105]
	v_mfma_f32_16x16x32_bf16 v[98:101], v[192:195], v[158:161], v[98:101]
	v_mfma_f32_16x16x32_bf16 v[94:97], v[162:165], v[196:199], v[94:97]
	v_mfma_f32_16x16x32_bf16 v[90:93], v[162:165], v[204:207], v[90:93]
	v_mfma_f32_16x16x32_bf16 v[86:89], v[170:173], v[196:199], v[86:89]
	v_mfma_f32_16x16x32_bf16 v[82:85], v[170:173], v[204:207], v[82:85]
	v_mfma_f32_16x16x32_bf16 v[78:81], v[180:183], v[196:199], v[78:81]
	v_mfma_f32_16x16x32_bf16 v[74:77], v[180:183], v[204:207], v[74:77]
	v_mfma_f32_16x16x32_bf16 v[70:73], v[188:191], v[196:199], v[70:73]
	v_mfma_f32_16x16x32_bf16 v[66:69], v[188:191], v[204:207], v[66:69]
	v_mfma_f32_16x16x32_bf16 v[94:97], v[166:169], v[200:203], v[94:97]
	v_mfma_f32_16x16x32_bf16 v[90:93], v[166:169], v[208:211], v[90:93]
	v_mfma_f32_16x16x32_bf16 v[86:89], v[174:177], v[200:203], v[86:89]
	v_mfma_f32_16x16x32_bf16 v[82:85], v[174:177], v[208:211], v[82:85]
	v_mfma_f32_16x16x32_bf16 v[78:81], v[184:187], v[200:203], v[78:81]
	v_mfma_f32_16x16x32_bf16 v[74:77], v[184:187], v[208:211], v[74:77]
	v_mfma_f32_16x16x32_bf16 v[70:73], v[192:195], v[200:203], v[70:73]
	v_mfma_f32_16x16x32_bf16 v[66:69], v[192:195], v[208:211], v[66:69]
	s_setprio 0
	s_barrier
	ds_read_b128 v[162:165], v134 offset:16384
	ds_read_b128 v[166:169], v134 offset:17408
	ds_read_b128 v[170:173], v134 offset:18432
	ds_read_b128 v[174:177], v134 offset:19456
	ds_read_b128 v[180:183], v134 offset:20480
	ds_read_b128 v[184:187], v134 offset:21504
	ds_read_b128 v[188:191], v134 offset:22528
	ds_read_b128 v[192:195], v134 offset:23552
	s_add_u32 s22, s24, s2
	s_addc_u32 s23, s25, s3
	s_add_u32 s22, s22, 0x100
	s_addc_u32 s23, s23, 0
	s_add_i32 s36, s14, 0x10000
	s_mov_b32 m0, s36
	s_nop 0
	global_load_lds_dwordx4 v136, s[22:23]
	s_add_i32 s36, s14, 0x12000
	s_mov_b32 m0, s36
	s_nop 0
	global_load_lds_dwordx4 v135, s[22:23]
	s_add_u32 s22, s9, s2
	s_addc_u32 s23, s12, s3
	s_add_u32 s22, s22, 0x100
	s_addc_u32 s23, s23, 0
	s_mov_b32 m0, s14
	s_nop 0
	global_load_lds_dwordx4 v136, s[22:23]
	s_add_i32 s36, s14, 0x2000
	s_mov_b32 m0, s36
	s_nop 0
	global_load_lds_dwordx4 v135, s[22:23]
	s_add_u32 s22, s26, s2
	s_addc_u32 s23, s27, s3
	s_add_u32 s22, s22, 0x100
	s_addc_u32 s23, s23, 0
	s_add_i32 s36, s14, 0x14000
	s_mov_b32 m0, s36
	s_nop 0
	global_load_lds_dwordx4 v136, s[22:23]
	s_add_i32 s36, s14, 0x16000
	s_mov_b32 m0, s36
	s_nop 0
	global_load_lds_dwordx4 v135, s[22:23]
	s_waitcnt vmcnt(8) lgkmcnt(0)
	s_barrier
	s_setprio 1
	v_mfma_f32_16x16x32_bf16 v[62:65], v[162:165], v[138:141], v[62:65]
	v_mfma_f32_16x16x32_bf16 v[58:61], v[162:165], v[154:157], v[58:61]
	v_mfma_f32_16x16x32_bf16 v[54:57], v[170:173], v[138:141], v[54:57]
	v_mfma_f32_16x16x32_bf16 v[50:53], v[170:173], v[154:157], v[50:53]
	v_mfma_f32_16x16x32_bf16 v[46:49], v[180:183], v[138:141], v[46:49]
	v_mfma_f32_16x16x32_bf16 v[42:45], v[180:183], v[154:157], v[42:45]
	v_mfma_f32_16x16x32_bf16 v[38:41], v[188:191], v[138:141], v[38:41]
	v_mfma_f32_16x16x32_bf16 v[34:37], v[188:191], v[154:157], v[34:37]
	v_mfma_f32_16x16x32_bf16 v[62:65], v[166:169], v[142:145], v[62:65]
	v_mfma_f32_16x16x32_bf16 v[58:61], v[166:169], v[158:161], v[58:61]
	v_mfma_f32_16x16x32_bf16 v[54:57], v[174:177], v[142:145], v[54:57]
	v_mfma_f32_16x16x32_bf16 v[50:53], v[174:177], v[158:161], v[50:53]
	v_mfma_f32_16x16x32_bf16 v[46:49], v[184:187], v[142:145], v[46:49]
	v_mfma_f32_16x16x32_bf16 v[42:45], v[184:187], v[158:161], v[42:45]
	v_mfma_f32_16x16x32_bf16 v[38:41], v[192:195], v[142:145], v[38:41]
	v_mfma_f32_16x16x32_bf16 v[34:37], v[192:195], v[158:161], v[34:37]
	v_mfma_f32_16x16x32_bf16 v[30:33], v[162:165], v[196:199], v[30:33]
	v_mfma_f32_16x16x32_bf16 v[26:29], v[162:165], v[204:207], v[26:29]
	v_mfma_f32_16x16x32_bf16 v[22:25], v[170:173], v[196:199], v[22:25]
	v_mfma_f32_16x16x32_bf16 v[18:21], v[170:173], v[204:207], v[18:21]
	v_mfma_f32_16x16x32_bf16 v[14:17], v[180:183], v[196:199], v[14:17]
	v_mfma_f32_16x16x32_bf16 v[10:13], v[180:183], v[204:207], v[10:13]
	v_mfma_f32_16x16x32_bf16 v[6:9], v[188:191], v[196:199], v[6:9]
	v_mfma_f32_16x16x32_bf16 v[2:5], v[188:191], v[204:207], v[2:5]
	v_mfma_f32_16x16x32_bf16 v[30:33], v[166:169], v[200:203], v[30:33]
	v_mfma_f32_16x16x32_bf16 v[26:29], v[166:169], v[208:211], v[26:29]
	v_mfma_f32_16x16x32_bf16 v[22:25], v[174:177], v[200:203], v[22:25]
	v_mfma_f32_16x16x32_bf16 v[18:21], v[174:177], v[208:211], v[18:21]
	v_mfma_f32_16x16x32_bf16 v[14:17], v[184:187], v[200:203], v[14:17]
	v_mfma_f32_16x16x32_bf16 v[10:13], v[184:187], v[208:211], v[10:13]
	v_mfma_f32_16x16x32_bf16 v[6:9], v[192:195], v[200:203], v[6:9]
	v_mfma_f32_16x16x32_bf16 v[2:5], v[192:195], v[208:211], v[2:5]
	s_setprio 0
	s_barrier
; #define WAIT_V(n) asm volatile("s_waitcnt vmcnt(" #n ")" ::: "memory")
; #define WAIT_L(n) asm volatile("s_waitcnt lgkmcnt(" #n ")" ::: "memory")
; #define BAR __builtin_amdgcn_s_barrier()
; #define SCHED __builtin_amdgcn_sched_barrier(0)
; #define STG_A(b, h, kt) stage_half_s(lds0 + ((b) * 2 + (h)) * HT_B, ((h) ? A1 : Ap) + (kt) * BK, off0, off1)
; #define STG_B(b, h, kt) stage_half_s(lds0 + (4 + (b) * 2 + (h)) * HT_B, ((h) ? B1p : Bp) + (kt) * BK, off0, off1)
; #define STG_A(b, h, kt) stage_half_s(lds0 + ((b) * 2 + (h)) * HT_B, ((h) ? A1 : Ap) + (kt) * BK, off0, off1)
; #define STG_B(b, h, kt) stage_half_s(lds0 + (4 + (b) * 2 + (h)) * HT_B, ((h) ? B1p : Bp) + (kt) * BK, off0, off1)
; #define LDA8(b, h) _Pragma("unroll") for (int m = 0; m < 4; ++m) _Pragma("unroll") for (int k = 0; k < 2; ++k) \
;     At[m][k] = *(const bf16x8*)(SA_(shm, b, h) + abase + (m * 2 + k) * 1024)
; #define LDB8(dst, b, h) _Pragma("unroll") for (int n = 0; n < 2; ++n) _Pragma("unroll") for (int k = 0; k < 2; ++k) \
;     dst[n][k] = *(const bf16x8*)(SB_(shm, b, h) + bbase + (n * 2 + k) * 1024)
; #define MMA8(ai, bj, Bx) do { __builtin_amdgcn_s_setprio(1); \
;     _Pragma("unroll") for (int m = 0; m < 4; ++m) _Pragma("unroll") for (int n = 0; n < 2; ++n) _Pragma("unroll") for (int k = 0; k < 2; ++k) \
;       acc[ai][bj][m][n] = __builtin_amdgcn_mfma_f32_16x16x32_bf16(At[m][k], Bx[n][k], acc[ai][bj][m][n], 0, 0, 0); \
;     __builtin_amdgcn_s_setprio(0); } while (0)
; template <bool HS>
; __device__ __forceinline__ void gemm_tile8(const u16* __restrict__ Ap, const u16* __restrict__ Bp, int K,
;                                            f32x4 (&acc)[2][2][4][2], char* shm, const int tid, const float* hsr = nullptr) {
;     ...
;     LDB8(B0, 1, 0); SCHED; LDA8(1, 0); STG_A(0, 1, t + 2);
;     WAIT_L(8); BAR; WAIT_L(0); MMA8(0, 0, B0); BAR; SCHED;
;     LDB8(B1, 1, 1); STG_B(1, 0, t + 3);
;     BAR; WAIT_L(0); MMA8(0, 1, B1); BAR;
;     LDA8(1, 1); STG_A(1, 0, t + 3);
;     BAR; WAIT_L(0); MMA8(1, 0, B0); BAR; SCHED;
;     STG_B(1, 1, t + 3);
;     WAIT_V(6); BAR; MMA8(1, 1, B1); BAR;
;   }
	v_add_u32_e32 v158, 0x18000, v137
	ds_read_b128 v[138:141], v158
	ds_read_b128 v[142:145], v158 offset:1024
	ds_read_b128 v[154:157], v158 offset:2048
	ds_read_b128 v[158:161], v158 offset:3072
	ds_read_b128 v[162:165], v134 offset:32768
	ds_read_b128 v[166:169], v134 offset:33792
	ds_read_b128 v[170:173], v134 offset:34816
	ds_read_b128 v[174:177], v134 offset:35840
	ds_read_b128 v[180:183], v134 offset:36864
	ds_read_b128 v[184:187], v134 offset:37888
	ds_read_b128 v[188:191], v134 offset:38912
	ds_read_b128 v[192:195], v134 offset:39936
	v_add_u32_e32 v208, 0x1c000, v137
	ds_read_b128 v[196:199], v208
	ds_read_b128 v[200:203], v208 offset:1024
	ds_read_b128 v[204:207], v208 offset:2048
	ds_read_b128 v[208:211], v208 offset:3072
	s_add_u32 s22, s17, s2
	s_addc_u32 s23, s18, s3
	s_add_u32 s22, s22, 0x100
	s_addc_u32 s23, s23, 0
	s_add_i32 s36, s14, 0x4000
	s_mov_b32 m0, s36
	s_nop 0
	global_load_lds_dwordx4 v136, s[22:23]
	s_add_i32 s36, s14, 0x6000
	s_mov_b32 m0, s36
	s_nop 0
	global_load_lds_dwordx4 v135, s[22:23]
	s_waitcnt vmcnt(8) lgkmcnt(0)
	s_barrier
	s_setprio 1
	v_mfma_f32_16x16x32_bf16 v[126:129], v[162:165], v[138:141], v[126:129]
	v_mfma_f32_16x16x32_bf16 v[122:125], v[162:165], v[154:157], v[122:125]
	v_mfma_f32_16x16x32_bf16 v[118:121], v[170:173], v[138:141], v[118:121]
	v_mfma_f32_16x16x32_bf16 v[114:117], v[170:173], v[154:157], v[114:117]
	v_mfma_f32_16x16x32_bf16 v[110:113], v[180:183], v[138:141], v[110:113]
	v_mfma_f32_16x16x32_bf16 v[106:109], v[180:183], v[154:157], v[106:109]
	v_mfma_f32_16x16x32_bf16 v[102:105], v[188:191], v[138:141], v[102:105]
	v_mfma_f32_16x16x32_bf16 v[98:101], v[188:191], v[154:157], v[98:101]
	v_mfma_f32_16x16x32_bf16 v[126:129], v[166:169], v[142:145], v[126:129]
	v_mfma_f32_16x16x32_bf16 v[122:125], v[166:169], v[158:161], v[122:125]
	v_mfma_f32_16x16x32_bf16 v[118:121], v[174:177], v[142:145], v[118:121]
	v_mfma_f32_16x16x32_bf16 v[114:117], v[174:177], v[158:161], v[114:117]
	v_mfma_f32_16x16x32_bf16 v[110:113], v[184:187], v[142:145], v[110:113]
	v_mfma_f32_16x16x32_bf16 v[106:109], v[184:187], v[158:161], v[106:109]
	v_mfma_f32_16x16x32_bf16 v[102:105], v[192:195], v[142:145], v[102:105]
	v_mfma_f32_16x16x32_bf16 v[98:101], v[192:195], v[158:161], v[98:101]
	v_mfma_f32_16x16x32_bf16 v[94:97], v[162:165], v[196:199], v[94:97]
	v_mfma_f32_16x16x32_bf16 v[90:93], v[162:165], v[204:207], v[90:93]
	v_mfma_f32_16x16x32_bf16 v[86:89], v[170:173], v[196:199], v[86:89]
	v_mfma_f32_16x16x32_bf16 v[82:85], v[170:173], v[204:207], v[82:85]
	v_mfma_f32_16x16x32_bf16 v[78:81], v[180:183], v[196:199], v[78:81]
	v_mfma_f32_16x16x32_bf16 v[74:77], v[180:183], v[204:207], v[74:77]
	v_mfma_f32_16x16x32_bf16 v[70:73], v[188:191], v[196:199], v[70:73]
	v_mfma_f32_16x16x32_bf16 v[66:69], v[188:191], v[204:207], v[66:69]
	v_mfma_f32_16x16x32_bf16 v[94:97], v[166:169], v[200:203], v[94:97]
	v_mfma_f32_16x16x32_bf16 v[90:93], v[166:169], v[208:211], v[90:93]
	v_mfma_f32_16x16x32_bf16 v[86:89], v[174:177], v[200:203], v[86:89]
	v_mfma_f32_16x16x32_bf16 v[82:85], v[174:177], v[208:211], v[82:85]
	v_mfma_f32_16x16x32_bf16 v[78:81], v[184:187], v[200:203], v[78:81]
	v_mfma_f32_16x16x32_bf16 v[74:77], v[184:187], v[208:211], v[74:77]
	v_mfma_f32_16x16x32_bf16 v[70:73], v[192:195], v[200:203], v[70:73]
	v_mfma_f32_16x16x32_bf16 v[66:69], v[192:195], v[208:211], v[66:69]
	s_setprio 0
	s_barrier
	ds_read_b128 v[162:165], v134 offset:49152
	ds_read_b128 v[166:169], v134 offset:50176
	ds_read_b128 v[170:173], v134 offset:51200
	ds_read_b128 v[174:177], v134 offset:52224
	ds_read_b128 v[180:183], v134 offset:53248
	ds_read_b128 v[184:187], v134 offset:54272
	ds_read_b128 v[188:191], v134 offset:55296
	ds_read_b128 v[192:195], v134 offset:56320
	s_add_u32 s22, s24, s2
	s_addc_u32 s23, s25, s3
	s_add_u32 s22, s22, 0x180
	s_addc_u32 s23, s23, 0
	s_add_i32 s36, s14, 0x18000
	s_mov_b32 m0, s36
	s_nop 0
	global_load_lds_dwordx4 v136, s[22:23]
	s_add_i32 s36, s14, 0x1a000
	s_mov_b32 m0, s36
	s_nop 0
	global_load_lds_dwordx4 v135, s[22:23]
	s_add_u32 s22, s9, s2
	s_addc_u32 s23, s12, s3
	s_add_u32 s22, s22, 0x180
	s_addc_u32 s23, s23, 0
	s_add_i32 s36, s14, 0x8000
	s_mov_b32 m0, s36
	s_nop 0
	global_load_lds_dwordx4 v136, s[22:23]
	s_add_i32 s36, s14, 0xa000
	s_mov_b32 m0, s36
	s_nop 0
	global_load_lds_dwordx4 v135, s[22:23]
	s_add_u32 s22, s26, s2
	s_addc_u32 s23, s27, s3
	s_add_u32 s22, s22, 0x180
	s_addc_u32 s23, s23, 0
	s_add_i32 s36, s14, 0x1c000
	s_mov_b32 m0, s36
	s_nop 0
	global_load_lds_dwordx4 v136, s[22:23]
	s_add_i32 s36, s14, 0x1e000
	s_mov_b32 m0, s36
	s_nop 0
	global_load_lds_dwordx4 v135, s[22:23]
	s_waitcnt vmcnt(8) lgkmcnt(0)
	s_barrier
	s_setprio 1
	v_mfma_f32_16x16x32_bf16 v[62:65], v[162:165], v[138:141], v[62:65]
	v_mfma_f32_16x16x32_bf16 v[58:61], v[162:165], v[154:157], v[58:61]
	v_mfma_f32_16x16x32_bf16 v[54:57], v[170:173], v[138:141], v[54:57]
	v_mfma_f32_16x16x32_bf16 v[50:53], v[170:173], v[154:157], v[50:53]
	v_mfma_f32_16x16x32_bf16 v[46:49], v[180:183], v[138:141], v[46:49]
	v_mfma_f32_16x16x32_bf16 v[42:45], v[180:183], v[154:157], v[42:45]
	v_mfma_f32_16x16x32_bf16 v[38:41], v[188:191], v[138:141], v[38:41]
	v_mfma_f32_16x16x32_bf16 v[34:37], v[188:191], v[154:157], v[34:37]
	v_mfma_f32_16x16x32_bf16 v[62:65], v[166:169], v[142:145], v[62:65]
	v_mfma_f32_16x16x32_bf16 v[58:61], v[166:169], v[158:161], v[58:61]
	v_mfma_f32_16x16x32_bf16 v[54:57], v[174:177], v[142:145], v[54:57]
	v_mfma_f32_16x16x32_bf16 v[50:53], v[174:177], v[158:161], v[50:53]
	v_mfma_f32_16x16x32_bf16 v[46:49], v[184:187], v[142:145], v[46:49]
	v_mfma_f32_16x16x32_bf16 v[42:45], v[184:187], v[158:161], v[42:45]
	v_mfma_f32_16x16x32_bf16 v[38:41], v[192:195], v[142:145], v[38:41]
	v_mfma_f32_16x16x32_bf16 v[34:37], v[192:195], v[158:161], v[34:37]
	v_mfma_f32_16x16x32_bf16 v[30:33], v[162:165], v[196:199], v[30:33]
	v_mfma_f32_16x16x32_bf16 v[26:29], v[162:165], v[204:207], v[26:29]
	v_mfma_f32_16x16x32_bf16 v[22:25], v[170:173], v[196:199], v[22:25]
	v_mfma_f32_16x16x32_bf16 v[18:21], v[170:173], v[204:207], v[18:21]
	v_mfma_f32_16x16x32_bf16 v[14:17], v[180:183], v[196:199], v[14:17]
	v_mfma_f32_16x16x32_bf16 v[10:13], v[180:183], v[204:207], v[10:13]
	v_mfma_f32_16x16x32_bf16 v[6:9], v[188:191], v[196:199], v[6:9]
	v_mfma_f32_16x16x32_bf16 v[2:5], v[188:191], v[204:207], v[2:5]
	v_mfma_f32_16x16x32_bf16 v[30:33], v[166:169], v[200:203], v[30:33]
	v_mfma_f32_16x16x32_bf16 v[26:29], v[166:169], v[208:211], v[26:29]
	v_mfma_f32_16x16x32_bf16 v[22:25], v[174:177], v[200:203], v[22:25]
	v_mfma_f32_16x16x32_bf16 v[18:21], v[174:177], v[208:211], v[18:21]
	v_mfma_f32_16x16x32_bf16 v[14:17], v[184:187], v[200:203], v[14:17]
	v_mfma_f32_16x16x32_bf16 v[10:13], v[184:187], v[208:211], v[10:13]
	v_mfma_f32_16x16x32_bf16 v[6:9], v[192:195], v[200:203], v[6:9]
	v_mfma_f32_16x16x32_bf16 v[2:5], v[192:195], v[208:211], v[2:5]
	s_setprio 0
	s_barrier
	s_add_i32 s19, s19, 2
	s_add_u32 s2, s2, 0x100
	s_addc_u32 s3, s3, 0
	s_cmp_lt_u32 s19, 12
	s_cbranch_scc1 .Lk_conv_out

; #define WAIT_V(n) asm volatile("s_waitcnt vmcnt(" #n ")" ::: "memory")
; #define WAIT_L(n) asm volatile("s_waitcnt lgkmcnt(" #n ")" ::: "memory")
; #define BAR __builtin_amdgcn_s_barrier()
; #define SCHED __builtin_amdgcn_sched_barrier(0)
; #define STG_A(b, h, kt) stage_half_s(lds0 + ((b) * 2 + (h)) * HT_B, ((h) ? A1 : Ap) + (kt) * BK, off0, off1)
; #define STG_A(b, h, kt) stage_half_s(lds0 + ((b) * 2 + (h)) * HT_B, ((h) ? A1 : Ap) + (kt) * BK, off0, off1)
; #define LDA8(b, h) _Pragma("unroll") for (int m = 0; m < 4; ++m) _Pragma("unroll") for (int k = 0; k < 2; ++k) \
;     At[m][k] = *(const bf16x8*)(SA_(shm, b, h) + abase + (m * 2 + k) * 1024)
; #define LDB8(dst, b, h) _Pragma("unroll") for (int n = 0; n < 2; ++n) _Pragma("unroll") for (int k = 0; k < 2; ++k) \
;     dst[n][k] = *(const bf16x8*)(SB_(shm, b, h) + bbase + (n * 2 + k) * 1024)
; template <bool HS>
; __device__ __forceinline__ void gemm_tile8(const u16* __restrict__ Ap, const u16* __restrict__ Bp, int K,
;                                            f32x4 (&acc)[2][2][4][2], char* shm, const int tid, const float* hsr = nullptr) {
;   const int wid = tid >> 6, lane = tid & 63, wr = wid >> 2, wc = wid & 3, fr = lane & 15, fq = lane >> 4;
;   int r0, c0, r1, c1;
;   stage_rc(tid * 16, r0, c0);
;   stage_rc(tid * 16 + 8192, r1, c1);
;   const unsigned off0 = (unsigned)(r0 * K + c0) * 2u, off1 = (unsigned)(r1 * K + c1) * 2u;
;   const int wvoff = __builtin_amdgcn_readfirstlane(tid >> 6) * 1024;
;   const u16* A1 = Ap + (size_t)128 * K;
;   const u16* B1p = Bp + (size_t)128 * K;
; #pragma unroll
;   for (int a = 0; a < 2; ++a)
; #pragma unroll
;     for (int b = 0; b < 2; ++b)
; #pragma unroll
;       for (int m = 0; m < 4; ++m)
; #pragma unroll
;         for (int n = 0; n < 2; ++n) acc[a][b][m][n] = f32x4{0.f, 0.f, 0.f, 0.f};
;   const int abase = lds_byte(wr * 64 + fr, fq * 8), bbase = lds_byte(wc * 32 + fr, fq * 8);
;   bf16x8 At[4][2], B0[2][2], B1[2][2];
;   const unsigned lds0 = (unsigned)(size_t)(__attribute__((address_space(3))) char*)shm + (unsigned)wvoff;
;     ...
;   const int nt = K / BK;
;   WAIT_V(0);
;   if (wr == 1) BAR;
;   BAR;
;     ...
;     LDB8(B0, 0, 0); SCHED; LDA8(0, 0); STG_A(1, 1, t + 1);
;     WAIT_L(8); BAR; WAIT_L(0); MMA8(0, 0, B0); BAR; SCHED;
.LBB0_317:
	s_or_b64 exec, exec, s[6:7]
	v_mov_b32_e32 v4, s11
	v_bfe_i32 v4, v4, 0, 8
	v_ashrrev_i32_e32 v5, 31, v4
	v_lshlrev_b64 v[4:5], 19, v[4:5]
	v_bfe_i32 v6, v0, 27, 1
	v_lshl_add_u64 v[130:131], s[0:1], 0, v[4:5]
	v_lshlrev_b32_e32 v4, 4, v0
	v_lshrrev_b32_e32 v6, 22, v6
	v_add_u32_e32 v6, v4, v6
	v_and_b32_e32 v6, 0xfffffc00, v6
	v_ashrrev_i32_e32 v5, 31, v0
	v_sub_u32_e32 v6, v4, v6
	v_lshrrev_b32_e32 v5, 26, v5
	v_lshrrev_b32_e32 v7, 4, v6
	v_add_u32_e32 v5, v0, v5
	v_bitop3_b32 v7, v7, v6, 32 bitop3:0x6c
	v_ashrrev_i32_e32 v6, 31, v6
	v_ashrrev_i32_e32 v5, 6, v5
	v_lshrrev_b32_e32 v6, 26, v6
	v_lshlrev_b32_e32 v8, 3, v5
	v_add_u32_e32 v6, v7, v6
	v_and_b32_e32 v8, 0x1ffff0, v8
	v_ashrrev_i32_e32 v6, 6, v6
	v_add_u32_e32 v8, v6, v8
	v_mul_i32_i24_e32 v6, 64, v6
	v_add_u32_e32 v4, 0x2000, v4
	v_sub_u32_e32 v6, v7, v6
	v_ashrrev_i32_e32 v7, 31, v4
	v_lshrrev_b32_e32 v7, 22, v7
	v_add_u32_e32 v7, v4, v7
	v_ashrrev_i32_e32 v7, 10, v7
	v_mul_i32_i24_e32 v9, 0x400, v7
	v_sub_u32_e32 v4, v4, v9
	v_lshrrev_b32_e32 v9, 4, v4
	v_bitop3_b32 v4, v9, v4, 32 bitop3:0x6c
	v_ashrrev_i32_e32 v10, 31, v4
	v_lshrrev_b32_e32 v10, 26, v10
	v_add_u32_e32 v10, v4, v10
	v_lshlrev_b32_e32 v9, 3, v7
	v_lshrrev_b32_e32 v11, 6, v10
	v_and_b32_e32 v10, 0xc0, v10
	s_ashr_i32 s5, s4, 31
	v_and_b32_e32 v9, 0x1ffff0, v9
	v_lshlrev_b32_e32 v7, 5, v7
	v_sub_u32_e32 v4, v4, v10
	s_lshl_b64 s[6:7], s[4:5], 11
	v_lshlrev_b32_e32 v5, 5, v5
	v_add_u32_e32 v9, v11, v9
	v_and_b32_e32 v7, 32, v7
	v_ashrrev_i16_sdwa v4, v178, sext(v4) dst_sel:DWORD dst_unused:UNUSED_PAD src0_sel:DWORD src1_sel:BYTE_0
	s_add_u32 s8, s88, s6
	v_and_b32_e32 v5, 32, v5
	v_ashrrev_i16_sdwa v6, v178, sext(v6) dst_sel:DWORD dst_unused:UNUSED_PAD src0_sel:DWORD src1_sel:BYTE_0
	v_bfe_i32 v4, v4, 0, 16
	v_lshl_or_b32 v7, v9, 10, v7
	s_addc_u32 s9, s89, s7
	v_bfe_i32 v6, v6, 0, 16
	v_lshl_or_b32 v5, v8, 10, v5
	v_and_b32_e32 v8, 15, v0
	v_add_lshl_u32 v139, v7, v4, 1
	s_lshl_b32 s10, s10, 10
	v_lshlrev_b32_e32 v7, 2, v0
	v_add_lshl_u32 v140, v5, v6, 1
	s_mov_b64 s[4:5], 0x40000
	v_and_b32_e32 v4, 48, v0
	v_lshlrev_b32_e32 v5, 6, v8
	v_and_b32_e32 v7, 32, v7
	s_add_i32 s11, s10, 0
	v_lshl_add_u64 v[132:133], v[130:131], 0, s[4:5]
	v_or_b32_e32 v6, v5, v4
	v_bitop3_b32 v4, v5, v7, v4 bitop3:0x36
	v_lshlrev_b32_e32 v2, 12, v2
	s_movk_i32 s4, 0x3000
	s_add_u32 s13, s8, 0x40100
	v_lshlrev_b32_e32 v3, 13, v3
	v_and_or_b32 v141, v2, s4, v4
	s_addc_u32 s14, s9, 0
	v_readlane_b32 s4, v254, 34
	v_bitop3_b32 v3, v6, v3, v7 bitop3:0xde
	s_add_u32 s15, s4, s6
	v_readlane_b32 s4, v254, 35
	v_mov_b32_e32 v2, 0
	s_addc_u32 s16, s4, s7
	s_mov_b32 s17, -2
	s_mov_b64 s[4:5], 0
	v_add_u32_e32 v138, 0, v3
	s_waitcnt lgkmcnt(0)
	v_readfirstlane_b32 s24, v130
	v_readfirstlane_b32 s25, v131
	v_readfirstlane_b32 s22, v132
	v_readfirstlane_b32 s23, v133
	s_barrier
	s_barrier
	v_add_u32_e32 v154, 0x10000, v141
	ds_read_b128 v[142:145], v154
	ds_read_b128 v[146:149], v154 offset:1024
	ds_read_b128 v[150:153], v154 offset:2048
	ds_read_b128 v[154:157], v154 offset:3072
	ds_read_b128 v[158:161], v138
	ds_read_b128 v[162:165], v138 offset:1024
	ds_read_b128 v[166:169], v138 offset:2048
	ds_read_b128 v[170:173], v138 offset:3072
	ds_read_b128 v[174:177], v138 offset:4096
	ds_read_b128 v[180:183], v138 offset:5120
	ds_read_b128 v[184:187], v138 offset:6144
	ds_read_b128 v[188:191], v138 offset:7168
	v_add_u32_e32 v204, 0x14000, v141
	ds_read_b128 v[192:195], v204
	ds_read_b128 v[196:199], v204 offset:1024
	ds_read_b128 v[200:203], v204 offset:2048
	ds_read_b128 v[204:207], v204 offset:3072
	s_add_u32 s20, s15, s4
	s_addc_u32 s21, s16, s5
	s_add_u32 s20, s20, 0x80
	s_addc_u32 s21, s21, 0
	s_add_i32 s18, s11, 0xc000
	s_mov_b32 m0, s18
	s_nop 0
	global_load_lds_dwordx4 v140, s[20:21]
	s_add_i32 s18, s11, 0xe000
	s_mov_b32 m0, s18
	s_nop 0
	global_load_lds_dwordx4 v139, s[20:21]
	s_waitcnt vmcnt(8) lgkmcnt(0)
	s_barrier
	s_setprio 1
	v_mfma_f32_16x16x32_bf16 v[126:129], v[158:161], v[142:145], 0
	v_mfma_f32_16x16x32_bf16 v[122:125], v[158:161], v[150:153], 0
	v_mfma_f32_16x16x32_bf16 v[118:121], v[166:169], v[142:145], 0
	v_mfma_f32_16x16x32_bf16 v[114:117], v[166:169], v[150:153], 0
	v_mfma_f32_16x16x32_bf16 v[110:113], v[174:177], v[142:145], 0
	v_mfma_f32_16x16x32_bf16 v[106:109], v[174:177], v[150:153], 0
	v_mfma_f32_16x16x32_bf16 v[102:105], v[184:187], v[142:145], 0
	v_mfma_f32_16x16x32_bf16 v[98:101], v[184:187], v[150:153], 0
	v_mfma_f32_16x16x32_bf16 v[126:129], v[162:165], v[146:149], v[126:129]
	v_mfma_f32_16x16x32_bf16 v[122:125], v[162:165], v[154:157], v[122:125]
	v_mfma_f32_16x16x32_bf16 v[118:121], v[170:173], v[146:149], v[118:121]
	v_mfma_f32_16x16x32_bf16 v[114:117], v[170:173], v[154:157], v[114:117]
	v_mfma_f32_16x16x32_bf16 v[110:113], v[180:183], v[146:149], v[110:113]
	v_mfma_f32_16x16x32_bf16 v[106:109], v[180:183], v[154:157], v[106:109]
	v_mfma_f32_16x16x32_bf16 v[102:105], v[188:191], v[146:149], v[102:105]
	v_mfma_f32_16x16x32_bf16 v[98:101], v[188:191], v[154:157], v[98:101]
	v_mfma_f32_16x16x32_bf16 v[94:97], v[158:161], v[192:195], 0
	v_mfma_f32_16x16x32_bf16 v[90:93], v[158:161], v[200:203], 0
	v_mfma_f32_16x16x32_bf16 v[86:89], v[166:169], v[192:195], 0
	v_mfma_f32_16x16x32_bf16 v[82:85], v[166:169], v[200:203], 0
	v_mfma_f32_16x16x32_bf16 v[78:81], v[174:177], v[192:195], 0
	v_mfma_f32_16x16x32_bf16 v[74:77], v[174:177], v[200:203], 0
	v_mfma_f32_16x16x32_bf16 v[70:73], v[184:187], v[192:195], 0
	v_mfma_f32_16x16x32_bf16 v[66:69], v[184:187], v[200:203], 0
	v_mfma_f32_16x16x32_bf16 v[94:97], v[162:165], v[196:199], v[94:97]
	v_mfma_f32_16x16x32_bf16 v[90:93], v[162:165], v[204:207], v[90:93]
	v_mfma_f32_16x16x32_bf16 v[86:89], v[170:173], v[196:199], v[86:89]
	v_mfma_f32_16x16x32_bf16 v[82:85], v[170:173], v[204:207], v[82:85]
	v_mfma_f32_16x16x32_bf16 v[78:81], v[180:183], v[196:199], v[78:81]
	v_mfma_f32_16x16x32_bf16 v[74:77], v[180:183], v[204:207], v[74:77]
	v_mfma_f32_16x16x32_bf16 v[70:73], v[188:191], v[196:199], v[70:73]
	v_mfma_f32_16x16x32_bf16 v[66:69], v[188:191], v[204:207], v[66:69]
	s_setprio 0
	s_barrier
; #define WAIT_V(n) asm volatile("s_waitcnt vmcnt(" #n ")" ::: "memory")
; #define WAIT_L(n) asm volatile("s_waitcnt lgkmcnt(" #n ")" ::: "memory")
; #define BAR __builtin_amdgcn_s_barrier()
; #define SCHED __builtin_amdgcn_sched_barrier(0)
; #define STG_A(b, h, kt) stage_half_s(lds0 + ((b) * 2 + (h)) * HT_B, ((h) ? A1 : Ap) + (kt) * BK, off0, off1)
; #define STG_B(b, h, kt) stage_half_s(lds0 + (4 + (b) * 2 + (h)) * HT_B, ((h) ? B1p : Bp) + (kt) * BK, off0, off1)
; #define STG_A(b, h, kt) stage_half_s(lds0 + ((b) * 2 + (h)) * HT_B, ((h) ? A1 : Ap) + (kt) * BK, off0, off1)
; #define STG_B(b, h, kt) stage_half_s(lds0 + (4 + (b) * 2 + (h)) * HT_B, ((h) ? B1p : Bp) + (kt) * BK, off0, off1)
; #define LDA8(b, h) _Pragma("unroll") for (int m = 0; m < 4; ++m) _Pragma("unroll") for (int k = 0; k < 2; ++k) \
;     At[m][k] = *(const bf16x8*)(SA_(shm, b, h) + abase + (m * 2 + k) * 1024)
; #define LDB8(dst, b, h) _Pragma("unroll") for (int n = 0; n < 2; ++n) _Pragma("unroll") for (int k = 0; k < 2; ++k) \
;     dst[n][k] = *(const bf16x8*)(SB_(shm, b, h) + bbase + (n * 2 + k) * 1024)
; #define MMA8(ai, bj, Bx) do { __builtin_amdgcn_s_setprio(1); \
;     _Pragma("unroll") for (int m = 0; m < 4; ++m) _Pragma("unroll") for (int n = 0; n < 2; ++n) _Pragma("unroll") for (int k = 0; k < 2; ++k) \
;       acc[ai][bj][m][n] = __builtin_amdgcn_mfma_f32_16x16x32_bf16(At[m][k], Bx[n][k], acc[ai][bj][m][n], 0, 0, 0); \
;     __builtin_amdgcn_s_setprio(0); } while (0)
; template <bool HS>
; __device__ __forceinline__ void gemm_tile8(const u16* __restrict__ Ap, const u16* __restrict__ Bp, int K,
;                                            f32x4 (&acc)[2][2][4][2], char* shm, const int tid, const float* hsr = nullptr) {
;     ...
;     LDA8(0, 1); STG_A(0, 0, t + 2);
;     BAR; WAIT_L(0); MMA8(1, 0, B0); BAR; SCHED;
;     STG_B(0, 1, t + 2);
;     WAIT_V(6); BAR; MMA8(1, 1, B1); BAR;
;     LDB8(B0, 1, 0); SCHED; LDA8(1, 0); STG_A(0, 1, t + 2);
;     WAIT_L(8); BAR; WAIT_L(0); MMA8(0, 0, B0); BAR; SCHED;
;     LDB8(B1, 1, 1); STG_B(1, 0, t + 3);
;     BAR; WAIT_L(0); MMA8(0, 1, B1); BAR;
	ds_read_b128 v[158:161], v138 offset:16384
	ds_read_b128 v[162:165], v138 offset:17408
	ds_read_b128 v[166:169], v138 offset:18432
	ds_read_b128 v[170:173], v138 offset:19456
	ds_read_b128 v[174:177], v138 offset:20480
	ds_read_b128 v[180:183], v138 offset:21504
	ds_read_b128 v[184:187], v138 offset:22528
	ds_read_b128 v[188:191], v138 offset:23552
	s_add_u32 s20, s24, s4
	s_addc_u32 s21, s25, s5
	s_add_u32 s20, s20, 0x100
	s_addc_u32 s21, s21, 0
	s_add_i32 s18, s11, 0x10000
	s_mov_b32 m0, s18
	s_nop 0
	global_load_lds_dwordx4 v140, s[20:21]
	s_add_i32 s18, s11, 0x12000
	s_mov_b32 m0, s18
	s_nop 0
	global_load_lds_dwordx4 v139, s[20:21]
	s_add_u32 s20, s8, s4
	s_addc_u32 s21, s9, s5
	s_add_u32 s20, s20, 0x100
	s_addc_u32 s21, s21, 0
	s_mov_b32 m0, s11
	s_nop 0
	global_load_lds_dwordx4 v140, s[20:21]
	s_add_i32 s18, s11, 0x2000
	s_mov_b32 m0, s18
	s_nop 0
	global_load_lds_dwordx4 v139, s[20:21]
	s_add_u32 s20, s22, s4
	s_addc_u32 s21, s23, s5
	s_add_u32 s20, s20, 0x100
	s_addc_u32 s21, s21, 0
	s_add_i32 s18, s11, 0x14000
	s_mov_b32 m0, s18
	s_nop 0
	global_load_lds_dwordx4 v140, s[20:21]
	s_add_i32 s18, s11, 0x16000
	s_mov_b32 m0, s18
	s_nop 0
	global_load_lds_dwordx4 v139, s[20:21]
	s_waitcnt vmcnt(8) lgkmcnt(0)
	s_barrier
	s_setprio 1
	v_mfma_f32_16x16x32_bf16 v[62:65], v[158:161], v[142:145], 0
	v_mfma_f32_16x16x32_bf16 v[58:61], v[158:161], v[150:153], 0
	v_mfma_f32_16x16x32_bf16 v[54:57], v[166:169], v[142:145], 0
	v_mfma_f32_16x16x32_bf16 v[50:53], v[166:169], v[150:153], 0
	v_mfma_f32_16x16x32_bf16 v[46:49], v[174:177], v[142:145], 0
	v_mfma_f32_16x16x32_bf16 v[42:45], v[174:177], v[150:153], 0
	v_mfma_f32_16x16x32_bf16 v[38:41], v[184:187], v[142:145], 0
	v_mfma_f32_16x16x32_bf16 v[34:37], v[184:187], v[150:153], 0
	v_mfma_f32_16x16x32_bf16 v[62:65], v[162:165], v[146:149], v[62:65]
	v_mfma_f32_16x16x32_bf16 v[58:61], v[162:165], v[154:157], v[58:61]
	v_mfma_f32_16x16x32_bf16 v[54:57], v[170:173], v[146:149], v[54:57]
	v_mfma_f32_16x16x32_bf16 v[50:53], v[170:173], v[154:157], v[50:53]
	v_mfma_f32_16x16x32_bf16 v[46:49], v[180:183], v[146:149], v[46:49]
	v_mfma_f32_16x16x32_bf16 v[42:45], v[180:183], v[154:157], v[42:45]
	v_mfma_f32_16x16x32_bf16 v[38:41], v[188:191], v[146:149], v[38:41]
	v_mfma_f32_16x16x32_bf16 v[34:37], v[188:191], v[154:157], v[34:37]
	v_mfma_f32_16x16x32_bf16 v[30:33], v[158:161], v[192:195], 0
	v_mfma_f32_16x16x32_bf16 v[26:29], v[158:161], v[200:203], 0
	v_mfma_f32_16x16x32_bf16 v[22:25], v[166:169], v[192:195], 0
	v_mfma_f32_16x16x32_bf16 v[18:21], v[166:169], v[200:203], 0
	v_mfma_f32_16x16x32_bf16 v[14:17], v[174:177], v[192:195], 0
	v_mfma_f32_16x16x32_bf16 v[10:13], v[174:177], v[200:203], 0
	v_mfma_f32_16x16x32_bf16 v[6:9], v[184:187], v[192:195], 0
	v_mfma_f32_16x16x32_bf16 v[2:5], v[184:187], v[200:203], 0
	v_mfma_f32_16x16x32_bf16 v[30:33], v[162:165], v[196:199], v[30:33]
	v_mfma_f32_16x16x32_bf16 v[26:29], v[162:165], v[204:207], v[26:29]
	v_mfma_f32_16x16x32_bf16 v[22:25], v[170:173], v[196:199], v[22:25]
	v_mfma_f32_16x16x32_bf16 v[18:21], v[170:173], v[204:207], v[18:21]
	v_mfma_f32_16x16x32_bf16 v[14:17], v[180:183], v[196:199], v[14:17]
	v_mfma_f32_16x16x32_bf16 v[10:13], v[180:183], v[204:207], v[10:13]
	v_mfma_f32_16x16x32_bf16 v[6:9], v[188:191], v[196:199], v[6:9]
	v_mfma_f32_16x16x32_bf16 v[2:5], v[188:191], v[204:207], v[2:5]
	s_setprio 0
	s_barrier
	v_add_u32_e32 v154, 0x18000, v141
	ds_read_b128 v[142:145], v154
	ds_read_b128 v[146:149], v154 offset:1024
	ds_read_b128 v[150:153], v154 offset:2048
	ds_read_b128 v[154:157], v154 offset:3072
	ds_read_b128 v[158:161], v138 offset:32768
	ds_read_b128 v[162:165], v138 offset:33792
	ds_read_b128 v[166:169], v138 offset:34816
	ds_read_b128 v[170:173], v138 offset:35840
	ds_read_b128 v[174:177], v138 offset:36864
	ds_read_b128 v[180:183], v138 offset:37888
	ds_read_b128 v[184:187], v138 offset:38912
	ds_read_b128 v[188:191], v138 offset:39936
	v_add_u32_e32 v204, 0x1c000, v141
	ds_read_b128 v[192:195], v204
	ds_read_b128 v[196:199], v204 offset:1024
	ds_read_b128 v[200:203], v204 offset:2048
	ds_read_b128 v[204:207], v204 offset:3072
	s_add_u32 s20, s15, s4
	s_addc_u32 s21, s16, s5
	s_add_u32 s20, s20, 0x100
	s_addc_u32 s21, s21, 0
	s_add_i32 s18, s11, 0x4000
	s_mov_b32 m0, s18
	s_nop 0
	global_load_lds_dwordx4 v140, s[20:21]
	s_add_i32 s18, s11, 0x6000
	s_mov_b32 m0, s18
	s_nop 0
	global_load_lds_dwordx4 v139, s[20:21]
	s_waitcnt vmcnt(8) lgkmcnt(0)
	s_barrier
	s_setprio 1
	v_mfma_f32_16x16x32_bf16 v[126:129], v[158:161], v[142:145], v[126:129]
	v_mfma_f32_16x16x32_bf16 v[122:125], v[158:161], v[150:153], v[122:125]
	v_mfma_f32_16x16x32_bf16 v[118:121], v[166:169], v[142:145], v[118:121]
	v_mfma_f32_16x16x32_bf16 v[114:117], v[166:169], v[150:153], v[114:117]
	v_mfma_f32_16x16x32_bf16 v[110:113], v[174:177], v[142:145], v[110:113]
	v_mfma_f32_16x16x32_bf16 v[106:109], v[174:177], v[150:153], v[106:109]
	v_mfma_f32_16x16x32_bf16 v[102:105], v[184:187], v[142:145], v[102:105]
	v_mfma_f32_16x16x32_bf16 v[98:101], v[184:187], v[150:153], v[98:101]
	v_mfma_f32_16x16x32_bf16 v[126:129], v[162:165], v[146:149], v[126:129]
	v_mfma_f32_16x16x32_bf16 v[122:125], v[162:165], v[154:157], v[122:125]
	v_mfma_f32_16x16x32_bf16 v[118:121], v[170:173], v[146:149], v[118:121]
	v_mfma_f32_16x16x32_bf16 v[114:117], v[170:173], v[154:157], v[114:117]
	v_mfma_f32_16x16x32_bf16 v[110:113], v[180:183], v[146:149], v[110:113]
	v_mfma_f32_16x16x32_bf16 v[106:109], v[180:183], v[154:157], v[106:109]
	v_mfma_f32_16x16x32_bf16 v[102:105], v[188:191], v[146:149], v[102:105]
	v_mfma_f32_16x16x32_bf16 v[98:101], v[188:191], v[154:157], v[98:101]
	v_mfma_f32_16x16x32_bf16 v[94:97], v[158:161], v[192:195], v[94:97]
	v_mfma_f32_16x16x32_bf16 v[90:93], v[158:161], v[200:203], v[90:93]
	v_mfma_f32_16x16x32_bf16 v[86:89], v[166:169], v[192:195], v[86:89]
	v_mfma_f32_16x16x32_bf16 v[82:85], v[166:169], v[200:203], v[82:85]
	v_mfma_f32_16x16x32_bf16 v[78:81], v[174:177], v[192:195], v[78:81]
	v_mfma_f32_16x16x32_bf16 v[74:77], v[174:177], v[200:203], v[74:77]
	v_mfma_f32_16x16x32_bf16 v[70:73], v[184:187], v[192:195], v[70:73]
	v_mfma_f32_16x16x32_bf16 v[66:69], v[184:187], v[200:203], v[66:69]
	v_mfma_f32_16x16x32_bf16 v[94:97], v[162:165], v[196:199], v[94:97]
	v_mfma_f32_16x16x32_bf16 v[90:93], v[162:165], v[204:207], v[90:93]
	v_mfma_f32_16x16x32_bf16 v[86:89], v[170:173], v[196:199], v[86:89]
	v_mfma_f32_16x16x32_bf16 v[82:85], v[170:173], v[204:207], v[82:85]
	v_mfma_f32_16x16x32_bf16 v[78:81], v[180:183], v[196:199], v[78:81]
	v_mfma_f32_16x16x32_bf16 v[74:77], v[180:183], v[204:207], v[74:77]
	v_mfma_f32_16x16x32_bf16 v[70:73], v[188:191], v[196:199], v[70:73]
	v_mfma_f32_16x16x32_bf16 v[66:69], v[188:191], v[204:207], v[66:69]
	s_setprio 0
	s_barrier
; #define WAIT_V(n) asm volatile("s_waitcnt vmcnt(" #n ")" ::: "memory")
; #define WAIT_L(n) asm volatile("s_waitcnt lgkmcnt(" #n ")" ::: "memory")
; #define BAR __builtin_amdgcn_s_barrier()
; #define SCHED __builtin_amdgcn_sched_barrier(0)
; #define STG_A(b, h, kt) stage_half_s(lds0 + ((b) * 2 + (h)) * HT_B, ((h) ? A1 : Ap) + (kt) * BK, off0, off1)
; #define STG_B(b, h, kt) stage_half_s(lds0 + (4 + (b) * 2 + (h)) * HT_B, ((h) ? B1p : Bp) + (kt) * BK, off0, off1)
; #define STG_A(b, h, kt) stage_half_s(lds0 + ((b) * 2 + (h)) * HT_B, ((h) ? A1 : Ap) + (kt) * BK, off0, off1)
; #define STG_B(b, h, kt) stage_half_s(lds0 + (4 + (b) * 2 + (h)) * HT_B, ((h) ? B1p : Bp) + (kt) * BK, off0, off1)
; #define LDA8(b, h) _Pragma("unroll") for (int m = 0; m < 4; ++m) _Pragma("unroll") for (int k = 0; k < 2; ++k) \
;     At[m][k] = *(const bf16x8*)(SA_(shm, b, h) + abase + (m * 2 + k) * 1024)
; #define LDB8(dst, b, h) _Pragma("unroll") for (int n = 0; n < 2; ++n) _Pragma("unroll") for (int k = 0; k < 2; ++k) \
;     dst[n][k] = *(const bf16x8*)(SB_(shm, b, h) + bbase + (n * 2 + k) * 1024)
; #define MMA8(ai, bj, Bx) do { __builtin_amdgcn_s_setprio(1); \
;     _Pragma("unroll") for (int m = 0; m < 4; ++m) _Pragma("unroll") for (int n = 0; n < 2; ++n) _Pragma("unroll") for (int k = 0; k < 2; ++k) \
;       acc[ai][bj][m][n] = __builtin_amdgcn_mfma_f32_16x16x32_bf16(At[m][k], Bx[n][k], acc[ai][bj][m][n], 0, 0, 0); \
;     __builtin_amdgcn_s_setprio(0); } while (0)
; template <bool HS>
; __device__ __forceinline__ void gemm_tile8(const u16* __restrict__ Ap, const u16* __restrict__ Bp, int K,
;                                            f32x4 (&acc)[2][2][4][2], char* shm, const int tid, const float* hsr = nullptr) {
;     ...
;     LDB8(B0, 0, 0); SCHED; LDA8(0, 0); STG_A(1, 1, t + 1);
;     WAIT_L(8); BAR; WAIT_L(0); MMA8(0, 0, B0); BAR; SCHED;
;     ...
;     LDA8(1, 1); STG_A(1, 0, t + 3);
;     BAR; WAIT_L(0); MMA8(1, 0, B0); BAR; SCHED;
;     STG_B(1, 1, t + 3);
;     WAIT_V(6); BAR; MMA8(1, 1, B1); BAR;
;   }
	ds_read_b128 v[158:161], v138 offset:49152
	ds_read_b128 v[162:165], v138 offset:50176
	ds_read_b128 v[166:169], v138 offset:51200
	ds_read_b128 v[170:173], v138 offset:52224
	ds_read_b128 v[174:177], v138 offset:53248
	ds_read_b128 v[180:183], v138 offset:54272
	ds_read_b128 v[184:187], v138 offset:55296
	ds_read_b128 v[188:191], v138 offset:56320
	s_add_u32 s20, s24, s4
	s_addc_u32 s21, s25, s5
	s_add_u32 s20, s20, 0x180
	s_addc_u32 s21, s21, 0
	s_add_i32 s18, s11, 0x18000
	s_mov_b32 m0, s18
	s_nop 0
	global_load_lds_dwordx4 v140, s[20:21]
	s_add_i32 s18, s11, 0x1a000
	s_mov_b32 m0, s18
	s_nop 0
	global_load_lds_dwordx4 v139, s[20:21]
	s_add_u32 s20, s8, s4
	s_addc_u32 s21, s9, s5
	s_add_u32 s20, s20, 0x180
	s_addc_u32 s21, s21, 0
	s_add_i32 s18, s11, 0x8000
	s_mov_b32 m0, s18
	s_nop 0
	global_load_lds_dwordx4 v140, s[20:21]
	s_add_i32 s18, s11, 0xa000
	s_mov_b32 m0, s18
	s_nop 0
	global_load_lds_dwordx4 v139, s[20:21]
	s_add_u32 s20, s22, s4
	s_addc_u32 s21, s23, s5
	s_add_u32 s20, s20, 0x180
	s_addc_u32 s21, s21, 0
	s_add_i32 s18, s11, 0x1c000
	s_mov_b32 m0, s18
	s_nop 0
	global_load_lds_dwordx4 v140, s[20:21]
	s_add_i32 s18, s11, 0x1e000
	s_mov_b32 m0, s18
	s_nop 0
	global_load_lds_dwordx4 v139, s[20:21]
	s_waitcnt vmcnt(8) lgkmcnt(0)
	s_barrier
	s_setprio 1
	v_mfma_f32_16x16x32_bf16 v[62:65], v[158:161], v[142:145], v[62:65]
	v_mfma_f32_16x16x32_bf16 v[58:61], v[158:161], v[150:153], v[58:61]
	v_mfma_f32_16x16x32_bf16 v[54:57], v[166:169], v[142:145], v[54:57]
	v_mfma_f32_16x16x32_bf16 v[50:53], v[166:169], v[150:153], v[50:53]
	v_mfma_f32_16x16x32_bf16 v[46:49], v[174:177], v[142:145], v[46:49]
	v_mfma_f32_16x16x32_bf16 v[42:45], v[174:177], v[150:153], v[42:45]
	v_mfma_f32_16x16x32_bf16 v[38:41], v[184:187], v[142:145], v[38:41]
	v_mfma_f32_16x16x32_bf16 v[34:37], v[184:187], v[150:153], v[34:37]
	v_mfma_f32_16x16x32_bf16 v[62:65], v[162:165], v[146:149], v[62:65]
	v_mfma_f32_16x16x32_bf16 v[58:61], v[162:165], v[154:157], v[58:61]
	v_mfma_f32_16x16x32_bf16 v[54:57], v[170:173], v[146:149], v[54:57]
	v_mfma_f32_16x16x32_bf16 v[50:53], v[170:173], v[154:157], v[50:53]
	v_mfma_f32_16x16x32_bf16 v[46:49], v[180:183], v[146:149], v[46:49]
	v_mfma_f32_16x16x32_bf16 v[42:45], v[180:183], v[154:157], v[42:45]
	v_mfma_f32_16x16x32_bf16 v[38:41], v[188:191], v[146:149], v[38:41]
	v_mfma_f32_16x16x32_bf16 v[34:37], v[188:191], v[154:157], v[34:37]
	v_mfma_f32_16x16x32_bf16 v[30:33], v[158:161], v[192:195], v[30:33]
	v_mfma_f32_16x16x32_bf16 v[26:29], v[158:161], v[200:203], v[26:29]
	v_mfma_f32_16x16x32_bf16 v[22:25], v[166:169], v[192:195], v[22:25]
	v_mfma_f32_16x16x32_bf16 v[18:21], v[166:169], v[200:203], v[18:21]
	v_mfma_f32_16x16x32_bf16 v[14:17], v[174:177], v[192:195], v[14:17]
	v_mfma_f32_16x16x32_bf16 v[10:13], v[174:177], v[200:203], v[10:13]
	v_mfma_f32_16x16x32_bf16 v[6:9], v[184:187], v[192:195], v[6:9]
	v_mfma_f32_16x16x32_bf16 v[2:5], v[184:187], v[200:203], v[2:5]
	v_mfma_f32_16x16x32_bf16 v[30:33], v[162:165], v[196:199], v[30:33]
	v_mfma_f32_16x16x32_bf16 v[26:29], v[162:165], v[204:207], v[26:29]
	v_mfma_f32_16x16x32_bf16 v[22:25], v[170:173], v[196:199], v[22:25]
	v_mfma_f32_16x16x32_bf16 v[18:21], v[170:173], v[204:207], v[18:21]
	v_mfma_f32_16x16x32_bf16 v[14:17], v[180:183], v[196:199], v[14:17]
	v_mfma_f32_16x16x32_bf16 v[10:13], v[180:183], v[204:207], v[10:13]
	v_mfma_f32_16x16x32_bf16 v[6:9], v[188:191], v[196:199], v[6:9]
	v_mfma_f32_16x16x32_bf16 v[2:5], v[188:191], v[204:207], v[2:5]
	s_setprio 0
	s_barrier
	s_add_i32 s17, s17, 2
	s_add_u32 s4, s4, 0x100
	s_addc_u32 s5, s5, 0
	s_cmp_lt_u32 s17, 12
	s_cbranch_scc0 .Lk_conv_in_exit
.Lk_conv_in:
	v_add_u32_e32 v154, 0x10000, v141
	ds_read_b128 v[142:145], v154
	ds_read_b128 v[146:149], v154 offset:1024
	ds_read_b128 v[150:153], v154 offset:2048
	ds_read_b128 v[154:157], v154 offset:3072
	ds_read_b128 v[158:161], v138
	ds_read_b128 v[162:165], v138 offset:1024
	ds_read_b128 v[166:169], v138 offset:2048
	ds_read_b128 v[170:173], v138 offset:3072
	ds_read_b128 v[174:177], v138 offset:4096
	ds_read_b128 v[180:183], v138 offset:5120
	ds_read_b128 v[184:187], v138 offset:6144
	ds_read_b128 v[188:191], v138 offset:7168
	v_add_u32_e32 v204, 0x14000, v141
	ds_read_b128 v[192:195], v204
	ds_read_b128 v[196:199], v204 offset:1024
	ds_read_b128 v[200:203], v204 offset:2048
	ds_read_b128 v[204:207], v204 offset:3072
	s_add_u32 s20, s15, s4
	s_addc_u32 s21, s16, s5
	s_add_u32 s20, s20, 0x80
	s_addc_u32 s21, s21, 0
	s_add_i32 s18, s11, 0xc000
	s_mov_b32 m0, s18
	s_nop 0
	global_load_lds_dwordx4 v140, s[20:21]
	s_add_i32 s18, s11, 0xe000
	s_mov_b32 m0, s18
	s_nop 0
	global_load_lds_dwordx4 v139, s[20:21]
	s_waitcnt vmcnt(8) lgkmcnt(0)
	s_barrier
; #define WAIT_V(n) asm volatile("s_waitcnt vmcnt(" #n ")" ::: "memory")
; #define WAIT_L(n) asm volatile("s_waitcnt lgkmcnt(" #n ")" ::: "memory")
; #define BAR __builtin_amdgcn_s_barrier()
; #define SCHED __builtin_amdgcn_sched_barrier(0)
; #define STG_A(b, h, kt) stage_half_s(lds0 + ((b) * 2 + (h)) * HT_B, ((h) ? A1 : Ap) + (kt) * BK, off0, off1)
; #define STG_B(b, h, kt) stage_half_s(lds0 + (4 + (b) * 2 + (h)) * HT_B, ((h) ? B1p : Bp) + (kt) * BK, off0, off1)
; #define STG_A(b, h, kt) stage_half_s(lds0 + ((b) * 2 + (h)) * HT_B, ((h) ? A1 : Ap) + (kt) * BK, off0, off1)
; #define STG_B(b, h, kt) stage_half_s(lds0 + (4 + (b) * 2 + (h)) * HT_B, ((h) ? B1p : Bp) + (kt) * BK, off0, off1)
; #define LDA8(b, h) _Pragma("unroll") for (int m = 0; m < 4; ++m) _Pragma("unroll") for (int k = 0; k < 2; ++k) \
;     At[m][k] = *(const bf16x8*)(SA_(shm, b, h) + abase + (m * 2 + k) * 1024)
; #define LDB8(dst, b, h) _Pragma("unroll") for (int n = 0; n < 2; ++n) _Pragma("unroll") for (int k = 0; k < 2; ++k) \
;     dst[n][k] = *(const bf16x8*)(SB_(shm, b, h) + bbase + (n * 2 + k) * 1024)
; #define MMA8(ai, bj, Bx) do { __builtin_amdgcn_s_setprio(1); \
;     _Pragma("unroll") for (int m = 0; m < 4; ++m) _Pragma("unroll") for (int n = 0; n < 2; ++n) _Pragma("unroll") for (int k = 0; k < 2; ++k) \
;       acc[ai][bj][m][n] = __builtin_amdgcn_mfma_f32_16x16x32_bf16(At[m][k], Bx[n][k], acc[ai][bj][m][n], 0, 0, 0); \
;     __builtin_amdgcn_s_setprio(0); } while (0)
; template <bool HS>
; __device__ __forceinline__ void gemm_tile8(const u16* __restrict__ Ap, const u16* __restrict__ Bp, int K,
;                                            f32x4 (&acc)[2][2][4][2], char* shm, const int tid, const float* hsr = nullptr) {
;     ...
;     WAIT_L(8); BAR; WAIT_L(0); MMA8(0, 0, B0); BAR; SCHED;
;     LDB8(B1, 0, 1); STG_B(0, 0, t + 2);
;     BAR; WAIT_L(0); MMA8(0, 1, B1); BAR;
;     LDA8(0, 1); STG_A(0, 0, t + 2);
;     BAR; WAIT_L(0); MMA8(1, 0, B0); BAR; SCHED;
;     STG_B(0, 1, t + 2);
;     WAIT_V(6); BAR; MMA8(1, 1, B1); BAR;
	s_setprio 1
	v_mfma_f32_16x16x32_bf16 v[126:129], v[158:161], v[142:145], v[126:129]
	v_mfma_f32_16x16x32_bf16 v[122:125], v[158:161], v[150:153], v[122:125]
	v_mfma_f32_16x16x32_bf16 v[118:121], v[166:169], v[142:145], v[118:121]
	v_mfma_f32_16x16x32_bf16 v[114:117], v[166:169], v[150:153], v[114:117]
	v_mfma_f32_16x16x32_bf16 v[110:113], v[174:177], v[142:145], v[110:113]
	v_mfma_f32_16x16x32_bf16 v[106:109], v[174:177], v[150:153], v[106:109]
	v_mfma_f32_16x16x32_bf16 v[102:105], v[184:187], v[142:145], v[102:105]
	v_mfma_f32_16x16x32_bf16 v[98:101], v[184:187], v[150:153], v[98:101]
	v_mfma_f32_16x16x32_bf16 v[126:129], v[162:165], v[146:149], v[126:129]
	v_mfma_f32_16x16x32_bf16 v[122:125], v[162:165], v[154:157], v[122:125]
	v_mfma_f32_16x16x32_bf16 v[118:121], v[170:173], v[146:149], v[118:121]
	v_mfma_f32_16x16x32_bf16 v[114:117], v[170:173], v[154:157], v[114:117]
	v_mfma_f32_16x16x32_bf16 v[110:113], v[180:183], v[146:149], v[110:113]
	v_mfma_f32_16x16x32_bf16 v[106:109], v[180:183], v[154:157], v[106:109]
	v_mfma_f32_16x16x32_bf16 v[102:105], v[188:191], v[146:149], v[102:105]
	v_mfma_f32_16x16x32_bf16 v[98:101], v[188:191], v[154:157], v[98:101]
	v_mfma_f32_16x16x32_bf16 v[94:97], v[158:161], v[192:195], v[94:97]
	v_mfma_f32_16x16x32_bf16 v[90:93], v[158:161], v[200:203], v[90:93]
	v_mfma_f32_16x16x32_bf16 v[86:89], v[166:169], v[192:195], v[86:89]
	v_mfma_f32_16x16x32_bf16 v[82:85], v[166:169], v[200:203], v[82:85]
	v_mfma_f32_16x16x32_bf16 v[78:81], v[174:177], v[192:195], v[78:81]
	v_mfma_f32_16x16x32_bf16 v[74:77], v[174:177], v[200:203], v[74:77]
	v_mfma_f32_16x16x32_bf16 v[70:73], v[184:187], v[192:195], v[70:73]
	v_mfma_f32_16x16x32_bf16 v[66:69], v[184:187], v[200:203], v[66:69]
	v_mfma_f32_16x16x32_bf16 v[94:97], v[162:165], v[196:199], v[94:97]
	v_mfma_f32_16x16x32_bf16 v[90:93], v[162:165], v[204:207], v[90:93]
	v_mfma_f32_16x16x32_bf16 v[86:89], v[170:173], v[196:199], v[86:89]
	v_mfma_f32_16x16x32_bf16 v[82:85], v[170:173], v[204:207], v[82:85]
	v_mfma_f32_16x16x32_bf16 v[78:81], v[180:183], v[196:199], v[78:81]
	v_mfma_f32_16x16x32_bf16 v[74:77], v[180:183], v[204:207], v[74:77]
	v_mfma_f32_16x16x32_bf16 v[70:73], v[188:191], v[196:199], v[70:73]
	v_mfma_f32_16x16x32_bf16 v[66:69], v[188:191], v[204:207], v[66:69]
	s_setprio 0
	s_barrier
	ds_read_b128 v[158:161], v138 offset:16384
	ds_read_b128 v[162:165], v138 offset:17408
	ds_read_b128 v[166:169], v138 offset:18432
	ds_read_b128 v[170:173], v138 offset:19456
	ds_read_b128 v[174:177], v138 offset:20480
	ds_read_b128 v[180:183], v138 offset:21504
	ds_read_b128 v[184:187], v138 offset:22528
	ds_read_b128 v[188:191], v138 offset:23552
	s_add_u32 s20, s24, s4
	s_addc_u32 s21, s25, s5
	s_add_u32 s20, s20, 0x100
	s_addc_u32 s21, s21, 0
	s_add_i32 s18, s11, 0x10000
	s_mov_b32 m0, s18
	s_nop 0
	global_load_lds_dwordx4 v140, s[20:21]
	s_add_i32 s18, s11, 0x12000
	s_mov_b32 m0, s18
	s_nop 0
	global_load_lds_dwordx4 v139, s[20:21]
	s_add_u32 s20, s8, s4
	s_addc_u32 s21, s9, s5
	s_add_u32 s20, s20, 0x100
	s_addc_u32 s21, s21, 0
	s_mov_b32 m0, s11
	s_nop 0
	global_load_lds_dwordx4 v140, s[20:21]
	s_add_i32 s18, s11, 0x2000
	s_mov_b32 m0, s18
	s_nop 0
	global_load_lds_dwordx4 v139, s[20:21]
	s_add_u32 s20, s22, s4
	s_addc_u32 s21, s23, s5
	s_add_u32 s20, s20, 0x100
	s_addc_u32 s21, s21, 0
	s_add_i32 s18, s11, 0x14000
	s_mov_b32 m0, s18
	s_nop 0
	global_load_lds_dwordx4 v140, s[20:21]
	s_add_i32 s18, s11, 0x16000
	s_mov_b32 m0, s18
	s_nop 0
	global_load_lds_dwordx4 v139, s[20:21]
	s_waitcnt vmcnt(8) lgkmcnt(0)
	s_barrier
	s_setprio 1
	v_mfma_f32_16x16x32_bf16 v[62:65], v[158:161], v[142:145], v[62:65]
	v_mfma_f32_16x16x32_bf16 v[58:61], v[158:161], v[150:153], v[58:61]
	v_mfma_f32_16x16x32_bf16 v[54:57], v[166:169], v[142:145], v[54:57]
	v_mfma_f32_16x16x32_bf16 v[50:53], v[166:169], v[150:153], v[50:53]
	v_mfma_f32_16x16x32_bf16 v[46:49], v[174:177], v[142:145], v[46:49]
	v_mfma_f32_16x16x32_bf16 v[42:45], v[174:177], v[150:153], v[42:45]
	v_mfma_f32_16x16x32_bf16 v[38:41], v[184:187], v[142:145], v[38:41]
	v_mfma_f32_16x16x32_bf16 v[34:37], v[184:187], v[150:153], v[34:37]
	v_mfma_f32_16x16x32_bf16 v[62:65], v[162:165], v[146:149], v[62:65]
	v_mfma_f32_16x16x32_bf16 v[58:61], v[162:165], v[154:157], v[58:61]
	v_mfma_f32_16x16x32_bf16 v[54:57], v[170:173], v[146:149], v[54:57]
	v_mfma_f32_16x16x32_bf16 v[50:53], v[170:173], v[154:157], v[50:53]
	v_mfma_f32_16x16x32_bf16 v[46:49], v[180:183], v[146:149], v[46:49]
	v_mfma_f32_16x16x32_bf16 v[42:45], v[180:183], v[154:157], v[42:45]
	v_mfma_f32_16x16x32_bf16 v[38:41], v[188:191], v[146:149], v[38:41]
	v_mfma_f32_16x16x32_bf16 v[34:37], v[188:191], v[154:157], v[34:37]
	v_mfma_f32_16x16x32_bf16 v[30:33], v[158:161], v[192:195], v[30:33]
	v_mfma_f32_16x16x32_bf16 v[26:29], v[158:161], v[200:203], v[26:29]
	v_mfma_f32_16x16x32_bf16 v[22:25], v[166:169], v[192:195], v[22:25]
	v_mfma_f32_16x16x32_bf16 v[18:21], v[166:169], v[200:203], v[18:21]
	v_mfma_f32_16x16x32_bf16 v[14:17], v[174:177], v[192:195], v[14:17]
	v_mfma_f32_16x16x32_bf16 v[10:13], v[174:177], v[200:203], v[10:13]
	v_mfma_f32_16x16x32_bf16 v[6:9], v[184:187], v[192:195], v[6:9]
	v_mfma_f32_16x16x32_bf16 v[2:5], v[184:187], v[200:203], v[2:5]
	v_mfma_f32_16x16x32_bf16 v[30:33], v[162:165], v[196:199], v[30:33]
	v_mfma_f32_16x16x32_bf16 v[26:29], v[162:165], v[204:207], v[26:29]
	v_mfma_f32_16x16x32_bf16 v[22:25], v[170:173], v[196:199], v[22:25]
	v_mfma_f32_16x16x32_bf16 v[18:21], v[170:173], v[204:207], v[18:21]
	v_mfma_f32_16x16x32_bf16 v[14:17], v[180:183], v[196:199], v[14:17]
	v_mfma_f32_16x16x32_bf16 v[10:13], v[180:183], v[204:207], v[10:13]
	v_mfma_f32_16x16x32_bf16 v[6:9], v[188:191], v[196:199], v[6:9]
	v_mfma_f32_16x16x32_bf16 v[2:5], v[188:191], v[204:207], v[2:5]
	s_setprio 0
	s_barrier
; #define WAIT_V(n) asm volatile("s_waitcnt vmcnt(" #n ")" ::: "memory")
; #define WAIT_L(n) asm volatile("s_waitcnt lgkmcnt(" #n ")" ::: "memory")
; #define BAR __builtin_amdgcn_s_barrier()
; #define SCHED __builtin_amdgcn_sched_barrier(0)
; #define STG_A(b, h, kt) stage_half_s(lds0 + ((b) * 2 + (h)) * HT_B, ((h) ? A1 : Ap) + (kt) * BK, off0, off1)
; #define STG_B(b, h, kt) stage_half_s(lds0 + (4 + (b) * 2 + (h)) * HT_B, ((h) ? B1p : Bp) + (kt) * BK, off0, off1)
; #define STG_A(b, h, kt) stage_half_s(lds0 + ((b) * 2 + (h)) * HT_B, ((h) ? A1 : Ap) + (kt) * BK, off0, off1)
; #define STG_B(b, h, kt) stage_half_s(lds0 + (4 + (b) * 2 + (h)) * HT_B, ((h) ? B1p : Bp) + (kt) * BK, off0, off1)
; #define LDA8(b, h) _Pragma("unroll") for (int m = 0; m < 4; ++m) _Pragma("unroll") for (int k = 0; k < 2; ++k) \
;     At[m][k] = *(const bf16x8*)(SA_(shm, b, h) + abase + (m * 2 + k) * 1024)
; #define LDB8(dst, b, h) _Pragma("unroll") for (int n = 0; n < 2; ++n) _Pragma("unroll") for (int k = 0; k < 2; ++k) \
;     dst[n][k] = *(const bf16x8*)(SB_(shm, b, h) + bbase + (n * 2 + k) * 1024)
; #define MMA8(ai, bj, Bx) do { __builtin_amdgcn_s_setprio(1); \
;     _Pragma("unroll") for (int m = 0; m < 4; ++m) _Pragma("unroll") for (int n = 0; n < 2; ++n) _Pragma("unroll") for (int k = 0; k < 2; ++k) \
;       acc[ai][bj][m][n] = __builtin_amdgcn_mfma_f32_16x16x32_bf16(At[m][k], Bx[n][k], acc[ai][bj][m][n], 0, 0, 0); \
;     __builtin_amdgcn_s_setprio(0); } while (0)
; template <bool HS>
; __device__ __forceinline__ void gemm_tile8(const u16* __restrict__ Ap, const u16* __restrict__ Bp, int K,
;                                            f32x4 (&acc)[2][2][4][2], char* shm, const int tid, const float* hsr = nullptr) {
;     ...
;     LDB8(B0, 1, 0); SCHED; LDA8(1, 0); STG_A(0, 1, t + 2);
;     WAIT_L(8); BAR; WAIT_L(0); MMA8(0, 0, B0); BAR; SCHED;
;     LDB8(B1, 1, 1); STG_B(1, 0, t + 3);
;     BAR; WAIT_L(0); MMA8(0, 1, B1); BAR;
;     LDA8(1, 1); STG_A(1, 0, t + 3);
;     BAR; WAIT_L(0); MMA8(1, 0, B0); BAR; SCHED;
;     STG_B(1, 1, t + 3);
;     WAIT_V(6); BAR; MMA8(1, 1, B1); BAR;
;   }
	v_add_u32_e32 v154, 0x18000, v141
	ds_read_b128 v[142:145], v154
	ds_read_b128 v[146:149], v154 offset:1024
	ds_read_b128 v[150:153], v154 offset:2048
	ds_read_b128 v[154:157], v154 offset:3072
	ds_read_b128 v[158:161], v138 offset:32768
	ds_read_b128 v[162:165], v138 offset:33792
	ds_read_b128 v[166:169], v138 offset:34816
	ds_read_b128 v[170:173], v138 offset:35840
	ds_read_b128 v[174:177], v138 offset:36864
	ds_read_b128 v[180:183], v138 offset:37888
	ds_read_b128 v[184:187], v138 offset:38912
	ds_read_b128 v[188:191], v138 offset:39936
	v_add_u32_e32 v204, 0x1c000, v141
	ds_read_b128 v[192:195], v204
	ds_read_b128 v[196:199], v204 offset:1024
	ds_read_b128 v[200:203], v204 offset:2048
	ds_read_b128 v[204:207], v204 offset:3072
	s_add_u32 s20, s15, s4
	s_addc_u32 s21, s16, s5
	s_add_u32 s20, s20, 0x100
	s_addc_u32 s21, s21, 0
	s_add_i32 s18, s11, 0x4000
	s_mov_b32 m0, s18
	s_nop 0
	global_load_lds_dwordx4 v140, s[20:21]
	s_add_i32 s18, s11, 0x6000
	s_mov_b32 m0, s18
	s_nop 0
	global_load_lds_dwordx4 v139, s[20:21]
	s_waitcnt vmcnt(8) lgkmcnt(0)
	s_barrier
	s_setprio 1
	v_mfma_f32_16x16x32_bf16 v[126:129], v[158:161], v[142:145], v[126:129]
	v_mfma_f32_16x16x32_bf16 v[122:125], v[158:161], v[150:153], v[122:125]
	v_mfma_f32_16x16x32_bf16 v[118:121], v[166:169], v[142:145], v[118:121]
	v_mfma_f32_16x16x32_bf16 v[114:117], v[166:169], v[150:153], v[114:117]
	v_mfma_f32_16x16x32_bf16 v[110:113], v[174:177], v[142:145], v[110:113]
	v_mfma_f32_16x16x32_bf16 v[106:109], v[174:177], v[150:153], v[106:109]
	v_mfma_f32_16x16x32_bf16 v[102:105], v[184:187], v[142:145], v[102:105]
	v_mfma_f32_16x16x32_bf16 v[98:101], v[184:187], v[150:153], v[98:101]
	v_mfma_f32_16x16x32_bf16 v[126:129], v[162:165], v[146:149], v[126:129]
	v_mfma_f32_16x16x32_bf16 v[122:125], v[162:165], v[154:157], v[122:125]
	v_mfma_f32_16x16x32_bf16 v[118:121], v[170:173], v[146:149], v[118:121]
	v_mfma_f32_16x16x32_bf16 v[114:117], v[170:173], v[154:157], v[114:117]
	v_mfma_f32_16x16x32_bf16 v[110:113], v[180:183], v[146:149], v[110:113]
	v_mfma_f32_16x16x32_bf16 v[106:109], v[180:183], v[154:157], v[106:109]
	v_mfma_f32_16x16x32_bf16 v[102:105], v[188:191], v[146:149], v[102:105]
	v_mfma_f32_16x16x32_bf16 v[98:101], v[188:191], v[154:157], v[98:101]
	v_mfma_f32_16x16x32_bf16 v[94:97], v[158:161], v[192:195], v[94:97]
	v_mfma_f32_16x16x32_bf16 v[90:93], v[158:161], v[200:203], v[90:93]
	v_mfma_f32_16x16x32_bf16 v[86:89], v[166:169], v[192:195], v[86:89]
	v_mfma_f32_16x16x32_bf16 v[82:85], v[166:169], v[200:203], v[82:85]
	v_mfma_f32_16x16x32_bf16 v[78:81], v[174:177], v[192:195], v[78:81]
	v_mfma_f32_16x16x32_bf16 v[74:77], v[174:177], v[200:203], v[74:77]
	v_mfma_f32_16x16x32_bf16 v[70:73], v[184:187], v[192:195], v[70:73]
	v_mfma_f32_16x16x32_bf16 v[66:69], v[184:187], v[200:203], v[66:69]
	v_mfma_f32_16x16x32_bf16 v[94:97], v[162:165], v[196:199], v[94:97]
	v_mfma_f32_16x16x32_bf16 v[90:93], v[162:165], v[204:207], v[90:93]
	v_mfma_f32_16x16x32_bf16 v[86:89], v[170:173], v[196:199], v[86:89]
	v_mfma_f32_16x16x32_bf16 v[82:85], v[170:173], v[204:207], v[82:85]
	v_mfma_f32_16x16x32_bf16 v[78:81], v[180:183], v[196:199], v[78:81]
	v_mfma_f32_16x16x32_bf16 v[74:77], v[180:183], v[204:207], v[74:77]
	v_mfma_f32_16x16x32_bf16 v[70:73], v[188:191], v[196:199], v[70:73]
	v_mfma_f32_16x16x32_bf16 v[66:69], v[188:191], v[204:207], v[66:69]
	s_setprio 0
	s_barrier
	ds_read_b128 v[158:161], v138 offset:49152
	ds_read_b128 v[162:165], v138 offset:50176
	ds_read_b128 v[166:169], v138 offset:51200
	ds_read_b128 v[170:173], v138 offset:52224
	ds_read_b128 v[174:177], v138 offset:53248
	ds_read_b128 v[180:183], v138 offset:54272
	ds_read_b128 v[184:187], v138 offset:55296
	ds_read_b128 v[188:191], v138 offset:56320
	s_add_u32 s20, s24, s4
	s_addc_u32 s21, s25, s5
	s_add_u32 s20, s20, 0x180
	s_addc_u32 s21, s21, 0
	s_add_i32 s18, s11, 0x18000
	s_mov_b32 m0, s18
	s_nop 0
	global_load_lds_dwordx4 v140, s[20:21]
	s_add_i32 s18, s11, 0x1a000
	s_mov_b32 m0, s18
	s_nop 0
	global_load_lds_dwordx4 v139, s[20:21]
	s_add_u32 s20, s8, s4
	s_addc_u32 s21, s9, s5
	s_add_u32 s20, s20, 0x180
	s_addc_u32 s21, s21, 0
	s_add_i32 s18, s11, 0x8000
	s_mov_b32 m0, s18
	s_nop 0
	global_load_lds_dwordx4 v140, s[20:21]
	s_add_i32 s18, s11, 0xa000
	s_mov_b32 m0, s18
	s_nop 0
	global_load_lds_dwordx4 v139, s[20:21]
	s_add_u32 s20, s22, s4
	s_addc_u32 s21, s23, s5
	s_add_u32 s20, s20, 0x180
	s_addc_u32 s21, s21, 0
	s_add_i32 s18, s11, 0x1c000
	s_mov_b32 m0, s18
	s_nop 0
	global_load_lds_dwordx4 v140, s[20:21]
	s_add_i32 s18, s11, 0x1e000
	s_mov_b32 m0, s18
	s_nop 0
	global_load_lds_dwordx4 v139, s[20:21]
	s_waitcnt vmcnt(8) lgkmcnt(0)
	s_barrier
	s_setprio 1
	v_mfma_f32_16x16x32_bf16 v[62:65], v[158:161], v[142:145], v[62:65]
	v_mfma_f32_16x16x32_bf16 v[58:61], v[158:161], v[150:153], v[58:61]
	v_mfma_f32_16x16x32_bf16 v[54:57], v[166:169], v[142:145], v[54:57]
	v_mfma_f32_16x16x32_bf16 v[50:53], v[166:169], v[150:153], v[50:53]
	v_mfma_f32_16x16x32_bf16 v[46:49], v[174:177], v[142:145], v[46:49]
	v_mfma_f32_16x16x32_bf16 v[42:45], v[174:177], v[150:153], v[42:45]
	v_mfma_f32_16x16x32_bf16 v[38:41], v[184:187], v[142:145], v[38:41]
	v_mfma_f32_16x16x32_bf16 v[34:37], v[184:187], v[150:153], v[34:37]
	v_mfma_f32_16x16x32_bf16 v[62:65], v[162:165], v[146:149], v[62:65]
	v_mfma_f32_16x16x32_bf16 v[58:61], v[162:165], v[154:157], v[58:61]
	v_mfma_f32_16x16x32_bf16 v[54:57], v[170:173], v[146:149], v[54:57]
	v_mfma_f32_16x16x32_bf16 v[50:53], v[170:173], v[154:157], v[50:53]
	v_mfma_f32_16x16x32_bf16 v[46:49], v[180:183], v[146:149], v[46:49]
	v_mfma_f32_16x16x32_bf16 v[42:45], v[180:183], v[154:157], v[42:45]
	v_mfma_f32_16x16x32_bf16 v[38:41], v[188:191], v[146:149], v[38:41]
	v_mfma_f32_16x16x32_bf16 v[34:37], v[188:191], v[154:157], v[34:37]
	v_mfma_f32_16x16x32_bf16 v[30:33], v[158:161], v[192:195], v[30:33]
	v_mfma_f32_16x16x32_bf16 v[26:29], v[158:161], v[200:203], v[26:29]
	v_mfma_f32_16x16x32_bf16 v[22:25], v[166:169], v[192:195], v[22:25]
	v_mfma_f32_16x16x32_bf16 v[18:21], v[166:169], v[200:203], v[18:21]
	v_mfma_f32_16x16x32_bf16 v[14:17], v[174:177], v[192:195], v[14:17]
	v_mfma_f32_16x16x32_bf16 v[10:13], v[174:177], v[200:203], v[10:13]
	v_mfma_f32_16x16x32_bf16 v[6:9], v[184:187], v[192:195], v[6:9]
	v_mfma_f32_16x16x32_bf16 v[2:5], v[184:187], v[200:203], v[2:5]
	v_mfma_f32_16x16x32_bf16 v[30:33], v[162:165], v[196:199], v[30:33]
	v_mfma_f32_16x16x32_bf16 v[26:29], v[162:165], v[204:207], v[26:29]
	v_mfma_f32_16x16x32_bf16 v[22:25], v[170:173], v[196:199], v[22:25]
	v_mfma_f32_16x16x32_bf16 v[18:21], v[170:173], v[204:207], v[18:21]
	v_mfma_f32_16x16x32_bf16 v[14:17], v[180:183], v[196:199], v[14:17]
	v_mfma_f32_16x16x32_bf16 v[10:13], v[180:183], v[204:207], v[10:13]
	v_mfma_f32_16x16x32_bf16 v[6:9], v[188:191], v[196:199], v[6:9]
	v_mfma_f32_16x16x32_bf16 v[2:5], v[188:191], v[204:207], v[2:5]
	s_setprio 0
	s_barrier
	s_add_i32 s17, s17, 2
	s_add_u32 s4, s4, 0x100
	s_addc_u32 s5, s5, 0
	s_cmp_lt_u32 s17, 12
	s_cbranch_scc1 .Lk_conv_in

; #define WAIT_V(n) asm volatile("s_waitcnt vmcnt(" #n ")" ::: "memory")
; #define WAIT_L(n) asm volatile("s_waitcnt lgkmcnt(" #n ")" ::: "memory")
; #define BAR __builtin_amdgcn_s_barrier()
; #define SCHED __builtin_amdgcn_sched_barrier(0)
; #define STG_A(b, h, kt) stage_half_s(lds0 + ((b) * 2 + (h)) * HT_B, ((h) ? A1 : Ap) + (kt) * BK, off0, off1)
; #define STG_A(b, h, kt) stage_half_s(lds0 + ((b) * 2 + (h)) * HT_B, ((h) ? A1 : Ap) + (kt) * BK, off0, off1)
; #define LDA8(b, h) _Pragma("unroll") for (int m = 0; m < 4; ++m) _Pragma("unroll") for (int k = 0; k < 2; ++k) \
;     At[m][k] = *(const bf16x8*)(SA_(shm, b, h) + abase + (m * 2 + k) * 1024)
; #define LDB8(dst, b, h) _Pragma("unroll") for (int n = 0; n < 2; ++n) _Pragma("unroll") for (int k = 0; k < 2; ++k) \
;     dst[n][k] = *(const bf16x8*)(SB_(shm, b, h) + bbase + (n * 2 + k) * 1024)
; template <bool HS>
; __device__ __forceinline__ void gemm_tile8(const u16* __restrict__ Ap, const u16* __restrict__ Bp, int K,
;                                            f32x4 (&acc)[2][2][4][2], char* shm, const int tid, const float* hsr = nullptr) {
;   const int wid = tid >> 6, lane = tid & 63, wr = wid >> 2, wc = wid & 3, fr = lane & 15, fq = lane >> 4;
;   int r0, c0, r1, c1;
;   stage_rc(tid * 16, r0, c0);
;   stage_rc(tid * 16 + 8192, r1, c1);
;   const unsigned off0 = (unsigned)(r0 * K + c0) * 2u, off1 = (unsigned)(r1 * K + c1) * 2u;
;   const int wvoff = __builtin_amdgcn_readfirstlane(tid >> 6) * 1024;
;   const u16* A1 = Ap + (size_t)128 * K;
;   const u16* B1p = Bp + (size_t)128 * K;
; #pragma unroll
;   for (int a = 0; a < 2; ++a)
; #pragma unroll
;     for (int b = 0; b < 2; ++b)
; #pragma unroll
;       for (int m = 0; m < 4; ++m)
; #pragma unroll
;         for (int n = 0; n < 2; ++n) acc[a][b][m][n] = f32x4{0.f, 0.f, 0.f, 0.f};
;   const int abase = lds_byte(wr * 64 + fr, fq * 8), bbase = lds_byte(wc * 32 + fr, fq * 8);
;   bf16x8 At[4][2], B0[2][2], B1[2][2];
;   const unsigned lds0 = (unsigned)(size_t)(__attribute__((address_space(3))) char*)shm + (unsigned)wvoff;
;     ...
;   const int nt = K / BK;
;   WAIT_V(0);
;   if (wr == 1) BAR;
;   BAR;
;     ...
;     LDB8(B0, 0, 0); SCHED; LDA8(0, 0); STG_A(1, 1, t + 1);
;     WAIT_L(8); BAR; WAIT_L(0); MMA8(0, 0, B0); BAR; SCHED;
.LBB0_582:
	s_or_b64 exec, exec, s[8:9]
	v_bfe_i32 v6, v0, 27, 1
	v_lshlrev_b32_e32 v4, 4, v0
	v_lshrrev_b32_e32 v6, 22, v6
	v_add_u32_e32 v6, v4, v6
	v_and_b32_e32 v6, 0xfffffc00, v6
	v_ashrrev_i32_e32 v5, 31, v0
	v_sub_u32_e32 v6, v4, v6
	v_lshrrev_b32_e32 v5, 26, v5
	v_lshrrev_b32_e32 v7, 4, v6
	v_add_u32_e32 v5, v0, v5
	v_bitop3_b32 v7, v7, v6, 32 bitop3:0x6c
	v_ashrrev_i32_e32 v6, 31, v6
	v_ashrrev_i32_e32 v5, 6, v5
	v_lshrrev_b32_e32 v6, 26, v6
	v_lshlrev_b32_e32 v8, 3, v5
	v_add_u32_e32 v6, v7, v6
	v_and_b32_e32 v8, 0x1ffff0, v8
	v_ashrrev_i32_e32 v6, 6, v6
	v_add_u32_e32 v8, v6, v8
	v_mul_i32_i24_e32 v6, 64, v6
	v_add_u32_e32 v4, 0x2000, v4
	v_sub_u32_e32 v6, v7, v6
	v_ashrrev_i32_e32 v7, 31, v4
	v_lshrrev_b32_e32 v7, 22, v7
	v_add_u32_e32 v7, v4, v7
	v_ashrrev_i32_e32 v7, 10, v7
	v_mul_i32_i24_e32 v9, 0x400, v7
	v_sub_u32_e32 v4, v4, v9
	v_lshrrev_b32_e32 v9, 4, v4
	v_bitop3_b32 v4, v9, v4, 32 bitop3:0x6c
	s_ashr_i32 s7, s6, 31
	v_ashrrev_i32_e32 v10, 31, v4
	s_lshl_b64 s[6:7], s[6:7], 11
	v_readlane_b32 s20, v254, 47
	v_lshrrev_b32_e32 v10, 26, v10
	v_readlane_b32 s21, v254, 48
	s_add_u32 s8, s20, s6
	v_add_u32_e32 v10, v4, v10
	s_addc_u32 s9, s21, s7
	s_ashr_i32 s3, s2, 31
	v_lshlrev_b32_e32 v9, 3, v7
	v_lshrrev_b32_e32 v11, 6, v10
	v_and_b32_e32 v10, 0xc0, v10
	s_lshl_b64 s[6:7], s[2:3], 19
	v_readlane_b32 s3, v255, 7
	v_and_b32_e32 v9, 0x1ffff0, v9
	v_lshlrev_b32_e32 v7, 5, v7
	v_sub_u32_e32 v4, v4, v10
	s_add_u32 s3, s3, s6
	v_readlane_b32 s6, v255, 8
	v_lshlrev_b32_e32 v5, 5, v5
	v_add_u32_e32 v9, v11, v9
	v_and_b32_e32 v7, 32, v7
	v_ashrrev_i16_sdwa v4, v178, sext(v4) dst_sel:DWORD dst_unused:UNUSED_PAD src0_sel:DWORD src1_sel:BYTE_0
	s_addc_u32 s10, s6, s7
	v_and_b32_e32 v5, 32, v5
	v_ashrrev_i16_sdwa v6, v178, sext(v6) dst_sel:DWORD dst_unused:UNUSED_PAD src0_sel:DWORD src1_sel:BYTE_0
	v_bfe_i32 v4, v4, 0, 16
	v_lshl_or_b32 v7, v9, 10, v7
	s_lshl_b32 s11, s11, 10
	v_bfe_i32 v6, v6, 0, 16
	v_lshl_or_b32 v5, v8, 10, v5
	v_and_b32_e32 v8, 15, v0
	v_add_lshl_u32 v131, v7, v4, 1
	s_add_u32 s13, s3, 0x40000
	v_lshlrev_b32_e32 v7, 2, v0
	v_add_lshl_u32 v132, v5, v6, 1
	s_addc_u32 s14, s10, 0
	v_and_b32_e32 v4, 48, v0
	v_lshlrev_b32_e32 v5, 6, v8
	v_and_b32_e32 v7, 32, v7
	s_add_i32 s15, s11, 0
	v_or_b32_e32 v6, v5, v4
	v_bitop3_b32 v4, v5, v7, v4 bitop3:0x36
	v_lshlrev_b32_e32 v2, 12, v2
	s_movk_i32 s6, 0x3000
	s_add_u32 s16, s8, 0x40100
	v_and_or_b32 v133, v2, s6, v4
	s_addc_u32 s17, s9, 0
	s_add_i32 s6, s18, s19
	s_ashr_i32 s7, s6, 31
	v_lshlrev_b32_e32 v3, 13, v3
	s_lshl_b64 s[6:7], s[6:7], 11
	v_readlane_b32 s18, v254, 34
	v_bitop3_b32 v3, v6, v3, v7 bitop3:0xde
	s_add_u32 s18, s18, s6
	v_readlane_b32 s6, v254, 35
	v_mov_b32_e32 v2, 0
	s_addc_u32 s19, s6, s7
	s_mov_b32 s20, -2
	s_mov_b64 s[6:7], 0
	v_add_u32_e32 v130, 0, v3
	s_waitcnt lgkmcnt(0)
	v_readlane_b32 s22, v254, 49
	v_readlane_b32 s23, v254, 50
	s_barrier
	s_barrier
	v_add_u32_e32 v154, 0x10000, v133
	ds_read_b128 v[142:145], v154
	ds_read_b128 v[146:149], v154 offset:1024
	ds_read_b128 v[150:153], v154 offset:2048
	ds_read_b128 v[154:157], v154 offset:3072
	ds_read_b128 v[158:161], v130
	ds_read_b128 v[164:167], v130 offset:1024
	ds_read_b128 v[168:171], v130 offset:2048
	ds_read_b128 v[172:175], v130 offset:3072
	ds_read_b128 v[180:183], v130 offset:4096
	ds_read_b128 v[184:187], v130 offset:5120
	ds_read_b128 v[188:191], v130 offset:6144
	ds_read_b128 v[192:195], v130 offset:7168
	v_add_u32_e32 v208, 0x14000, v133
	ds_read_b128 v[196:199], v208
	ds_read_b128 v[200:203], v208 offset:1024
	ds_read_b128 v[204:207], v208 offset:2048
	ds_read_b128 v[208:211], v208 offset:3072
	s_add_u32 s24, s18, s6
	s_addc_u32 s25, s19, s7
	s_add_u32 s24, s24, 0x80
	s_addc_u32 s25, s25, 0
	s_add_i32 s23, s15, 0xc000
	s_mov_b32 m0, s23
	s_nop 0
	global_load_lds_dwordx4 v132, s[24:25]
	s_add_i32 s23, s15, 0xe000
	s_mov_b32 m0, s23
	s_nop 0
	global_load_lds_dwordx4 v131, s[24:25]
	s_waitcnt vmcnt(8) lgkmcnt(0)
	s_barrier
	s_setprio 1
	v_mfma_f32_16x16x32_bf16 v[126:129], v[158:161], v[142:145], 0
	v_mfma_f32_16x16x32_bf16 v[122:125], v[158:161], v[150:153], 0
	v_mfma_f32_16x16x32_bf16 v[118:121], v[168:171], v[142:145], 0
	v_mfma_f32_16x16x32_bf16 v[114:117], v[168:171], v[150:153], 0
	v_mfma_f32_16x16x32_bf16 v[110:113], v[180:183], v[142:145], 0
	v_mfma_f32_16x16x32_bf16 v[106:109], v[180:183], v[150:153], 0
	v_mfma_f32_16x16x32_bf16 v[102:105], v[188:191], v[142:145], 0
	v_mfma_f32_16x16x32_bf16 v[98:101], v[188:191], v[150:153], 0
	v_mfma_f32_16x16x32_bf16 v[126:129], v[164:167], v[146:149], v[126:129]
	v_mfma_f32_16x16x32_bf16 v[122:125], v[164:167], v[154:157], v[122:125]
	v_mfma_f32_16x16x32_bf16 v[118:121], v[172:175], v[146:149], v[118:121]
	v_mfma_f32_16x16x32_bf16 v[114:117], v[172:175], v[154:157], v[114:117]
	v_mfma_f32_16x16x32_bf16 v[110:113], v[184:187], v[146:149], v[110:113]
	v_mfma_f32_16x16x32_bf16 v[106:109], v[184:187], v[154:157], v[106:109]
	v_mfma_f32_16x16x32_bf16 v[102:105], v[192:195], v[146:149], v[102:105]
	v_mfma_f32_16x16x32_bf16 v[98:101], v[192:195], v[154:157], v[98:101]
	v_mfma_f32_16x16x32_bf16 v[94:97], v[158:161], v[196:199], 0
	v_mfma_f32_16x16x32_bf16 v[90:93], v[158:161], v[204:207], 0
	v_mfma_f32_16x16x32_bf16 v[86:89], v[168:171], v[196:199], 0
	v_mfma_f32_16x16x32_bf16 v[82:85], v[168:171], v[204:207], 0
	v_mfma_f32_16x16x32_bf16 v[78:81], v[180:183], v[196:199], 0
	v_mfma_f32_16x16x32_bf16 v[74:77], v[180:183], v[204:207], 0
	v_mfma_f32_16x16x32_bf16 v[70:73], v[188:191], v[196:199], 0
	v_mfma_f32_16x16x32_bf16 v[66:69], v[188:191], v[204:207], 0
	v_mfma_f32_16x16x32_bf16 v[94:97], v[164:167], v[200:203], v[94:97]
	v_mfma_f32_16x16x32_bf16 v[90:93], v[164:167], v[208:211], v[90:93]
	v_mfma_f32_16x16x32_bf16 v[86:89], v[172:175], v[200:203], v[86:89]
	v_mfma_f32_16x16x32_bf16 v[82:85], v[172:175], v[208:211], v[82:85]
	v_mfma_f32_16x16x32_bf16 v[78:81], v[184:187], v[200:203], v[78:81]
	v_mfma_f32_16x16x32_bf16 v[74:77], v[184:187], v[208:211], v[74:77]
	v_mfma_f32_16x16x32_bf16 v[70:73], v[192:195], v[200:203], v[70:73]
	v_mfma_f32_16x16x32_bf16 v[66:69], v[192:195], v[208:211], v[66:69]
	s_setprio 0
	s_barrier
; #define WAIT_V(n) asm volatile("s_waitcnt vmcnt(" #n ")" ::: "memory")
; #define WAIT_L(n) asm volatile("s_waitcnt lgkmcnt(" #n ")" ::: "memory")
; #define BAR __builtin_amdgcn_s_barrier()
; #define SCHED __builtin_amdgcn_sched_barrier(0)
; #define STG_A(b, h, kt) stage_half_s(lds0 + ((b) * 2 + (h)) * HT_B, ((h) ? A1 : Ap) + (kt) * BK, off0, off1)
; #define STG_B(b, h, kt) stage_half_s(lds0 + (4 + (b) * 2 + (h)) * HT_B, ((h) ? B1p : Bp) + (kt) * BK, off0, off1)
; #define STG_A(b, h, kt) stage_half_s(lds0 + ((b) * 2 + (h)) * HT_B, ((h) ? A1 : Ap) + (kt) * BK, off0, off1)
; #define STG_B(b, h, kt) stage_half_s(lds0 + (4 + (b) * 2 + (h)) * HT_B, ((h) ? B1p : Bp) + (kt) * BK, off0, off1)
; #define LDA8(b, h) _Pragma("unroll") for (int m = 0; m < 4; ++m) _Pragma("unroll") for (int k = 0; k < 2; ++k) \
;     At[m][k] = *(const bf16x8*)(SA_(shm, b, h) + abase + (m * 2 + k) * 1024)
; #define LDB8(dst, b, h) _Pragma("unroll") for (int n = 0; n < 2; ++n) _Pragma("unroll") for (int k = 0; k < 2; ++k) \
;     dst[n][k] = *(const bf16x8*)(SB_(shm, b, h) + bbase + (n * 2 + k) * 1024)
; #define MMA8(ai, bj, Bx) do { __builtin_amdgcn_s_setprio(1); \
;     _Pragma("unroll") for (int m = 0; m < 4; ++m) _Pragma("unroll") for (int n = 0; n < 2; ++n) _Pragma("unroll") for (int k = 0; k < 2; ++k) \
;       acc[ai][bj][m][n] = __builtin_amdgcn_mfma_f32_16x16x32_bf16(At[m][k], Bx[n][k], acc[ai][bj][m][n], 0, 0, 0); \
;     __builtin_amdgcn_s_setprio(0); } while (0)
; template <bool HS>
; __device__ __forceinline__ void gemm_tile8(const u16* __restrict__ Ap, const u16* __restrict__ Bp, int K,
;                                            f32x4 (&acc)[2][2][4][2], char* shm, const int tid, const float* hsr = nullptr) {
;     ...
;     LDA8(0, 1); STG_A(0, 0, t + 2);
;     BAR; WAIT_L(0); MMA8(1, 0, B0); BAR; SCHED;
;     STG_B(0, 1, t + 2);
;     WAIT_V(6); BAR; MMA8(1, 1, B1); BAR;
;     LDB8(B0, 1, 0); SCHED; LDA8(1, 0); STG_A(0, 1, t + 2);
;     WAIT_L(8); BAR; WAIT_L(0); MMA8(0, 0, B0); BAR; SCHED;
;     LDB8(B1, 1, 1); STG_B(1, 0, t + 3);
;     BAR; WAIT_L(0); MMA8(0, 1, B1); BAR;
	ds_read_b128 v[158:161], v130 offset:16384
	ds_read_b128 v[164:167], v130 offset:17408
	ds_read_b128 v[168:171], v130 offset:18432
	ds_read_b128 v[172:175], v130 offset:19456
	ds_read_b128 v[180:183], v130 offset:20480
	ds_read_b128 v[184:187], v130 offset:21504
	ds_read_b128 v[188:191], v130 offset:22528
	ds_read_b128 v[192:195], v130 offset:23552
	s_add_u32 s24, s3, s6
	s_addc_u32 s25, s10, s7
	s_add_u32 s24, s24, 0x100
	s_addc_u32 s25, s25, 0
	s_add_i32 s23, s15, 0x10000
	s_mov_b32 m0, s23
	s_nop 0
	global_load_lds_dwordx4 v132, s[24:25]
	s_add_i32 s23, s15, 0x12000
	s_mov_b32 m0, s23
	s_nop 0
	global_load_lds_dwordx4 v131, s[24:25]
	s_add_u32 s24, s8, s6
	s_addc_u32 s25, s9, s7
	s_add_u32 s24, s24, 0x100
	s_addc_u32 s25, s25, 0
	s_mov_b32 m0, s15
	s_nop 0
	global_load_lds_dwordx4 v132, s[24:25]
	s_add_i32 s23, s15, 0x2000
	s_mov_b32 m0, s23
	s_nop 0
	global_load_lds_dwordx4 v131, s[24:25]
	s_add_u32 s24, s13, s6
	s_addc_u32 s25, s14, s7
	s_add_u32 s24, s24, 0x100
	s_addc_u32 s25, s25, 0
	s_add_i32 s23, s15, 0x14000
	s_mov_b32 m0, s23
	s_nop 0
	global_load_lds_dwordx4 v132, s[24:25]
	s_add_i32 s23, s15, 0x16000
	s_mov_b32 m0, s23
	s_nop 0
	global_load_lds_dwordx4 v131, s[24:25]
	s_waitcnt vmcnt(8) lgkmcnt(0)
	s_barrier
	s_setprio 1
	v_mfma_f32_16x16x32_bf16 v[62:65], v[158:161], v[142:145], 0
	v_mfma_f32_16x16x32_bf16 v[58:61], v[158:161], v[150:153], 0
	v_mfma_f32_16x16x32_bf16 v[54:57], v[168:171], v[142:145], 0
	v_mfma_f32_16x16x32_bf16 v[50:53], v[168:171], v[150:153], 0
	v_mfma_f32_16x16x32_bf16 v[46:49], v[180:183], v[142:145], 0
	v_mfma_f32_16x16x32_bf16 v[42:45], v[180:183], v[150:153], 0
	v_mfma_f32_16x16x32_bf16 v[38:41], v[188:191], v[142:145], 0
	v_mfma_f32_16x16x32_bf16 v[34:37], v[188:191], v[150:153], 0
	v_mfma_f32_16x16x32_bf16 v[62:65], v[164:167], v[146:149], v[62:65]
	v_mfma_f32_16x16x32_bf16 v[58:61], v[164:167], v[154:157], v[58:61]
	v_mfma_f32_16x16x32_bf16 v[54:57], v[172:175], v[146:149], v[54:57]
	v_mfma_f32_16x16x32_bf16 v[50:53], v[172:175], v[154:157], v[50:53]
	v_mfma_f32_16x16x32_bf16 v[46:49], v[184:187], v[146:149], v[46:49]
	v_mfma_f32_16x16x32_bf16 v[42:45], v[184:187], v[154:157], v[42:45]
	v_mfma_f32_16x16x32_bf16 v[38:41], v[192:195], v[146:149], v[38:41]
	v_mfma_f32_16x16x32_bf16 v[34:37], v[192:195], v[154:157], v[34:37]
	v_mfma_f32_16x16x32_bf16 v[30:33], v[158:161], v[196:199], 0
	v_mfma_f32_16x16x32_bf16 v[26:29], v[158:161], v[204:207], 0
	v_mfma_f32_16x16x32_bf16 v[22:25], v[168:171], v[196:199], 0
	v_mfma_f32_16x16x32_bf16 v[18:21], v[168:171], v[204:207], 0
	v_mfma_f32_16x16x32_bf16 v[14:17], v[180:183], v[196:199], 0
	v_mfma_f32_16x16x32_bf16 v[10:13], v[180:183], v[204:207], 0
	v_mfma_f32_16x16x32_bf16 v[6:9], v[188:191], v[196:199], 0
	v_mfma_f32_16x16x32_bf16 v[2:5], v[188:191], v[204:207], 0
	v_mfma_f32_16x16x32_bf16 v[30:33], v[164:167], v[200:203], v[30:33]
	v_mfma_f32_16x16x32_bf16 v[26:29], v[164:167], v[208:211], v[26:29]
	v_mfma_f32_16x16x32_bf16 v[22:25], v[172:175], v[200:203], v[22:25]
	v_mfma_f32_16x16x32_bf16 v[18:21], v[172:175], v[208:211], v[18:21]
	v_mfma_f32_16x16x32_bf16 v[14:17], v[184:187], v[200:203], v[14:17]
	v_mfma_f32_16x16x32_bf16 v[10:13], v[184:187], v[208:211], v[10:13]
	v_mfma_f32_16x16x32_bf16 v[6:9], v[192:195], v[200:203], v[6:9]
	v_mfma_f32_16x16x32_bf16 v[2:5], v[192:195], v[208:211], v[2:5]
	s_setprio 0
	s_barrier
	v_add_u32_e32 v154, 0x18000, v133
	ds_read_b128 v[142:145], v154
	ds_read_b128 v[146:149], v154 offset:1024
	ds_read_b128 v[150:153], v154 offset:2048
	ds_read_b128 v[154:157], v154 offset:3072
	ds_read_b128 v[158:161], v130 offset:32768
	ds_read_b128 v[164:167], v130 offset:33792
	ds_read_b128 v[168:171], v130 offset:34816
	ds_read_b128 v[172:175], v130 offset:35840
	ds_read_b128 v[180:183], v130 offset:36864
	ds_read_b128 v[184:187], v130 offset:37888
	ds_read_b128 v[188:191], v130 offset:38912
	ds_read_b128 v[192:195], v130 offset:39936
	v_add_u32_e32 v208, 0x1c000, v133
	ds_read_b128 v[196:199], v208
	ds_read_b128 v[200:203], v208 offset:1024
	ds_read_b128 v[204:207], v208 offset:2048
	ds_read_b128 v[208:211], v208 offset:3072
	s_add_u32 s24, s18, s6
	s_addc_u32 s25, s19, s7
	s_add_u32 s24, s24, 0x100
	s_addc_u32 s25, s25, 0
	s_add_i32 s23, s15, 0x4000
	s_mov_b32 m0, s23
	s_nop 0
	global_load_lds_dwordx4 v132, s[24:25]
	s_add_i32 s23, s15, 0x6000
	s_mov_b32 m0, s23
	s_nop 0
	global_load_lds_dwordx4 v131, s[24:25]
	s_waitcnt vmcnt(8) lgkmcnt(0)
	s_barrier
	s_setprio 1
	v_mfma_f32_16x16x32_bf16 v[126:129], v[158:161], v[142:145], v[126:129]
	v_mfma_f32_16x16x32_bf16 v[122:125], v[158:161], v[150:153], v[122:125]
	v_mfma_f32_16x16x32_bf16 v[118:121], v[168:171], v[142:145], v[118:121]
	v_mfma_f32_16x16x32_bf16 v[114:117], v[168:171], v[150:153], v[114:117]
	v_mfma_f32_16x16x32_bf16 v[110:113], v[180:183], v[142:145], v[110:113]
	v_mfma_f32_16x16x32_bf16 v[106:109], v[180:183], v[150:153], v[106:109]
	v_mfma_f32_16x16x32_bf16 v[102:105], v[188:191], v[142:145], v[102:105]
	v_mfma_f32_16x16x32_bf16 v[98:101], v[188:191], v[150:153], v[98:101]
	v_mfma_f32_16x16x32_bf16 v[126:129], v[164:167], v[146:149], v[126:129]
	v_mfma_f32_16x16x32_bf16 v[122:125], v[164:167], v[154:157], v[122:125]
	v_mfma_f32_16x16x32_bf16 v[118:121], v[172:175], v[146:149], v[118:121]
	v_mfma_f32_16x16x32_bf16 v[114:117], v[172:175], v[154:157], v[114:117]
	v_mfma_f32_16x16x32_bf16 v[110:113], v[184:187], v[146:149], v[110:113]
	v_mfma_f32_16x16x32_bf16 v[106:109], v[184:187], v[154:157], v[106:109]
	v_mfma_f32_16x16x32_bf16 v[102:105], v[192:195], v[146:149], v[102:105]
	v_mfma_f32_16x16x32_bf16 v[98:101], v[192:195], v[154:157], v[98:101]
	v_mfma_f32_16x16x32_bf16 v[94:97], v[158:161], v[196:199], v[94:97]
	v_mfma_f32_16x16x32_bf16 v[90:93], v[158:161], v[204:207], v[90:93]
	v_mfma_f32_16x16x32_bf16 v[86:89], v[168:171], v[196:199], v[86:89]
	v_mfma_f32_16x16x32_bf16 v[82:85], v[168:171], v[204:207], v[82:85]
	v_mfma_f32_16x16x32_bf16 v[78:81], v[180:183], v[196:199], v[78:81]
	v_mfma_f32_16x16x32_bf16 v[74:77], v[180:183], v[204:207], v[74:77]
	v_mfma_f32_16x16x32_bf16 v[70:73], v[188:191], v[196:199], v[70:73]
	v_mfma_f32_16x16x32_bf16 v[66:69], v[188:191], v[204:207], v[66:69]
	v_mfma_f32_16x16x32_bf16 v[94:97], v[164:167], v[200:203], v[94:97]
	v_mfma_f32_16x16x32_bf16 v[90:93], v[164:167], v[208:211], v[90:93]
	v_mfma_f32_16x16x32_bf16 v[86:89], v[172:175], v[200:203], v[86:89]
	v_mfma_f32_16x16x32_bf16 v[82:85], v[172:175], v[208:211], v[82:85]
	v_mfma_f32_16x16x32_bf16 v[78:81], v[184:187], v[200:203], v[78:81]
	v_mfma_f32_16x16x32_bf16 v[74:77], v[184:187], v[208:211], v[74:77]
	v_mfma_f32_16x16x32_bf16 v[70:73], v[192:195], v[200:203], v[70:73]
	v_mfma_f32_16x16x32_bf16 v[66:69], v[192:195], v[208:211], v[66:69]
	s_setprio 0
	s_barrier
; #define WAIT_V(n) asm volatile("s_waitcnt vmcnt(" #n ")" ::: "memory")
; #define WAIT_L(n) asm volatile("s_waitcnt lgkmcnt(" #n ")" ::: "memory")
; #define BAR __builtin_amdgcn_s_barrier()
; #define SCHED __builtin_amdgcn_sched_barrier(0)
; #define STG_A(b, h, kt) stage_half_s(lds0 + ((b) * 2 + (h)) * HT_B, ((h) ? A1 : Ap) + (kt) * BK, off0, off1)
; #define STG_B(b, h, kt) stage_half_s(lds0 + (4 + (b) * 2 + (h)) * HT_B, ((h) ? B1p : Bp) + (kt) * BK, off0, off1)
; #define STG_A(b, h, kt) stage_half_s(lds0 + ((b) * 2 + (h)) * HT_B, ((h) ? A1 : Ap) + (kt) * BK, off0, off1)
; #define STG_B(b, h, kt) stage_half_s(lds0 + (4 + (b) * 2 + (h)) * HT_B, ((h) ? B1p : Bp) + (kt) * BK, off0, off1)
; #define LDA8(b, h) _Pragma("unroll") for (int m = 0; m < 4; ++m) _Pragma("unroll") for (int k = 0; k < 2; ++k) \
;     At[m][k] = *(const bf16x8*)(SA_(shm, b, h) + abase + (m * 2 + k) * 1024)
; #define LDB8(dst, b, h) _Pragma("unroll") for (int n = 0; n < 2; ++n) _Pragma("unroll") for (int k = 0; k < 2; ++k) \
;     dst[n][k] = *(const bf16x8*)(SB_(shm, b, h) + bbase + (n * 2 + k) * 1024)
; #define MMA8(ai, bj, Bx) do { __builtin_amdgcn_s_setprio(1); \
;     _Pragma("unroll") for (int m = 0; m < 4; ++m) _Pragma("unroll") for (int n = 0; n < 2; ++n) _Pragma("unroll") for (int k = 0; k < 2; ++k) \
;       acc[ai][bj][m][n] = __builtin_amdgcn_mfma_f32_16x16x32_bf16(At[m][k], Bx[n][k], acc[ai][bj][m][n], 0, 0, 0); \
;     __builtin_amdgcn_s_setprio(0); } while (0)
; template <bool HS>
; __device__ __forceinline__ void gemm_tile8(const u16* __restrict__ Ap, const u16* __restrict__ Bp, int K,
;                                            f32x4 (&acc)[2][2][4][2], char* shm, const int tid, const float* hsr = nullptr) {
;     ...
;     LDB8(B0, 0, 0); SCHED; LDA8(0, 0); STG_A(1, 1, t + 1);
;     WAIT_L(8); BAR; WAIT_L(0); MMA8(0, 0, B0); BAR; SCHED;
;     ...
;     LDA8(1, 1); STG_A(1, 0, t + 3);
;     BAR; WAIT_L(0); MMA8(1, 0, B0); BAR; SCHED;
;     STG_B(1, 1, t + 3);
;     WAIT_V(6); BAR; MMA8(1, 1, B1); BAR;
;   }
	ds_read_b128 v[158:161], v130 offset:49152
	ds_read_b128 v[164:167], v130 offset:50176
	ds_read_b128 v[168:171], v130 offset:51200
	ds_read_b128 v[172:175], v130 offset:52224
	ds_read_b128 v[180:183], v130 offset:53248
	ds_read_b128 v[184:187], v130 offset:54272
	ds_read_b128 v[188:191], v130 offset:55296
	ds_read_b128 v[192:195], v130 offset:56320
	s_add_u32 s24, s3, s6
	s_addc_u32 s25, s10, s7
	s_add_u32 s24, s24, 0x180
	s_addc_u32 s25, s25, 0
	s_add_i32 s23, s15, 0x18000
	s_mov_b32 m0, s23
	s_nop 0
	global_load_lds_dwordx4 v132, s[24:25]
	s_add_i32 s23, s15, 0x1a000
	s_mov_b32 m0, s23
	s_nop 0
	global_load_lds_dwordx4 v131, s[24:25]
	s_add_u32 s24, s8, s6
	s_addc_u32 s25, s9, s7
	s_add_u32 s24, s24, 0x180
	s_addc_u32 s25, s25, 0
	s_add_i32 s23, s15, 0x8000
	s_mov_b32 m0, s23
	s_nop 0
	global_load_lds_dwordx4 v132, s[24:25]
	s_add_i32 s23, s15, 0xa000
	s_mov_b32 m0, s23
	s_nop 0
	global_load_lds_dwordx4 v131, s[24:25]
	s_add_u32 s24, s13, s6
	s_addc_u32 s25, s14, s7
	s_add_u32 s24, s24, 0x180
	s_addc_u32 s25, s25, 0
	s_add_i32 s23, s15, 0x1c000
	s_mov_b32 m0, s23
	s_nop 0
	global_load_lds_dwordx4 v132, s[24:25]
	s_add_i32 s23, s15, 0x1e000
	s_mov_b32 m0, s23
	s_nop 0
	global_load_lds_dwordx4 v131, s[24:25]
	s_waitcnt vmcnt(8) lgkmcnt(0)
	s_barrier
	s_setprio 1
	v_mfma_f32_16x16x32_bf16 v[62:65], v[158:161], v[142:145], v[62:65]
	v_mfma_f32_16x16x32_bf16 v[58:61], v[158:161], v[150:153], v[58:61]
	v_mfma_f32_16x16x32_bf16 v[54:57], v[168:171], v[142:145], v[54:57]
	v_mfma_f32_16x16x32_bf16 v[50:53], v[168:171], v[150:153], v[50:53]
	v_mfma_f32_16x16x32_bf16 v[46:49], v[180:183], v[142:145], v[46:49]
	v_mfma_f32_16x16x32_bf16 v[42:45], v[180:183], v[150:153], v[42:45]
	v_mfma_f32_16x16x32_bf16 v[38:41], v[188:191], v[142:145], v[38:41]
	v_mfma_f32_16x16x32_bf16 v[34:37], v[188:191], v[150:153], v[34:37]
	v_mfma_f32_16x16x32_bf16 v[62:65], v[164:167], v[146:149], v[62:65]
	v_mfma_f32_16x16x32_bf16 v[58:61], v[164:167], v[154:157], v[58:61]
	v_mfma_f32_16x16x32_bf16 v[54:57], v[172:175], v[146:149], v[54:57]
	v_mfma_f32_16x16x32_bf16 v[50:53], v[172:175], v[154:157], v[50:53]
	v_mfma_f32_16x16x32_bf16 v[46:49], v[184:187], v[146:149], v[46:49]
	v_mfma_f32_16x16x32_bf16 v[42:45], v[184:187], v[154:157], v[42:45]
	v_mfma_f32_16x16x32_bf16 v[38:41], v[192:195], v[146:149], v[38:41]
	v_mfma_f32_16x16x32_bf16 v[34:37], v[192:195], v[154:157], v[34:37]
	v_mfma_f32_16x16x32_bf16 v[30:33], v[158:161], v[196:199], v[30:33]
	v_mfma_f32_16x16x32_bf16 v[26:29], v[158:161], v[204:207], v[26:29]
	v_mfma_f32_16x16x32_bf16 v[22:25], v[168:171], v[196:199], v[22:25]
	v_mfma_f32_16x16x32_bf16 v[18:21], v[168:171], v[204:207], v[18:21]
	v_mfma_f32_16x16x32_bf16 v[14:17], v[180:183], v[196:199], v[14:17]
	v_mfma_f32_16x16x32_bf16 v[10:13], v[180:183], v[204:207], v[10:13]
	v_mfma_f32_16x16x32_bf16 v[6:9], v[188:191], v[196:199], v[6:9]
	v_mfma_f32_16x16x32_bf16 v[2:5], v[188:191], v[204:207], v[2:5]
	v_mfma_f32_16x16x32_bf16 v[30:33], v[164:167], v[200:203], v[30:33]
	v_mfma_f32_16x16x32_bf16 v[26:29], v[164:167], v[208:211], v[26:29]
	v_mfma_f32_16x16x32_bf16 v[22:25], v[172:175], v[200:203], v[22:25]
	v_mfma_f32_16x16x32_bf16 v[18:21], v[172:175], v[208:211], v[18:21]
	v_mfma_f32_16x16x32_bf16 v[14:17], v[184:187], v[200:203], v[14:17]
	v_mfma_f32_16x16x32_bf16 v[10:13], v[184:187], v[208:211], v[10:13]
	v_mfma_f32_16x16x32_bf16 v[6:9], v[192:195], v[200:203], v[6:9]
	v_mfma_f32_16x16x32_bf16 v[2:5], v[192:195], v[208:211], v[2:5]
	s_setprio 0
	s_barrier
	s_add_i32 s20, s20, 2
	s_add_u32 s6, s6, 0x100
	s_addc_u32 s7, s7, 0
	s_cmp_lt_u32 s20, 12
	s_cbranch_scc0 .Lk_ret_in_exit
.Lk_ret_in:
	v_add_u32_e32 v154, 0x10000, v133
	ds_read_b128 v[142:145], v154
	ds_read_b128 v[146:149], v154 offset:1024
	ds_read_b128 v[150:153], v154 offset:2048
	ds_read_b128 v[154:157], v154 offset:3072
	ds_read_b128 v[158:161], v130
	ds_read_b128 v[164:167], v130 offset:1024
	ds_read_b128 v[168:171], v130 offset:2048
	ds_read_b128 v[172:175], v130 offset:3072
	ds_read_b128 v[180:183], v130 offset:4096
	ds_read_b128 v[184:187], v130 offset:5120
	ds_read_b128 v[188:191], v130 offset:6144
	ds_read_b128 v[192:195], v130 offset:7168
	v_add_u32_e32 v208, 0x14000, v133
	ds_read_b128 v[196:199], v208
	ds_read_b128 v[200:203], v208 offset:1024
	ds_read_b128 v[204:207], v208 offset:2048
	ds_read_b128 v[208:211], v208 offset:3072
	s_add_u32 s24, s18, s6
	s_addc_u32 s25, s19, s7
	s_add_u32 s24, s24, 0x80
	s_addc_u32 s25, s25, 0
	s_add_i32 s23, s15, 0xc000
	s_mov_b32 m0, s23
	s_nop 0
	global_load_lds_dwordx4 v132, s[24:25]
	s_add_i32 s23, s15, 0xe000
	s_mov_b32 m0, s23
	s_nop 0
	global_load_lds_dwordx4 v131, s[24:25]
	s_waitcnt vmcnt(8) lgkmcnt(0)
	s_barrier
; #define WAIT_V(n) asm volatile("s_waitcnt vmcnt(" #n ")" ::: "memory")
; #define WAIT_L(n) asm volatile("s_waitcnt lgkmcnt(" #n ")" ::: "memory")
; #define BAR __builtin_amdgcn_s_barrier()
; #define SCHED __builtin_amdgcn_sched_barrier(0)
; #define STG_A(b, h, kt) stage_half_s(lds0 + ((b) * 2 + (h)) * HT_B, ((h) ? A1 : Ap) + (kt) * BK, off0, off1)
; #define STG_B(b, h, kt) stage_half_s(lds0 + (4 + (b) * 2 + (h)) * HT_B, ((h) ? B1p : Bp) + (kt) * BK, off0, off1)
; #define STG_A(b, h, kt) stage_half_s(lds0 + ((b) * 2 + (h)) * HT_B, ((h) ? A1 : Ap) + (kt) * BK, off0, off1)
; #define STG_B(b, h, kt) stage_half_s(lds0 + (4 + (b) * 2 + (h)) * HT_B, ((h) ? B1p : Bp) + (kt) * BK, off0, off1)
; #define LDA8(b, h) _Pragma("unroll") for (int m = 0; m < 4; ++m) _Pragma("unroll") for (int k = 0; k < 2; ++k) \
;     At[m][k] = *(const bf16x8*)(SA_(shm, b, h) + abase + (m * 2 + k) * 1024)
; #define LDB8(dst, b, h) _Pragma("unroll") for (int n = 0; n < 2; ++n) _Pragma("unroll") for (int k = 0; k < 2; ++k) \
;     dst[n][k] = *(const bf16x8*)(SB_(shm, b, h) + bbase + (n * 2 + k) * 1024)
; #define MMA8(ai, bj, Bx) do { __builtin_amdgcn_s_setprio(1); \
;     _Pragma("unroll") for (int m = 0; m < 4; ++m) _Pragma("unroll") for (int n = 0; n < 2; ++n) _Pragma("unroll") for (int k = 0; k < 2; ++k) \
;       acc[ai][bj][m][n] = __builtin_amdgcn_mfma_f32_16x16x32_bf16(At[m][k], Bx[n][k], acc[ai][bj][m][n], 0, 0, 0); \
;     __builtin_amdgcn_s_setprio(0); } while (0)
; template <bool HS>
; __device__ __forceinline__ void gemm_tile8(const u16* __restrict__ Ap, const u16* __restrict__ Bp, int K,
;                                            f32x4 (&acc)[2][2][4][2], char* shm, const int tid, const float* hsr = nullptr) {
;     ...
;     LDB8(B0, 0, 0); SCHED; LDA8(0, 0); STG_A(1, 1, t + 1);
;     WAIT_L(8); BAR; WAIT_L(0); MMA8(0, 0, B0); BAR; SCHED;
;     LDB8(B1, 0, 1); STG_B(0, 0, t + 2);
;     BAR; WAIT_L(0); MMA8(0, 1, B1); BAR;
;     LDA8(0, 1); STG_A(0, 0, t + 2);
;     BAR; WAIT_L(0); MMA8(1, 0, B0); BAR; SCHED;
;     STG_B(0, 1, t + 2);
;     WAIT_V(6); BAR; MMA8(1, 1, B1); BAR;
	s_setprio 1
	v_mfma_f32_16x16x32_bf16 v[126:129], v[158:161], v[142:145], v[126:129]
	v_mfma_f32_16x16x32_bf16 v[122:125], v[158:161], v[150:153], v[122:125]
	v_mfma_f32_16x16x32_bf16 v[118:121], v[168:171], v[142:145], v[118:121]
	v_mfma_f32_16x16x32_bf16 v[114:117], v[168:171], v[150:153], v[114:117]
	v_mfma_f32_16x16x32_bf16 v[110:113], v[180:183], v[142:145], v[110:113]
	v_mfma_f32_16x16x32_bf16 v[106:109], v[180:183], v[150:153], v[106:109]
	v_mfma_f32_16x16x32_bf16 v[102:105], v[188:191], v[142:145], v[102:105]
	v_mfma_f32_16x16x32_bf16 v[98:101], v[188:191], v[150:153], v[98:101]
	v_mfma_f32_16x16x32_bf16 v[126:129], v[164:167], v[146:149], v[126:129]
	v_mfma_f32_16x16x32_bf16 v[122:125], v[164:167], v[154:157], v[122:125]
	v_mfma_f32_16x16x32_bf16 v[118:121], v[172:175], v[146:149], v[118:121]
	v_mfma_f32_16x16x32_bf16 v[114:117], v[172:175], v[154:157], v[114:117]
	v_mfma_f32_16x16x32_bf16 v[110:113], v[184:187], v[146:149], v[110:113]
	v_mfma_f32_16x16x32_bf16 v[106:109], v[184:187], v[154:157], v[106:109]
	v_mfma_f32_16x16x32_bf16 v[102:105], v[192:195], v[146:149], v[102:105]
	v_mfma_f32_16x16x32_bf16 v[98:101], v[192:195], v[154:157], v[98:101]
	v_mfma_f32_16x16x32_bf16 v[94:97], v[158:161], v[196:199], v[94:97]
	v_mfma_f32_16x16x32_bf16 v[90:93], v[158:161], v[204:207], v[90:93]
	v_mfma_f32_16x16x32_bf16 v[86:89], v[168:171], v[196:199], v[86:89]
	v_mfma_f32_16x16x32_bf16 v[82:85], v[168:171], v[204:207], v[82:85]
	v_mfma_f32_16x16x32_bf16 v[78:81], v[180:183], v[196:199], v[78:81]
	v_mfma_f32_16x16x32_bf16 v[74:77], v[180:183], v[204:207], v[74:77]
	v_mfma_f32_16x16x32_bf16 v[70:73], v[188:191], v[196:199], v[70:73]
	v_mfma_f32_16x16x32_bf16 v[66:69], v[188:191], v[204:207], v[66:69]
	v_mfma_f32_16x16x32_bf16 v[94:97], v[164:167], v[200:203], v[94:97]
	v_mfma_f32_16x16x32_bf16 v[90:93], v[164:167], v[208:211], v[90:93]
	v_mfma_f32_16x16x32_bf16 v[86:89], v[172:175], v[200:203], v[86:89]
	v_mfma_f32_16x16x32_bf16 v[82:85], v[172:175], v[208:211], v[82:85]
	v_mfma_f32_16x16x32_bf16 v[78:81], v[184:187], v[200:203], v[78:81]
	v_mfma_f32_16x16x32_bf16 v[74:77], v[184:187], v[208:211], v[74:77]
	v_mfma_f32_16x16x32_bf16 v[70:73], v[192:195], v[200:203], v[70:73]
	v_mfma_f32_16x16x32_bf16 v[66:69], v[192:195], v[208:211], v[66:69]
	s_setprio 0
	s_barrier
	ds_read_b128 v[158:161], v130 offset:16384
	ds_read_b128 v[164:167], v130 offset:17408
	ds_read_b128 v[168:171], v130 offset:18432
	ds_read_b128 v[172:175], v130 offset:19456
	ds_read_b128 v[180:183], v130 offset:20480
	ds_read_b128 v[184:187], v130 offset:21504
	ds_read_b128 v[188:191], v130 offset:22528
	ds_read_b128 v[192:195], v130 offset:23552
	s_add_u32 s24, s3, s6
	s_addc_u32 s25, s10, s7
	s_add_u32 s24, s24, 0x100
	s_addc_u32 s25, s25, 0
	s_add_i32 s23, s15, 0x10000
	s_mov_b32 m0, s23
	s_nop 0
	global_load_lds_dwordx4 v132, s[24:25]
	s_add_i32 s23, s15, 0x12000
	s_mov_b32 m0, s23
	s_nop 0
	global_load_lds_dwordx4 v131, s[24:25]
	s_add_u32 s24, s8, s6
	s_addc_u32 s25, s9, s7
	s_add_u32 s24, s24, 0x100
	s_addc_u32 s25, s25, 0
	s_mov_b32 m0, s15
	s_nop 0
	global_load_lds_dwordx4 v132, s[24:25]
	s_add_i32 s23, s15, 0x2000
	s_mov_b32 m0, s23
	s_nop 0
	global_load_lds_dwordx4 v131, s[24:25]
	s_add_u32 s24, s13, s6
	s_addc_u32 s25, s14, s7
	s_add_u32 s24, s24, 0x100
	s_addc_u32 s25, s25, 0
	s_add_i32 s23, s15, 0x14000
	s_mov_b32 m0, s23
	s_nop 0
	global_load_lds_dwordx4 v132, s[24:25]
	s_add_i32 s23, s15, 0x16000
	s_mov_b32 m0, s23
	s_nop 0
	global_load_lds_dwordx4 v131, s[24:25]
	s_waitcnt vmcnt(8) lgkmcnt(0)
	s_barrier
	s_setprio 1
	v_mfma_f32_16x16x32_bf16 v[62:65], v[158:161], v[142:145], v[62:65]
	v_mfma_f32_16x16x32_bf16 v[58:61], v[158:161], v[150:153], v[58:61]
	v_mfma_f32_16x16x32_bf16 v[54:57], v[168:171], v[142:145], v[54:57]
	v_mfma_f32_16x16x32_bf16 v[50:53], v[168:171], v[150:153], v[50:53]
	v_mfma_f32_16x16x32_bf16 v[46:49], v[180:183], v[142:145], v[46:49]
	v_mfma_f32_16x16x32_bf16 v[42:45], v[180:183], v[150:153], v[42:45]
	v_mfma_f32_16x16x32_bf16 v[38:41], v[188:191], v[142:145], v[38:41]
	v_mfma_f32_16x16x32_bf16 v[34:37], v[188:191], v[150:153], v[34:37]
	v_mfma_f32_16x16x32_bf16 v[62:65], v[164:167], v[146:149], v[62:65]
	v_mfma_f32_16x16x32_bf16 v[58:61], v[164:167], v[154:157], v[58:61]
	v_mfma_f32_16x16x32_bf16 v[54:57], v[172:175], v[146:149], v[54:57]
	v_mfma_f32_16x16x32_bf16 v[50:53], v[172:175], v[154:157], v[50:53]
	v_mfma_f32_16x16x32_bf16 v[46:49], v[184:187], v[146:149], v[46:49]
	v_mfma_f32_16x16x32_bf16 v[42:45], v[184:187], v[154:157], v[42:45]
	v_mfma_f32_16x16x32_bf16 v[38:41], v[192:195], v[146:149], v[38:41]
	v_mfma_f32_16x16x32_bf16 v[34:37], v[192:195], v[154:157], v[34:37]
	v_mfma_f32_16x16x32_bf16 v[30:33], v[158:161], v[196:199], v[30:33]
	v_mfma_f32_16x16x32_bf16 v[26:29], v[158:161], v[204:207], v[26:29]
	v_mfma_f32_16x16x32_bf16 v[22:25], v[168:171], v[196:199], v[22:25]
	v_mfma_f32_16x16x32_bf16 v[18:21], v[168:171], v[204:207], v[18:21]
	v_mfma_f32_16x16x32_bf16 v[14:17], v[180:183], v[196:199], v[14:17]
	v_mfma_f32_16x16x32_bf16 v[10:13], v[180:183], v[204:207], v[10:13]
	v_mfma_f32_16x16x32_bf16 v[6:9], v[188:191], v[196:199], v[6:9]
	v_mfma_f32_16x16x32_bf16 v[2:5], v[188:191], v[204:207], v[2:5]
	v_mfma_f32_16x16x32_bf16 v[30:33], v[164:167], v[200:203], v[30:33]
	v_mfma_f32_16x16x32_bf16 v[26:29], v[164:167], v[208:211], v[26:29]
	v_mfma_f32_16x16x32_bf16 v[22:25], v[172:175], v[200:203], v[22:25]
	v_mfma_f32_16x16x32_bf16 v[18:21], v[172:175], v[208:211], v[18:21]
	v_mfma_f32_16x16x32_bf16 v[14:17], v[184:187], v[200:203], v[14:17]
	v_mfma_f32_16x16x32_bf16 v[10:13], v[184:187], v[208:211], v[10:13]
	v_mfma_f32_16x16x32_bf16 v[6:9], v[192:195], v[200:203], v[6:9]
	v_mfma_f32_16x16x32_bf16 v[2:5], v[192:195], v[208:211], v[2:5]
	s_setprio 0
	s_barrier
; #define WAIT_V(n) asm volatile("s_waitcnt vmcnt(" #n ")" ::: "memory")
; #define WAIT_L(n) asm volatile("s_waitcnt lgkmcnt(" #n ")" ::: "memory")
; #define BAR __builtin_amdgcn_s_barrier()
; #define SCHED __builtin_amdgcn_sched_barrier(0)
; #define STG_A(b, h, kt) stage_half_s(lds0 + ((b) * 2 + (h)) * HT_B, ((h) ? A1 : Ap) + (kt) * BK, off0, off1)
; #define STG_B(b, h, kt) stage_half_s(lds0 + (4 + (b) * 2 + (h)) * HT_B, ((h) ? B1p : Bp) + (kt) * BK, off0, off1)
; #define STG_A(b, h, kt) stage_half_s(lds0 + ((b) * 2 + (h)) * HT_B, ((h) ? A1 : Ap) + (kt) * BK, off0, off1)
; #define STG_B(b, h, kt) stage_half_s(lds0 + (4 + (b) * 2 + (h)) * HT_B, ((h) ? B1p : Bp) + (kt) * BK, off0, off1)
; #define LDA8(b, h) _Pragma("unroll") for (int m = 0; m < 4; ++m) _Pragma("unroll") for (int k = 0; k < 2; ++k) \
;     At[m][k] = *(const bf16x8*)(SA_(shm, b, h) + abase + (m * 2 + k) * 1024)
; #define LDB8(dst, b, h) _Pragma("unroll") for (int n = 0; n < 2; ++n) _Pragma("unroll") for (int k = 0; k < 2; ++k) \
;     dst[n][k] = *(const bf16x8*)(SB_(shm, b, h) + bbase + (n * 2 + k) * 1024)
; #define MMA8(ai, bj, Bx) do { __builtin_amdgcn_s_setprio(1); \
;     _Pragma("unroll") for (int m = 0; m < 4; ++m) _Pragma("unroll") for (int n = 0; n < 2; ++n) _Pragma("unroll") for (int k = 0; k < 2; ++k) \
;       acc[ai][bj][m][n] = __builtin_amdgcn_mfma_f32_16x16x32_bf16(At[m][k], Bx[n][k], acc[ai][bj][m][n], 0, 0, 0); \
;     __builtin_amdgcn_s_setprio(0); } while (0)
; template <bool HS>
; __device__ __forceinline__ void gemm_tile8(const u16* __restrict__ Ap, const u16* __restrict__ Bp, int K,
;                                            f32x4 (&acc)[2][2][4][2], char* shm, const int tid, const float* hsr = nullptr) {
;     ...
;     LDB8(B0, 1, 0); SCHED; LDA8(1, 0); STG_A(0, 1, t + 2);
;     WAIT_L(8); BAR; WAIT_L(0); MMA8(0, 0, B0); BAR; SCHED;
;     LDB8(B1, 1, 1); STG_B(1, 0, t + 3);
;     BAR; WAIT_L(0); MMA8(0, 1, B1); BAR;
;     LDA8(1, 1); STG_A(1, 0, t + 3);
;     BAR; WAIT_L(0); MMA8(1, 0, B0); BAR; SCHED;
;     STG_B(1, 1, t + 3);
;     WAIT_V(6); BAR; MMA8(1, 1, B1); BAR;
;   }
	v_add_u32_e32 v154, 0x18000, v133
	ds_read_b128 v[142:145], v154
	ds_read_b128 v[146:149], v154 offset:1024
	ds_read_b128 v[150:153], v154 offset:2048
	ds_read_b128 v[154:157], v154 offset:3072
	ds_read_b128 v[158:161], v130 offset:32768
	ds_read_b128 v[164:167], v130 offset:33792
	ds_read_b128 v[168:171], v130 offset:34816
	ds_read_b128 v[172:175], v130 offset:35840
	ds_read_b128 v[180:183], v130 offset:36864
	ds_read_b128 v[184:187], v130 offset:37888
	ds_read_b128 v[188:191], v130 offset:38912
	ds_read_b128 v[192:195], v130 offset:39936
	v_add_u32_e32 v208, 0x1c000, v133
	ds_read_b128 v[196:199], v208
	ds_read_b128 v[200:203], v208 offset:1024
	ds_read_b128 v[204:207], v208 offset:2048
	ds_read_b128 v[208:211], v208 offset:3072
	s_add_u32 s24, s18, s6
	s_addc_u32 s25, s19, s7
	s_add_u32 s24, s24, 0x100
	s_addc_u32 s25, s25, 0
	s_add_i32 s23, s15, 0x4000
	s_mov_b32 m0, s23
	s_nop 0
	global_load_lds_dwordx4 v132, s[24:25]
	s_add_i32 s23, s15, 0x6000
	s_mov_b32 m0, s23
	s_nop 0
	global_load_lds_dwordx4 v131, s[24:25]
	s_waitcnt vmcnt(8) lgkmcnt(0)
	s_barrier
	s_setprio 1
	v_mfma_f32_16x16x32_bf16 v[126:129], v[158:161], v[142:145], v[126:129]
	v_mfma_f32_16x16x32_bf16 v[122:125], v[158:161], v[150:153], v[122:125]
	v_mfma_f32_16x16x32_bf16 v[118:121], v[168:171], v[142:145], v[118:121]
	v_mfma_f32_16x16x32_bf16 v[114:117], v[168:171], v[150:153], v[114:117]
	v_mfma_f32_16x16x32_bf16 v[110:113], v[180:183], v[142:145], v[110:113]
	v_mfma_f32_16x16x32_bf16 v[106:109], v[180:183], v[150:153], v[106:109]
	v_mfma_f32_16x16x32_bf16 v[102:105], v[188:191], v[142:145], v[102:105]
	v_mfma_f32_16x16x32_bf16 v[98:101], v[188:191], v[150:153], v[98:101]
	v_mfma_f32_16x16x32_bf16 v[126:129], v[164:167], v[146:149], v[126:129]
	v_mfma_f32_16x16x32_bf16 v[122:125], v[164:167], v[154:157], v[122:125]
	v_mfma_f32_16x16x32_bf16 v[118:121], v[172:175], v[146:149], v[118:121]
	v_mfma_f32_16x16x32_bf16 v[114:117], v[172:175], v[154:157], v[114:117]
	v_mfma_f32_16x16x32_bf16 v[110:113], v[184:187], v[146:149], v[110:113]
	v_mfma_f32_16x16x32_bf16 v[106:109], v[184:187], v[154:157], v[106:109]
	v_mfma_f32_16x16x32_bf16 v[102:105], v[192:195], v[146:149], v[102:105]
	v_mfma_f32_16x16x32_bf16 v[98:101], v[192:195], v[154:157], v[98:101]
	v_mfma_f32_16x16x32_bf16 v[94:97], v[158:161], v[196:199], v[94:97]
	v_mfma_f32_16x16x32_bf16 v[90:93], v[158:161], v[204:207], v[90:93]
	v_mfma_f32_16x16x32_bf16 v[86:89], v[168:171], v[196:199], v[86:89]
	v_mfma_f32_16x16x32_bf16 v[82:85], v[168:171], v[204:207], v[82:85]
	v_mfma_f32_16x16x32_bf16 v[78:81], v[180:183], v[196:199], v[78:81]
	v_mfma_f32_16x16x32_bf16 v[74:77], v[180:183], v[204:207], v[74:77]
	v_mfma_f32_16x16x32_bf16 v[70:73], v[188:191], v[196:199], v[70:73]
	v_mfma_f32_16x16x32_bf16 v[66:69], v[188:191], v[204:207], v[66:69]
	v_mfma_f32_16x16x32_bf16 v[94:97], v[164:167], v[200:203], v[94:97]
	v_mfma_f32_16x16x32_bf16 v[90:93], v[164:167], v[208:211], v[90:93]
	v_mfma_f32_16x16x32_bf16 v[86:89], v[172:175], v[200:203], v[86:89]
	v_mfma_f32_16x16x32_bf16 v[82:85], v[172:175], v[208:211], v[82:85]
	v_mfma_f32_16x16x32_bf16 v[78:81], v[184:187], v[200:203], v[78:81]
	v_mfma_f32_16x16x32_bf16 v[74:77], v[184:187], v[208:211], v[74:77]
	v_mfma_f32_16x16x32_bf16 v[70:73], v[192:195], v[200:203], v[70:73]
	v_mfma_f32_16x16x32_bf16 v[66:69], v[192:195], v[208:211], v[66:69]
	s_setprio 0
	s_barrier
	ds_read_b128 v[158:161], v130 offset:49152
	ds_read_b128 v[164:167], v130 offset:50176
	ds_read_b128 v[168:171], v130 offset:51200
	ds_read_b128 v[172:175], v130 offset:52224
	ds_read_b128 v[180:183], v130 offset:53248
	ds_read_b128 v[184:187], v130 offset:54272
	ds_read_b128 v[188:191], v130 offset:55296
	ds_read_b128 v[192:195], v130 offset:56320
	s_add_u32 s24, s3, s6
	s_addc_u32 s25, s10, s7
	s_add_u32 s24, s24, 0x180
	s_addc_u32 s25, s25, 0
	s_add_i32 s23, s15, 0x18000
	s_mov_b32 m0, s23
	s_nop 0
	global_load_lds_dwordx4 v132, s[24:25]
	s_add_i32 s23, s15, 0x1a000
	s_mov_b32 m0, s23
	s_nop 0
	global_load_lds_dwordx4 v131, s[24:25]
	s_add_u32 s24, s8, s6
	s_addc_u32 s25, s9, s7
	s_add_u32 s24, s24, 0x180
	s_addc_u32 s25, s25, 0
	s_add_i32 s23, s15, 0x8000
	s_mov_b32 m0, s23
	s_nop 0
	global_load_lds_dwordx4 v132, s[24:25]
	s_add_i32 s23, s15, 0xa000
	s_mov_b32 m0, s23
	s_nop 0
	global_load_lds_dwordx4 v131, s[24:25]
	s_add_u32 s24, s13, s6
	s_addc_u32 s25, s14, s7
	s_add_u32 s24, s24, 0x180
	s_addc_u32 s25, s25, 0
	s_add_i32 s23, s15, 0x1c000
	s_mov_b32 m0, s23
	s_nop 0
	global_load_lds_dwordx4 v132, s[24:25]
	s_add_i32 s23, s15, 0x1e000
	s_mov_b32 m0, s23
	s_nop 0
	global_load_lds_dwordx4 v131, s[24:25]
	s_waitcnt vmcnt(8) lgkmcnt(0)
	s_barrier
	s_setprio 1
	v_mfma_f32_16x16x32_bf16 v[62:65], v[158:161], v[142:145], v[62:65]
	v_mfma_f32_16x16x32_bf16 v[58:61], v[158:161], v[150:153], v[58:61]
	v_mfma_f32_16x16x32_bf16 v[54:57], v[168:171], v[142:145], v[54:57]
	v_mfma_f32_16x16x32_bf16 v[50:53], v[168:171], v[150:153], v[50:53]
	v_mfma_f32_16x16x32_bf16 v[46:49], v[180:183], v[142:145], v[46:49]
	v_mfma_f32_16x16x32_bf16 v[42:45], v[180:183], v[150:153], v[42:45]
	v_mfma_f32_16x16x32_bf16 v[38:41], v[188:191], v[142:145], v[38:41]
	v_mfma_f32_16x16x32_bf16 v[34:37], v[188:191], v[150:153], v[34:37]
	v_mfma_f32_16x16x32_bf16 v[62:65], v[164:167], v[146:149], v[62:65]
	v_mfma_f32_16x16x32_bf16 v[58:61], v[164:167], v[154:157], v[58:61]
	v_mfma_f32_16x16x32_bf16 v[54:57], v[172:175], v[146:149], v[54:57]
	v_mfma_f32_16x16x32_bf16 v[50:53], v[172:175], v[154:157], v[50:53]
	v_mfma_f32_16x16x32_bf16 v[46:49], v[184:187], v[146:149], v[46:49]
	v_mfma_f32_16x16x32_bf16 v[42:45], v[184:187], v[154:157], v[42:45]
	v_mfma_f32_16x16x32_bf16 v[38:41], v[192:195], v[146:149], v[38:41]
	v_mfma_f32_16x16x32_bf16 v[34:37], v[192:195], v[154:157], v[34:37]
	v_mfma_f32_16x16x32_bf16 v[30:33], v[158:161], v[196:199], v[30:33]
	v_mfma_f32_16x16x32_bf16 v[26:29], v[158:161], v[204:207], v[26:29]
	v_mfma_f32_16x16x32_bf16 v[22:25], v[168:171], v[196:199], v[22:25]
	v_mfma_f32_16x16x32_bf16 v[18:21], v[168:171], v[204:207], v[18:21]
	v_mfma_f32_16x16x32_bf16 v[14:17], v[180:183], v[196:199], v[14:17]
	v_mfma_f32_16x16x32_bf16 v[10:13], v[180:183], v[204:207], v[10:13]
	v_mfma_f32_16x16x32_bf16 v[6:9], v[188:191], v[196:199], v[6:9]
	v_mfma_f32_16x16x32_bf16 v[2:5], v[188:191], v[204:207], v[2:5]
	v_mfma_f32_16x16x32_bf16 v[30:33], v[164:167], v[200:203], v[30:33]
	v_mfma_f32_16x16x32_bf16 v[26:29], v[164:167], v[208:211], v[26:29]
	v_mfma_f32_16x16x32_bf16 v[22:25], v[172:175], v[200:203], v[22:25]
	v_mfma_f32_16x16x32_bf16 v[18:21], v[172:175], v[208:211], v[18:21]
	v_mfma_f32_16x16x32_bf16 v[14:17], v[184:187], v[200:203], v[14:17]
	v_mfma_f32_16x16x32_bf16 v[10:13], v[184:187], v[208:211], v[10:13]
	v_mfma_f32_16x16x32_bf16 v[6:9], v[192:195], v[200:203], v[6:9]
	v_mfma_f32_16x16x32_bf16 v[2:5], v[192:195], v[208:211], v[2:5]
	s_setprio 0
	s_barrier
	s_add_i32 s20, s20, 2
	s_add_u32 s6, s6, 0x100
	s_addc_u32 s7, s7, 0
	s_cmp_lt_u32 s20, 12
	s_cbranch_scc1 .Lk_ret_in

; #define WAIT_L(n) asm volatile("s_waitcnt lgkmcnt(" #n ")" ::: "memory")
; #define BAR __builtin_amdgcn_s_barrier()
; #define SCHED __builtin_amdgcn_sched_barrier(0)
; #define STG_A(b, h, kt) stage_half_s(lds0 + ((b) * 2 + (h)) * HT_B, ((h) ? A1 : Ap) + (kt) * BK, off0, off1)
; #define STG_A(b, h, kt) stage_half_s(lds0 + ((b) * 2 + (h)) * HT_B, ((h) ? A1 : Ap) + (kt) * BK, off0, off1)
; #define LDA8(b, h) _Pragma("unroll") for (int m = 0; m < 4; ++m) _Pragma("unroll") for (int k = 0; k < 2; ++k) \
;     At[m][k] = *(const bf16x8*)(SA_(shm, b, h) + abase + (m * 2 + k) * 1024)
; #define LDB8(dst, b, h) _Pragma("unroll") for (int n = 0; n < 2; ++n) _Pragma("unroll") for (int k = 0; k < 2; ++k) \
;     dst[n][k] = *(const bf16x8*)(SB_(shm, b, h) + bbase + (n * 2 + k) * 1024)
; template <bool HS>
; __device__ __forceinline__ void gemm_tile8(const u16* __restrict__ Ap, const u16* __restrict__ Bp, int K,
;                                            f32x4 (&acc)[2][2][4][2], char* shm, const int tid, const float* hsr = nullptr) {
;   const int wid = tid >> 6, lane = tid & 63, wr = wid >> 2, wc = wid & 3, fr = lane & 15, fq = lane >> 4;
;   int r0, c0, r1, c1;
;   stage_rc(tid * 16, r0, c0);
;   stage_rc(tid * 16 + 8192, r1, c1);
;   const unsigned off0 = (unsigned)(r0 * K + c0) * 2u, off1 = (unsigned)(r1 * K + c1) * 2u;
;   const int wvoff = __builtin_amdgcn_readfirstlane(tid >> 6) * 1024;
;   const u16* A1 = Ap + (size_t)128 * K;
;   const u16* B1p = Bp + (size_t)128 * K;
; #pragma unroll
;   for (int a = 0; a < 2; ++a)
; #pragma unroll
;     for (int b = 0; b < 2; ++b)
; #pragma unroll
;       for (int m = 0; m < 4; ++m)
; #pragma unroll
;         for (int n = 0; n < 2; ++n) acc[a][b][m][n] = f32x4{0.f, 0.f, 0.f, 0.f};
;   const int abase = lds_byte(wr * 64 + fr, fq * 8), bbase = lds_byte(wc * 32 + fr, fq * 8);
;   bf16x8 At[4][2], B0[2][2], B1[2][2];
;   const unsigned lds0 = (unsigned)(size_t)(__attribute__((address_space(3))) char*)shm + (unsigned)wvoff;
;     ...
;     LDB8(B0, 0, 0); SCHED; LDA8(0, 0); STG_A(1, 1, t + 1);
;     WAIT_L(8); BAR; WAIT_L(0); MMA8(0, 0, B0); BAR; SCHED;
.LBB0_650:
	s_or_b64 exec, exec, s[0:1]
	v_bfe_i32 v6, v0, 27, 1
	v_lshlrev_b32_e32 v4, 4, v0
	v_lshrrev_b32_e32 v6, 22, v6
	v_add_u32_e32 v6, v4, v6
	v_and_b32_e32 v6, 0xfffffc00, v6
	v_ashrrev_i32_e32 v5, 31, v0
	v_sub_u32_e32 v6, v4, v6
	v_lshrrev_b32_e32 v5, 26, v5
	v_lshrrev_b32_e32 v7, 4, v6
	v_add_u32_e32 v5, v0, v5
	v_bitop3_b32 v7, v7, v6, 32 bitop3:0x6c
	v_ashrrev_i32_e32 v6, 31, v6
	v_ashrrev_i32_e32 v5, 6, v5
	v_lshrrev_b32_e32 v6, 26, v6
	v_lshlrev_b32_e32 v8, 3, v5
	v_add_u32_e32 v6, v7, v6
	v_and_b32_e32 v8, 0xfffff0, v8
	v_ashrrev_i32_e32 v6, 6, v6
	v_add_u32_e32 v8, v6, v8
	v_mul_i32_i24_e32 v6, 64, v6
	v_add_u32_e32 v4, 0x2000, v4
	v_sub_u32_e32 v6, v7, v6
	v_ashrrev_i32_e32 v7, 31, v4
	v_lshrrev_b32_e32 v7, 22, v7
	v_add_u32_e32 v7, v4, v7
	v_ashrrev_i32_e32 v7, 10, v7
	v_mul_i32_i24_e32 v9, 0x400, v7
	v_sub_u32_e32 v4, v4, v9
	v_lshrrev_b32_e32 v9, 4, v4
	s_ashr_i32 s5, s4, 31
	s_mul_i32 s1, s4, 0x1600
	v_bitop3_b32 v4, v9, v4, 32 bitop3:0x6c
	s_mul_hi_i32 s0, s4, 0x1600
	s_add_u32 s3, s90, s1
	v_ashrrev_i32_e32 v10, 31, v4
	s_addc_u32 s8, s91, s0
	s_mul_i32 s0, s10, 0x160000
	v_lshrrev_b32_e32 v10, 26, v10
	s_ashr_i32 s1, s0, 31
	v_lshlrev_b32_e32 v9, 3, v7
	v_add_u32_e32 v10, v4, v10
	v_lshl_add_u64 v[130:131], v[146:147], 0, s[0:1]
	v_and_b32_e32 v9, 0xfffff0, v9
	v_lshrrev_b32_e32 v11, 6, v10
	v_and_b32_e32 v10, 0xc0, v10
	s_movk_i32 s0, 0xb00
	v_lshlrev_b32_e32 v5, 5, v5
	v_add_u32_e32 v9, v11, v9
	v_sub_u32_e32 v4, v4, v10
	v_mul_lo_u32 v8, v8, s0
	v_lshlrev_b32_e32 v7, 5, v7
	v_ashrrev_i16_sdwa v4, v178, sext(v4) dst_sel:DWORD dst_unused:UNUSED_PAD src0_sel:DWORD src1_sel:BYTE_0
	v_and_or_b32 v5, v5, 32, v8
	v_mul_lo_u32 v8, v9, s0
	v_ashrrev_i16_sdwa v6, v178, sext(v6) dst_sel:DWORD dst_unused:UNUSED_PAD src0_sel:DWORD src1_sel:BYTE_0
	v_bfe_i32 v4, v4, 0, 16
	v_and_or_b32 v7, v7, 32, v8
	v_bfe_i32 v6, v6, 0, 16
	s_add_u32 s9, s3, 0xb0000
	v_and_b32_e32 v8, 15, v0
	v_add_lshl_u32 v135, v7, v4, 1
	v_lshlrev_b32_e32 v7, 2, v0
	s_addc_u32 s11, s8, 0
	v_add_lshl_u32 v136, v5, v6, 1
	s_lshl_b32 s12, s12, 10
	s_mov_b64 s[0:1], 0xb0000
	v_and_b32_e32 v4, 48, v0
	v_lshlrev_b32_e32 v5, 6, v8
	v_and_b32_e32 v7, 32, v7
	v_lshl_add_u64 v[132:133], v[130:131], 0, s[0:1]
	v_or_b32_e32 v6, v5, v4
	v_lshlrev_b32_e32 v3, 13, v3
	v_bitop3_b32 v4, v5, v7, v4 bitop3:0x36
	v_lshlrev_b32_e32 v2, 12, v2
	s_movk_i32 s0, 0x3000
	s_add_i32 s13, s12, 0
	v_bitop3_b32 v3, v6, v3, v7 bitop3:0xde
	v_and_or_b32 v137, v2, s0, v4
	s_add_u32 s14, s3, 0xb0100
	v_mov_b32_e32 v2, 0
	s_addc_u32 s15, s8, 0
	s_mov_b32 s16, -2
	s_mov_b64 s[0:1], 0
	v_add_u32_e32 v134, 0, v3
	s_waitcnt lgkmcnt(0)
	v_readfirstlane_b32 s22, v130
	v_readfirstlane_b32 s23, v131
	v_readfirstlane_b32 s18, v132
	v_readfirstlane_b32 s19, v133
	s_barrier
	s_barrier
	v_add_u32_e32 v164, 0x10000, v137
	ds_read_b128 v[138:141], v164
	ds_read_b128 v[142:145], v164 offset:1024
	ds_read_b128 v[156:159], v164 offset:2048
	ds_read_b128 v[164:167], v164 offset:3072
	ds_read_b128 v[168:171], v134
	ds_read_b128 v[172:175], v134 offset:1024
	ds_read_b128 v[180:183], v134 offset:2048
	ds_read_b128 v[184:187], v134 offset:3072
	ds_read_b128 v[188:191], v134 offset:4096
	ds_read_b128 v[192:195], v134 offset:5120
	ds_read_b128 v[196:199], v134 offset:6144
	ds_read_b128 v[200:203], v134 offset:7168
	v_add_u32_e32 v220, 0x14000, v137
	ds_read_b128 v[204:207], v220
	ds_read_b128 v[208:211], v220 offset:1024
	ds_read_b128 v[212:215], v220 offset:2048
	ds_read_b128 v[220:223], v220 offset:3072
	s_add_u32 s20, s9, s0
	s_addc_u32 s21, s11, s1
	s_add_u32 s20, s20, 0x80
	s_addc_u32 s21, s21, 0
	s_add_i32 s17, s13, 0xc000
	s_mov_b32 m0, s17
	s_nop 0
	global_load_lds_dwordx4 v136, s[20:21]
	s_add_i32 s17, s13, 0xe000
	s_mov_b32 m0, s17
	s_nop 0
	global_load_lds_dwordx4 v135, s[20:21]
	s_waitcnt vmcnt(8) lgkmcnt(0)
	s_barrier
	s_setprio 1
	v_mfma_f32_16x16x32_bf16 v[126:129], v[168:171], v[138:141], 0
	v_mfma_f32_16x16x32_bf16 v[122:125], v[168:171], v[156:159], 0
	v_mfma_f32_16x16x32_bf16 v[118:121], v[180:183], v[138:141], 0
	v_mfma_f32_16x16x32_bf16 v[114:117], v[180:183], v[156:159], 0
	v_mfma_f32_16x16x32_bf16 v[110:113], v[188:191], v[138:141], 0
	v_mfma_f32_16x16x32_bf16 v[106:109], v[188:191], v[156:159], 0
	v_mfma_f32_16x16x32_bf16 v[102:105], v[196:199], v[138:141], 0
	v_mfma_f32_16x16x32_bf16 v[98:101], v[196:199], v[156:159], 0
	v_mfma_f32_16x16x32_bf16 v[126:129], v[172:175], v[142:145], v[126:129]
	v_mfma_f32_16x16x32_bf16 v[122:125], v[172:175], v[164:167], v[122:125]
	v_mfma_f32_16x16x32_bf16 v[118:121], v[184:187], v[142:145], v[118:121]
	v_mfma_f32_16x16x32_bf16 v[114:117], v[184:187], v[164:167], v[114:117]
	v_mfma_f32_16x16x32_bf16 v[110:113], v[192:195], v[142:145], v[110:113]
	v_mfma_f32_16x16x32_bf16 v[106:109], v[192:195], v[164:167], v[106:109]
	v_mfma_f32_16x16x32_bf16 v[102:105], v[200:203], v[142:145], v[102:105]
	v_mfma_f32_16x16x32_bf16 v[98:101], v[200:203], v[164:167], v[98:101]
	v_mfma_f32_16x16x32_bf16 v[94:97], v[168:171], v[204:207], 0
	v_mfma_f32_16x16x32_bf16 v[90:93], v[168:171], v[212:215], 0
	v_mfma_f32_16x16x32_bf16 v[86:89], v[180:183], v[204:207], 0
	v_mfma_f32_16x16x32_bf16 v[82:85], v[180:183], v[212:215], 0
	v_mfma_f32_16x16x32_bf16 v[78:81], v[188:191], v[204:207], 0
	v_mfma_f32_16x16x32_bf16 v[74:77], v[188:191], v[212:215], 0
	v_mfma_f32_16x16x32_bf16 v[70:73], v[196:199], v[204:207], 0
	v_mfma_f32_16x16x32_bf16 v[66:69], v[196:199], v[212:215], 0
	v_mfma_f32_16x16x32_bf16 v[94:97], v[172:175], v[208:211], v[94:97]
	v_mfma_f32_16x16x32_bf16 v[90:93], v[172:175], v[220:223], v[90:93]
	v_mfma_f32_16x16x32_bf16 v[86:89], v[184:187], v[208:211], v[86:89]
	v_mfma_f32_16x16x32_bf16 v[82:85], v[184:187], v[220:223], v[82:85]
	v_mfma_f32_16x16x32_bf16 v[78:81], v[192:195], v[208:211], v[78:81]
	v_mfma_f32_16x16x32_bf16 v[74:77], v[192:195], v[220:223], v[74:77]
	v_mfma_f32_16x16x32_bf16 v[70:73], v[200:203], v[208:211], v[70:73]
	v_mfma_f32_16x16x32_bf16 v[66:69], v[200:203], v[220:223], v[66:69]
	s_setprio 0
	s_barrier
; #define WAIT_V(n) asm volatile("s_waitcnt vmcnt(" #n ")" ::: "memory")
; #define WAIT_L(n) asm volatile("s_waitcnt lgkmcnt(" #n ")" ::: "memory")
; #define BAR __builtin_amdgcn_s_barrier()
; #define SCHED __builtin_amdgcn_sched_barrier(0)
; #define STG_A(b, h, kt) stage_half_s(lds0 + ((b) * 2 + (h)) * HT_B, ((h) ? A1 : Ap) + (kt) * BK, off0, off1)
; #define STG_B(b, h, kt) stage_half_s(lds0 + (4 + (b) * 2 + (h)) * HT_B, ((h) ? B1p : Bp) + (kt) * BK, off0, off1)
; #define STG_A(b, h, kt) stage_half_s(lds0 + ((b) * 2 + (h)) * HT_B, ((h) ? A1 : Ap) + (kt) * BK, off0, off1)
; #define STG_B(b, h, kt) stage_half_s(lds0 + (4 + (b) * 2 + (h)) * HT_B, ((h) ? B1p : Bp) + (kt) * BK, off0, off1)
; #define LDA8(b, h) _Pragma("unroll") for (int m = 0; m < 4; ++m) _Pragma("unroll") for (int k = 0; k < 2; ++k) \
;     At[m][k] = *(const bf16x8*)(SA_(shm, b, h) + abase + (m * 2 + k) * 1024)
; #define LDB8(dst, b, h) _Pragma("unroll") for (int n = 0; n < 2; ++n) _Pragma("unroll") for (int k = 0; k < 2; ++k) \
;     dst[n][k] = *(const bf16x8*)(SB_(shm, b, h) + bbase + (n * 2 + k) * 1024)
; #define MMA8(ai, bj, Bx) do { __builtin_amdgcn_s_setprio(1); \
;     _Pragma("unroll") for (int m = 0; m < 4; ++m) _Pragma("unroll") for (int n = 0; n < 2; ++n) _Pragma("unroll") for (int k = 0; k < 2; ++k) \
;       acc[ai][bj][m][n] = __builtin_amdgcn_mfma_f32_16x16x32_bf16(At[m][k], Bx[n][k], acc[ai][bj][m][n], 0, 0, 0); \
;     __builtin_amdgcn_s_setprio(0); } while (0)
; template <bool HS>
; __device__ __forceinline__ void gemm_tile8(const u16* __restrict__ Ap, const u16* __restrict__ Bp, int K,
;                                            f32x4 (&acc)[2][2][4][2], char* shm, const int tid, const float* hsr = nullptr) {
;     ...
;     LDB8(B1, 0, 1); STG_B(0, 0, t + 2);
;     BAR; WAIT_L(0); MMA8(0, 1, B1); BAR;
;     LDA8(0, 1); STG_A(0, 0, t + 2);
;     BAR; WAIT_L(0); MMA8(1, 0, B0); BAR; SCHED;
;     STG_B(0, 1, t + 2);
;     WAIT_V(6); BAR; MMA8(1, 1, B1); BAR;
;     LDB8(B0, 1, 0); SCHED; LDA8(1, 0); STG_A(0, 1, t + 2);
;     WAIT_L(8); BAR; WAIT_L(0); MMA8(0, 0, B0); BAR; SCHED;
;     LDB8(B1, 1, 1); STG_B(1, 0, t + 3);
;     BAR; WAIT_L(0); MMA8(0, 1, B1); BAR;
	ds_read_b128 v[168:171], v134 offset:16384
	ds_read_b128 v[172:175], v134 offset:17408
	ds_read_b128 v[180:183], v134 offset:18432
	ds_read_b128 v[184:187], v134 offset:19456
	ds_read_b128 v[188:191], v134 offset:20480
	ds_read_b128 v[192:195], v134 offset:21504
	ds_read_b128 v[196:199], v134 offset:22528
	ds_read_b128 v[200:203], v134 offset:23552
	s_add_u32 s20, s22, s0
	s_addc_u32 s21, s23, s1
	s_add_u32 s20, s20, 0x100
	s_addc_u32 s21, s21, 0
	s_add_i32 s17, s13, 0x10000
	s_mov_b32 m0, s17
	s_nop 0
	global_load_lds_dwordx4 v136, s[20:21]
	s_add_i32 s17, s13, 0x12000
	s_mov_b32 m0, s17
	s_nop 0
	global_load_lds_dwordx4 v135, s[20:21]
	s_add_u32 s20, s3, s0
	s_addc_u32 s21, s8, s1
	s_add_u32 s20, s20, 0x100
	s_addc_u32 s21, s21, 0
	s_mov_b32 m0, s13
	s_nop 0
	global_load_lds_dwordx4 v136, s[20:21]
	s_add_i32 s17, s13, 0x2000
	s_mov_b32 m0, s17
	s_nop 0
	global_load_lds_dwordx4 v135, s[20:21]
	s_add_u32 s20, s18, s0
	s_addc_u32 s21, s19, s1
	s_add_u32 s20, s20, 0x100
	s_addc_u32 s21, s21, 0
	s_add_i32 s17, s13, 0x14000
	s_mov_b32 m0, s17
	s_nop 0
	global_load_lds_dwordx4 v136, s[20:21]
	s_add_i32 s17, s13, 0x16000
	s_mov_b32 m0, s17
	s_nop 0
	global_load_lds_dwordx4 v135, s[20:21]
	s_waitcnt vmcnt(8) lgkmcnt(0)
	s_barrier
	s_setprio 1
	v_mfma_f32_16x16x32_bf16 v[62:65], v[168:171], v[138:141], 0
	v_mfma_f32_16x16x32_bf16 v[58:61], v[168:171], v[156:159], 0
	v_mfma_f32_16x16x32_bf16 v[54:57], v[180:183], v[138:141], 0
	v_mfma_f32_16x16x32_bf16 v[50:53], v[180:183], v[156:159], 0
	v_mfma_f32_16x16x32_bf16 v[46:49], v[188:191], v[138:141], 0
	v_mfma_f32_16x16x32_bf16 v[42:45], v[188:191], v[156:159], 0
	v_mfma_f32_16x16x32_bf16 v[38:41], v[196:199], v[138:141], 0
	v_mfma_f32_16x16x32_bf16 v[34:37], v[196:199], v[156:159], 0
	v_mfma_f32_16x16x32_bf16 v[62:65], v[172:175], v[142:145], v[62:65]
	v_mfma_f32_16x16x32_bf16 v[58:61], v[172:175], v[164:167], v[58:61]
	v_mfma_f32_16x16x32_bf16 v[54:57], v[184:187], v[142:145], v[54:57]
	v_mfma_f32_16x16x32_bf16 v[50:53], v[184:187], v[164:167], v[50:53]
	v_mfma_f32_16x16x32_bf16 v[46:49], v[192:195], v[142:145], v[46:49]
	v_mfma_f32_16x16x32_bf16 v[42:45], v[192:195], v[164:167], v[42:45]
	v_mfma_f32_16x16x32_bf16 v[38:41], v[200:203], v[142:145], v[38:41]
	v_mfma_f32_16x16x32_bf16 v[34:37], v[200:203], v[164:167], v[34:37]
	v_mfma_f32_16x16x32_bf16 v[30:33], v[168:171], v[204:207], 0
	v_mfma_f32_16x16x32_bf16 v[26:29], v[168:171], v[212:215], 0
	v_mfma_f32_16x16x32_bf16 v[22:25], v[180:183], v[204:207], 0
	v_mfma_f32_16x16x32_bf16 v[18:21], v[180:183], v[212:215], 0
	v_mfma_f32_16x16x32_bf16 v[14:17], v[188:191], v[204:207], 0
	v_mfma_f32_16x16x32_bf16 v[10:13], v[188:191], v[212:215], 0
	v_mfma_f32_16x16x32_bf16 v[6:9], v[196:199], v[204:207], 0
	v_mfma_f32_16x16x32_bf16 v[2:5], v[196:199], v[212:215], 0
	v_mfma_f32_16x16x32_bf16 v[30:33], v[172:175], v[208:211], v[30:33]
	v_mfma_f32_16x16x32_bf16 v[26:29], v[172:175], v[220:223], v[26:29]
	v_mfma_f32_16x16x32_bf16 v[22:25], v[184:187], v[208:211], v[22:25]
	v_mfma_f32_16x16x32_bf16 v[18:21], v[184:187], v[220:223], v[18:21]
	v_mfma_f32_16x16x32_bf16 v[14:17], v[192:195], v[208:211], v[14:17]
	v_mfma_f32_16x16x32_bf16 v[10:13], v[192:195], v[220:223], v[10:13]
	v_mfma_f32_16x16x32_bf16 v[6:9], v[200:203], v[208:211], v[6:9]
	v_mfma_f32_16x16x32_bf16 v[2:5], v[200:203], v[220:223], v[2:5]
	s_setprio 0
	s_barrier
	v_add_u32_e32 v164, 0x18000, v137
	ds_read_b128 v[138:141], v164
	ds_read_b128 v[142:145], v164 offset:1024
	ds_read_b128 v[156:159], v164 offset:2048
	ds_read_b128 v[164:167], v164 offset:3072
	ds_read_b128 v[168:171], v134 offset:32768
	ds_read_b128 v[172:175], v134 offset:33792
	ds_read_b128 v[180:183], v134 offset:34816
	ds_read_b128 v[184:187], v134 offset:35840
	ds_read_b128 v[188:191], v134 offset:36864
	ds_read_b128 v[192:195], v134 offset:37888
	ds_read_b128 v[196:199], v134 offset:38912
	ds_read_b128 v[200:203], v134 offset:39936
	v_add_u32_e32 v220, 0x1c000, v137
	ds_read_b128 v[204:207], v220
	ds_read_b128 v[208:211], v220 offset:1024
	ds_read_b128 v[212:215], v220 offset:2048
	ds_read_b128 v[220:223], v220 offset:3072
	s_add_u32 s20, s9, s0
	s_addc_u32 s21, s11, s1
	s_add_u32 s20, s20, 0x100
	s_addc_u32 s21, s21, 0
	s_add_i32 s17, s13, 0x4000
	s_mov_b32 m0, s17
	s_nop 0
	global_load_lds_dwordx4 v136, s[20:21]
	s_add_i32 s17, s13, 0x6000
	s_mov_b32 m0, s17
	s_nop 0
	global_load_lds_dwordx4 v135, s[20:21]
	s_waitcnt vmcnt(8) lgkmcnt(0)
	s_barrier
	s_setprio 1
	v_mfma_f32_16x16x32_bf16 v[126:129], v[168:171], v[138:141], v[126:129]
	v_mfma_f32_16x16x32_bf16 v[122:125], v[168:171], v[156:159], v[122:125]
	v_mfma_f32_16x16x32_bf16 v[118:121], v[180:183], v[138:141], v[118:121]
	v_mfma_f32_16x16x32_bf16 v[114:117], v[180:183], v[156:159], v[114:117]
	v_mfma_f32_16x16x32_bf16 v[110:113], v[188:191], v[138:141], v[110:113]
	v_mfma_f32_16x16x32_bf16 v[106:109], v[188:191], v[156:159], v[106:109]
	v_mfma_f32_16x16x32_bf16 v[102:105], v[196:199], v[138:141], v[102:105]
	v_mfma_f32_16x16x32_bf16 v[98:101], v[196:199], v[156:159], v[98:101]
	v_mfma_f32_16x16x32_bf16 v[126:129], v[172:175], v[142:145], v[126:129]
	v_mfma_f32_16x16x32_bf16 v[122:125], v[172:175], v[164:167], v[122:125]
	v_mfma_f32_16x16x32_bf16 v[118:121], v[184:187], v[142:145], v[118:121]
	v_mfma_f32_16x16x32_bf16 v[114:117], v[184:187], v[164:167], v[114:117]
	v_mfma_f32_16x16x32_bf16 v[110:113], v[192:195], v[142:145], v[110:113]
	v_mfma_f32_16x16x32_bf16 v[106:109], v[192:195], v[164:167], v[106:109]
	v_mfma_f32_16x16x32_bf16 v[102:105], v[200:203], v[142:145], v[102:105]
	v_mfma_f32_16x16x32_bf16 v[98:101], v[200:203], v[164:167], v[98:101]
	v_mfma_f32_16x16x32_bf16 v[94:97], v[168:171], v[204:207], v[94:97]
	v_mfma_f32_16x16x32_bf16 v[90:93], v[168:171], v[212:215], v[90:93]
	v_mfma_f32_16x16x32_bf16 v[86:89], v[180:183], v[204:207], v[86:89]
	v_mfma_f32_16x16x32_bf16 v[82:85], v[180:183], v[212:215], v[82:85]
	v_mfma_f32_16x16x32_bf16 v[78:81], v[188:191], v[204:207], v[78:81]
	v_mfma_f32_16x16x32_bf16 v[74:77], v[188:191], v[212:215], v[74:77]
	v_mfma_f32_16x16x32_bf16 v[70:73], v[196:199], v[204:207], v[70:73]
	v_mfma_f32_16x16x32_bf16 v[66:69], v[196:199], v[212:215], v[66:69]
	v_mfma_f32_16x16x32_bf16 v[94:97], v[172:175], v[208:211], v[94:97]
	v_mfma_f32_16x16x32_bf16 v[90:93], v[172:175], v[220:223], v[90:93]
	v_mfma_f32_16x16x32_bf16 v[86:89], v[184:187], v[208:211], v[86:89]
	v_mfma_f32_16x16x32_bf16 v[82:85], v[184:187], v[220:223], v[82:85]
	v_mfma_f32_16x16x32_bf16 v[78:81], v[192:195], v[208:211], v[78:81]
	v_mfma_f32_16x16x32_bf16 v[74:77], v[192:195], v[220:223], v[74:77]
	v_mfma_f32_16x16x32_bf16 v[70:73], v[200:203], v[208:211], v[70:73]
	v_mfma_f32_16x16x32_bf16 v[66:69], v[200:203], v[220:223], v[66:69]
	s_setprio 0
	s_barrier
; #define WAIT_V(n) asm volatile("s_waitcnt vmcnt(" #n ")" ::: "memory")
; #define WAIT_L(n) asm volatile("s_waitcnt lgkmcnt(" #n ")" ::: "memory")
; #define BAR __builtin_amdgcn_s_barrier()
; #define SCHED __builtin_amdgcn_sched_barrier(0)
; #define STG_A(b, h, kt) stage_half_s(lds0 + ((b) * 2 + (h)) * HT_B, ((h) ? A1 : Ap) + (kt) * BK, off0, off1)
; #define STG_B(b, h, kt) stage_half_s(lds0 + (4 + (b) * 2 + (h)) * HT_B, ((h) ? B1p : Bp) + (kt) * BK, off0, off1)
; #define STG_A(b, h, kt) stage_half_s(lds0 + ((b) * 2 + (h)) * HT_B, ((h) ? A1 : Ap) + (kt) * BK, off0, off1)
; #define STG_B(b, h, kt) stage_half_s(lds0 + (4 + (b) * 2 + (h)) * HT_B, ((h) ? B1p : Bp) + (kt) * BK, off0, off1)
; #define LDA8(b, h) _Pragma("unroll") for (int m = 0; m < 4; ++m) _Pragma("unroll") for (int k = 0; k < 2; ++k) \
;     At[m][k] = *(const bf16x8*)(SA_(shm, b, h) + abase + (m * 2 + k) * 1024)
; #define LDB8(dst, b, h) _Pragma("unroll") for (int n = 0; n < 2; ++n) _Pragma("unroll") for (int k = 0; k < 2; ++k) \
;     dst[n][k] = *(const bf16x8*)(SB_(shm, b, h) + bbase + (n * 2 + k) * 1024)
; #define MMA8(ai, bj, Bx) do { __builtin_amdgcn_s_setprio(1); \
;     _Pragma("unroll") for (int m = 0; m < 4; ++m) _Pragma("unroll") for (int n = 0; n < 2; ++n) _Pragma("unroll") for (int k = 0; k < 2; ++k) \
;       acc[ai][bj][m][n] = __builtin_amdgcn_mfma_f32_16x16x32_bf16(At[m][k], Bx[n][k], acc[ai][bj][m][n], 0, 0, 0); \
;     __builtin_amdgcn_s_setprio(0); } while (0)
; template <bool HS>
; __device__ __forceinline__ void gemm_tile8(const u16* __restrict__ Ap, const u16* __restrict__ Bp, int K,
;                                            f32x4 (&acc)[2][2][4][2], char* shm, const int tid, const float* hsr = nullptr) {
;     ...
;     LDB8(B0, 0, 0); SCHED; LDA8(0, 0); STG_A(1, 1, t + 1);
;     WAIT_L(8); BAR; WAIT_L(0); MMA8(0, 0, B0); BAR; SCHED;
;     ...
;     LDA8(1, 1); STG_A(1, 0, t + 3);
;     BAR; WAIT_L(0); MMA8(1, 0, B0); BAR; SCHED;
;     STG_B(1, 1, t + 3);
;     WAIT_V(6); BAR; MMA8(1, 1, B1); BAR;
;   }
	ds_read_b128 v[168:171], v134 offset:49152
	ds_read_b128 v[172:175], v134 offset:50176
	ds_read_b128 v[180:183], v134 offset:51200
	ds_read_b128 v[184:187], v134 offset:52224
	ds_read_b128 v[188:191], v134 offset:53248
	ds_read_b128 v[192:195], v134 offset:54272
	ds_read_b128 v[196:199], v134 offset:55296
	ds_read_b128 v[200:203], v134 offset:56320
	s_add_u32 s20, s22, s0
	s_addc_u32 s21, s23, s1
	s_add_u32 s20, s20, 0x180
	s_addc_u32 s21, s21, 0
	s_add_i32 s17, s13, 0x18000
	s_mov_b32 m0, s17
	s_nop 0
	global_load_lds_dwordx4 v136, s[20:21]
	s_add_i32 s17, s13, 0x1a000
	s_mov_b32 m0, s17
	s_nop 0
	global_load_lds_dwordx4 v135, s[20:21]
	s_add_u32 s20, s3, s0
	s_addc_u32 s21, s8, s1
	s_add_u32 s20, s20, 0x180
	s_addc_u32 s21, s21, 0
	s_add_i32 s17, s13, 0x8000
	s_mov_b32 m0, s17
	s_nop 0
	global_load_lds_dwordx4 v136, s[20:21]
	s_add_i32 s17, s13, 0xa000
	s_mov_b32 m0, s17
	s_nop 0
	global_load_lds_dwordx4 v135, s[20:21]
	s_add_u32 s20, s18, s0
	s_addc_u32 s21, s19, s1
	s_add_u32 s20, s20, 0x180
	s_addc_u32 s21, s21, 0
	s_add_i32 s17, s13, 0x1c000
	s_mov_b32 m0, s17
	s_nop 0
	global_load_lds_dwordx4 v136, s[20:21]
	s_add_i32 s17, s13, 0x1e000
	s_mov_b32 m0, s17
	s_nop 0
	global_load_lds_dwordx4 v135, s[20:21]
	s_waitcnt vmcnt(8) lgkmcnt(0)
	s_barrier
	s_setprio 1
	v_mfma_f32_16x16x32_bf16 v[62:65], v[168:171], v[138:141], v[62:65]
	v_mfma_f32_16x16x32_bf16 v[58:61], v[168:171], v[156:159], v[58:61]
	v_mfma_f32_16x16x32_bf16 v[54:57], v[180:183], v[138:141], v[54:57]
	v_mfma_f32_16x16x32_bf16 v[50:53], v[180:183], v[156:159], v[50:53]
	v_mfma_f32_16x16x32_bf16 v[46:49], v[188:191], v[138:141], v[46:49]
	v_mfma_f32_16x16x32_bf16 v[42:45], v[188:191], v[156:159], v[42:45]
	v_mfma_f32_16x16x32_bf16 v[38:41], v[196:199], v[138:141], v[38:41]
	v_mfma_f32_16x16x32_bf16 v[34:37], v[196:199], v[156:159], v[34:37]
	v_mfma_f32_16x16x32_bf16 v[62:65], v[172:175], v[142:145], v[62:65]
	v_mfma_f32_16x16x32_bf16 v[58:61], v[172:175], v[164:167], v[58:61]
	v_mfma_f32_16x16x32_bf16 v[54:57], v[184:187], v[142:145], v[54:57]
	v_mfma_f32_16x16x32_bf16 v[50:53], v[184:187], v[164:167], v[50:53]
	v_mfma_f32_16x16x32_bf16 v[46:49], v[192:195], v[142:145], v[46:49]
	v_mfma_f32_16x16x32_bf16 v[42:45], v[192:195], v[164:167], v[42:45]
	v_mfma_f32_16x16x32_bf16 v[38:41], v[200:203], v[142:145], v[38:41]
	v_mfma_f32_16x16x32_bf16 v[34:37], v[200:203], v[164:167], v[34:37]
	v_mfma_f32_16x16x32_bf16 v[30:33], v[168:171], v[204:207], v[30:33]
	v_mfma_f32_16x16x32_bf16 v[26:29], v[168:171], v[212:215], v[26:29]
	v_mfma_f32_16x16x32_bf16 v[22:25], v[180:183], v[204:207], v[22:25]
	v_mfma_f32_16x16x32_bf16 v[18:21], v[180:183], v[212:215], v[18:21]
	v_mfma_f32_16x16x32_bf16 v[14:17], v[188:191], v[204:207], v[14:17]
	v_mfma_f32_16x16x32_bf16 v[10:13], v[188:191], v[212:215], v[10:13]
	v_mfma_f32_16x16x32_bf16 v[6:9], v[196:199], v[204:207], v[6:9]
	v_mfma_f32_16x16x32_bf16 v[2:5], v[196:199], v[212:215], v[2:5]
	v_mfma_f32_16x16x32_bf16 v[30:33], v[172:175], v[208:211], v[30:33]
	v_mfma_f32_16x16x32_bf16 v[26:29], v[172:175], v[220:223], v[26:29]
	v_mfma_f32_16x16x32_bf16 v[22:25], v[184:187], v[208:211], v[22:25]
	v_mfma_f32_16x16x32_bf16 v[18:21], v[184:187], v[220:223], v[18:21]
	v_mfma_f32_16x16x32_bf16 v[14:17], v[192:195], v[208:211], v[14:17]
	v_mfma_f32_16x16x32_bf16 v[10:13], v[192:195], v[220:223], v[10:13]
	v_mfma_f32_16x16x32_bf16 v[6:9], v[200:203], v[208:211], v[6:9]
	v_mfma_f32_16x16x32_bf16 v[2:5], v[200:203], v[220:223], v[2:5]
	s_setprio 0
	s_barrier
	s_add_i32 s16, s16, 2
	s_add_u32 s0, s0, 0x100
	s_addc_u32 s1, s1, 0
	s_cmp_lt_u32 s16, 40
	s_cbranch_scc0 .Lk_ffn_out_exit
.Lk_ffn_out:
	v_add_u32_e32 v164, 0x10000, v137
	ds_read_b128 v[138:141], v164
	ds_read_b128 v[142:145], v164 offset:1024
	ds_read_b128 v[156:159], v164 offset:2048
	ds_read_b128 v[164:167], v164 offset:3072
	ds_read_b128 v[168:171], v134
	ds_read_b128 v[172:175], v134 offset:1024
	ds_read_b128 v[180:183], v134 offset:2048
	ds_read_b128 v[184:187], v134 offset:3072
	ds_read_b128 v[188:191], v134 offset:4096
	ds_read_b128 v[192:195], v134 offset:5120
	ds_read_b128 v[196:199], v134 offset:6144
	ds_read_b128 v[200:203], v134 offset:7168
	v_add_u32_e32 v220, 0x14000, v137
	ds_read_b128 v[204:207], v220
	ds_read_b128 v[208:211], v220 offset:1024
	ds_read_b128 v[212:215], v220 offset:2048
	ds_read_b128 v[220:223], v220 offset:3072
	s_add_u32 s20, s9, s0
	s_addc_u32 s21, s11, s1
	s_add_u32 s20, s20, 0x80
	s_addc_u32 s21, s21, 0
	s_add_i32 s17, s13, 0xc000
	s_mov_b32 m0, s17
	s_nop 0
	global_load_lds_dwordx4 v136, s[20:21]
	s_add_i32 s17, s13, 0xe000
	s_mov_b32 m0, s17
	s_nop 0
	global_load_lds_dwordx4 v135, s[20:21]
	s_waitcnt vmcnt(8) lgkmcnt(0)
	s_barrier
; #define WAIT_V(n) asm volatile("s_waitcnt vmcnt(" #n ")" ::: "memory")
; #define WAIT_L(n) asm volatile("s_waitcnt lgkmcnt(" #n ")" ::: "memory")
; #define BAR __builtin_amdgcn_s_barrier()
; #define SCHED __builtin_amdgcn_sched_barrier(0)
; #define STG_A(b, h, kt) stage_half_s(lds0 + ((b) * 2 + (h)) * HT_B, ((h) ? A1 : Ap) + (kt) * BK, off0, off1)
; #define STG_B(b, h, kt) stage_half_s(lds0 + (4 + (b) * 2 + (h)) * HT_B, ((h) ? B1p : Bp) + (kt) * BK, off0, off1)
; #define STG_A(b, h, kt) stage_half_s(lds0 + ((b) * 2 + (h)) * HT_B, ((h) ? A1 : Ap) + (kt) * BK, off0, off1)
; #define STG_B(b, h, kt) stage_half_s(lds0 + (4 + (b) * 2 + (h)) * HT_B, ((h) ? B1p : Bp) + (kt) * BK, off0, off1)
; #define LDA8(b, h) _Pragma("unroll") for (int m = 0; m < 4; ++m) _Pragma("unroll") for (int k = 0; k < 2; ++k) \
;     At[m][k] = *(const bf16x8*)(SA_(shm, b, h) + abase + (m * 2 + k) * 1024)
; #define LDB8(dst, b, h) _Pragma("unroll") for (int n = 0; n < 2; ++n) _Pragma("unroll") for (int k = 0; k < 2; ++k) \
;     dst[n][k] = *(const bf16x8*)(SB_(shm, b, h) + bbase + (n * 2 + k) * 1024)
; #define MMA8(ai, bj, Bx) do { __builtin_amdgcn_s_setprio(1); \
;     _Pragma("unroll") for (int m = 0; m < 4; ++m) _Pragma("unroll") for (int n = 0; n < 2; ++n) _Pragma("unroll") for (int k = 0; k < 2; ++k) \
;       acc[ai][bj][m][n] = __builtin_amdgcn_mfma_f32_16x16x32_bf16(At[m][k], Bx[n][k], acc[ai][bj][m][n], 0, 0, 0); \
;     __builtin_amdgcn_s_setprio(0); } while (0)
; template <bool HS>
; __device__ __forceinline__ void gemm_tile8(const u16* __restrict__ Ap, const u16* __restrict__ Bp, int K,
;                                            f32x4 (&acc)[2][2][4][2], char* shm, const int tid, const float* hsr = nullptr) {
;     ...
;     LDB8(B0, 0, 0); SCHED; LDA8(0, 0); STG_A(1, 1, t + 1);
;     WAIT_L(8); BAR; WAIT_L(0); MMA8(0, 0, B0); BAR; SCHED;
;     LDB8(B1, 0, 1); STG_B(0, 0, t + 2);
;     BAR; WAIT_L(0); MMA8(0, 1, B1); BAR;
;     LDA8(0, 1); STG_A(0, 0, t + 2);
;     BAR; WAIT_L(0); MMA8(1, 0, B0); BAR; SCHED;
;     STG_B(0, 1, t + 2);
;     WAIT_V(6); BAR; MMA8(1, 1, B1); BAR;
	s_setprio 1
	v_mfma_f32_16x16x32_bf16 v[126:129], v[168:171], v[138:141], v[126:129]
	v_mfma_f32_16x16x32_bf16 v[122:125], v[168:171], v[156:159], v[122:125]
	v_mfma_f32_16x16x32_bf16 v[118:121], v[180:183], v[138:141], v[118:121]
	v_mfma_f32_16x16x32_bf16 v[114:117], v[180:183], v[156:159], v[114:117]
	v_mfma_f32_16x16x32_bf16 v[110:113], v[188:191], v[138:141], v[110:113]
	v_mfma_f32_16x16x32_bf16 v[106:109], v[188:191], v[156:159], v[106:109]
	v_mfma_f32_16x16x32_bf16 v[102:105], v[196:199], v[138:141], v[102:105]
	v_mfma_f32_16x16x32_bf16 v[98:101], v[196:199], v[156:159], v[98:101]
	v_mfma_f32_16x16x32_bf16 v[126:129], v[172:175], v[142:145], v[126:129]
	v_mfma_f32_16x16x32_bf16 v[122:125], v[172:175], v[164:167], v[122:125]
	v_mfma_f32_16x16x32_bf16 v[118:121], v[184:187], v[142:145], v[118:121]
	v_mfma_f32_16x16x32_bf16 v[114:117], v[184:187], v[164:167], v[114:117]
	v_mfma_f32_16x16x32_bf16 v[110:113], v[192:195], v[142:145], v[110:113]
	v_mfma_f32_16x16x32_bf16 v[106:109], v[192:195], v[164:167], v[106:109]
	v_mfma_f32_16x16x32_bf16 v[102:105], v[200:203], v[142:145], v[102:105]
	v_mfma_f32_16x16x32_bf16 v[98:101], v[200:203], v[164:167], v[98:101]
	v_mfma_f32_16x16x32_bf16 v[94:97], v[168:171], v[204:207], v[94:97]
	v_mfma_f32_16x16x32_bf16 v[90:93], v[168:171], v[212:215], v[90:93]
	v_mfma_f32_16x16x32_bf16 v[86:89], v[180:183], v[204:207], v[86:89]
	v_mfma_f32_16x16x32_bf16 v[82:85], v[180:183], v[212:215], v[82:85]
	v_mfma_f32_16x16x32_bf16 v[78:81], v[188:191], v[204:207], v[78:81]
	v_mfma_f32_16x16x32_bf16 v[74:77], v[188:191], v[212:215], v[74:77]
	v_mfma_f32_16x16x32_bf16 v[70:73], v[196:199], v[204:207], v[70:73]
	v_mfma_f32_16x16x32_bf16 v[66:69], v[196:199], v[212:215], v[66:69]
	v_mfma_f32_16x16x32_bf16 v[94:97], v[172:175], v[208:211], v[94:97]
	v_mfma_f32_16x16x32_bf16 v[90:93], v[172:175], v[220:223], v[90:93]
	v_mfma_f32_16x16x32_bf16 v[86:89], v[184:187], v[208:211], v[86:89]
	v_mfma_f32_16x16x32_bf16 v[82:85], v[184:187], v[220:223], v[82:85]
	v_mfma_f32_16x16x32_bf16 v[78:81], v[192:195], v[208:211], v[78:81]
	v_mfma_f32_16x16x32_bf16 v[74:77], v[192:195], v[220:223], v[74:77]
	v_mfma_f32_16x16x32_bf16 v[70:73], v[200:203], v[208:211], v[70:73]
	v_mfma_f32_16x16x32_bf16 v[66:69], v[200:203], v[220:223], v[66:69]
	s_setprio 0
	s_barrier
	ds_read_b128 v[168:171], v134 offset:16384
	ds_read_b128 v[172:175], v134 offset:17408
	ds_read_b128 v[180:183], v134 offset:18432
	ds_read_b128 v[184:187], v134 offset:19456
	ds_read_b128 v[188:191], v134 offset:20480
	ds_read_b128 v[192:195], v134 offset:21504
	ds_read_b128 v[196:199], v134 offset:22528
	ds_read_b128 v[200:203], v134 offset:23552
	s_add_u32 s20, s22, s0
	s_addc_u32 s21, s23, s1
	s_add_u32 s20, s20, 0x100
	s_addc_u32 s21, s21, 0
	s_add_i32 s17, s13, 0x10000
	s_mov_b32 m0, s17
	s_nop 0
	global_load_lds_dwordx4 v136, s[20:21]
	s_add_i32 s17, s13, 0x12000
	s_mov_b32 m0, s17
	s_nop 0
	global_load_lds_dwordx4 v135, s[20:21]
	s_add_u32 s20, s3, s0
	s_addc_u32 s21, s8, s1
	s_add_u32 s20, s20, 0x100
	s_addc_u32 s21, s21, 0
	s_mov_b32 m0, s13
	s_nop 0
	global_load_lds_dwordx4 v136, s[20:21]
	s_add_i32 s17, s13, 0x2000
	s_mov_b32 m0, s17
	s_nop 0
	global_load_lds_dwordx4 v135, s[20:21]
	s_add_u32 s20, s18, s0
	s_addc_u32 s21, s19, s1
	s_add_u32 s20, s20, 0x100
	s_addc_u32 s21, s21, 0
	s_add_i32 s17, s13, 0x14000
	s_mov_b32 m0, s17
	s_nop 0
	global_load_lds_dwordx4 v136, s[20:21]
	s_add_i32 s17, s13, 0x16000
	s_mov_b32 m0, s17
	s_nop 0
	global_load_lds_dwordx4 v135, s[20:21]
	s_waitcnt vmcnt(8) lgkmcnt(0)
	s_barrier
	s_setprio 1
	v_mfma_f32_16x16x32_bf16 v[62:65], v[168:171], v[138:141], v[62:65]
	v_mfma_f32_16x16x32_bf16 v[58:61], v[168:171], v[156:159], v[58:61]
	v_mfma_f32_16x16x32_bf16 v[54:57], v[180:183], v[138:141], v[54:57]
	v_mfma_f32_16x16x32_bf16 v[50:53], v[180:183], v[156:159], v[50:53]
	v_mfma_f32_16x16x32_bf16 v[46:49], v[188:191], v[138:141], v[46:49]
	v_mfma_f32_16x16x32_bf16 v[42:45], v[188:191], v[156:159], v[42:45]
	v_mfma_f32_16x16x32_bf16 v[38:41], v[196:199], v[138:141], v[38:41]
	v_mfma_f32_16x16x32_bf16 v[34:37], v[196:199], v[156:159], v[34:37]
	v_mfma_f32_16x16x32_bf16 v[62:65], v[172:175], v[142:145], v[62:65]
	v_mfma_f32_16x16x32_bf16 v[58:61], v[172:175], v[164:167], v[58:61]
	v_mfma_f32_16x16x32_bf16 v[54:57], v[184:187], v[142:145], v[54:57]
	v_mfma_f32_16x16x32_bf16 v[50:53], v[184:187], v[164:167], v[50:53]
	v_mfma_f32_16x16x32_bf16 v[46:49], v[192:195], v[142:145], v[46:49]
	v_mfma_f32_16x16x32_bf16 v[42:45], v[192:195], v[164:167], v[42:45]
	v_mfma_f32_16x16x32_bf16 v[38:41], v[200:203], v[142:145], v[38:41]
	v_mfma_f32_16x16x32_bf16 v[34:37], v[200:203], v[164:167], v[34:37]
	v_mfma_f32_16x16x32_bf16 v[30:33], v[168:171], v[204:207], v[30:33]
	v_mfma_f32_16x16x32_bf16 v[26:29], v[168:171], v[212:215], v[26:29]
	v_mfma_f32_16x16x32_bf16 v[22:25], v[180:183], v[204:207], v[22:25]
	v_mfma_f32_16x16x32_bf16 v[18:21], v[180:183], v[212:215], v[18:21]
	v_mfma_f32_16x16x32_bf16 v[14:17], v[188:191], v[204:207], v[14:17]
	v_mfma_f32_16x16x32_bf16 v[10:13], v[188:191], v[212:215], v[10:13]
	v_mfma_f32_16x16x32_bf16 v[6:9], v[196:199], v[204:207], v[6:9]
	v_mfma_f32_16x16x32_bf16 v[2:5], v[196:199], v[212:215], v[2:5]
	v_mfma_f32_16x16x32_bf16 v[30:33], v[172:175], v[208:211], v[30:33]
	v_mfma_f32_16x16x32_bf16 v[26:29], v[172:175], v[220:223], v[26:29]
	v_mfma_f32_16x16x32_bf16 v[22:25], v[184:187], v[208:211], v[22:25]
	v_mfma_f32_16x16x32_bf16 v[18:21], v[184:187], v[220:223], v[18:21]
	v_mfma_f32_16x16x32_bf16 v[14:17], v[192:195], v[208:211], v[14:17]
	v_mfma_f32_16x16x32_bf16 v[10:13], v[192:195], v[220:223], v[10:13]
	v_mfma_f32_16x16x32_bf16 v[6:9], v[200:203], v[208:211], v[6:9]
	v_mfma_f32_16x16x32_bf16 v[2:5], v[200:203], v[220:223], v[2:5]
	s_setprio 0
	s_barrier
; #define WAIT_V(n) asm volatile("s_waitcnt vmcnt(" #n ")" ::: "memory")
; #define WAIT_L(n) asm volatile("s_waitcnt lgkmcnt(" #n ")" ::: "memory")
; #define BAR __builtin_amdgcn_s_barrier()
; #define SCHED __builtin_amdgcn_sched_barrier(0)
; #define STG_A(b, h, kt) stage_half_s(lds0 + ((b) * 2 + (h)) * HT_B, ((h) ? A1 : Ap) + (kt) * BK, off0, off1)
; #define STG_B(b, h, kt) stage_half_s(lds0 + (4 + (b) * 2 + (h)) * HT_B, ((h) ? B1p : Bp) + (kt) * BK, off0, off1)
; #define STG_A(b, h, kt) stage_half_s(lds0 + ((b) * 2 + (h)) * HT_B, ((h) ? A1 : Ap) + (kt) * BK, off0, off1)
; #define STG_B(b, h, kt) stage_half_s(lds0 + (4 + (b) * 2 + (h)) * HT_B, ((h) ? B1p : Bp) + (kt) * BK, off0, off1)
; #define LDA8(b, h) _Pragma("unroll") for (int m = 0; m < 4; ++m) _Pragma("unroll") for (int k = 0; k < 2; ++k) \
;     At[m][k] = *(const bf16x8*)(SA_(shm, b, h) + abase + (m * 2 + k) * 1024)
; #define LDB8(dst, b, h) _Pragma("unroll") for (int n = 0; n < 2; ++n) _Pragma("unroll") for (int k = 0; k < 2; ++k) \
;     dst[n][k] = *(const bf16x8*)(SB_(shm, b, h) + bbase + (n * 2 + k) * 1024)
; #define MMA8(ai, bj, Bx) do { __builtin_amdgcn_s_setprio(1); \
;     _Pragma("unroll") for (int m = 0; m < 4; ++m) _Pragma("unroll") for (int n = 0; n < 2; ++n) _Pragma("unroll") for (int k = 0; k < 2; ++k) \
;       acc[ai][bj][m][n] = __builtin_amdgcn_mfma_f32_16x16x32_bf16(At[m][k], Bx[n][k], acc[ai][bj][m][n], 0, 0, 0); \
;     __builtin_amdgcn_s_setprio(0); } while (0)
; template <bool HS>
; __device__ __forceinline__ void gemm_tile8(const u16* __restrict__ Ap, const u16* __restrict__ Bp, int K,
;                                            f32x4 (&acc)[2][2][4][2], char* shm, const int tid, const float* hsr = nullptr) {
;     ...
;     LDB8(B0, 1, 0); SCHED; LDA8(1, 0); STG_A(0, 1, t + 2);
;     WAIT_L(8); BAR; WAIT_L(0); MMA8(0, 0, B0); BAR; SCHED;
;     LDB8(B1, 1, 1); STG_B(1, 0, t + 3);
;     BAR; WAIT_L(0); MMA8(0, 1, B1); BAR;
;     LDA8(1, 1); STG_A(1, 0, t + 3);
;     BAR; WAIT_L(0); MMA8(1, 0, B0); BAR; SCHED;
;     STG_B(1, 1, t + 3);
;     WAIT_V(6); BAR; MMA8(1, 1, B1); BAR;
;   }
	v_add_u32_e32 v164, 0x18000, v137
	ds_read_b128 v[138:141], v164
	ds_read_b128 v[142:145], v164 offset:1024
	ds_read_b128 v[156:159], v164 offset:2048
	ds_read_b128 v[164:167], v164 offset:3072
	ds_read_b128 v[168:171], v134 offset:32768
	ds_read_b128 v[172:175], v134 offset:33792
	ds_read_b128 v[180:183], v134 offset:34816
	ds_read_b128 v[184:187], v134 offset:35840
	ds_read_b128 v[188:191], v134 offset:36864
	ds_read_b128 v[192:195], v134 offset:37888
	ds_read_b128 v[196:199], v134 offset:38912
	ds_read_b128 v[200:203], v134 offset:39936
	v_add_u32_e32 v220, 0x1c000, v137
	ds_read_b128 v[204:207], v220
	ds_read_b128 v[208:211], v220 offset:1024
	ds_read_b128 v[212:215], v220 offset:2048
	ds_read_b128 v[220:223], v220 offset:3072
	s_add_u32 s20, s9, s0
	s_addc_u32 s21, s11, s1
	s_add_u32 s20, s20, 0x100
	s_addc_u32 s21, s21, 0
	s_add_i32 s17, s13, 0x4000
	s_mov_b32 m0, s17
	s_nop 0
	global_load_lds_dwordx4 v136, s[20:21]
	s_add_i32 s17, s13, 0x6000
	s_mov_b32 m0, s17
	s_nop 0
	global_load_lds_dwordx4 v135, s[20:21]
	s_waitcnt vmcnt(8) lgkmcnt(0)
	s_barrier
	s_setprio 1
	v_mfma_f32_16x16x32_bf16 v[126:129], v[168:171], v[138:141], v[126:129]
	v_mfma_f32_16x16x32_bf16 v[122:125], v[168:171], v[156:159], v[122:125]
	v_mfma_f32_16x16x32_bf16 v[118:121], v[180:183], v[138:141], v[118:121]
	v_mfma_f32_16x16x32_bf16 v[114:117], v[180:183], v[156:159], v[114:117]
	v_mfma_f32_16x16x32_bf16 v[110:113], v[188:191], v[138:141], v[110:113]
	v_mfma_f32_16x16x32_bf16 v[106:109], v[188:191], v[156:159], v[106:109]
	v_mfma_f32_16x16x32_bf16 v[102:105], v[196:199], v[138:141], v[102:105]
	v_mfma_f32_16x16x32_bf16 v[98:101], v[196:199], v[156:159], v[98:101]
	v_mfma_f32_16x16x32_bf16 v[126:129], v[172:175], v[142:145], v[126:129]
	v_mfma_f32_16x16x32_bf16 v[122:125], v[172:175], v[164:167], v[122:125]
	v_mfma_f32_16x16x32_bf16 v[118:121], v[184:187], v[142:145], v[118:121]
	v_mfma_f32_16x16x32_bf16 v[114:117], v[184:187], v[164:167], v[114:117]
	v_mfma_f32_16x16x32_bf16 v[110:113], v[192:195], v[142:145], v[110:113]
	v_mfma_f32_16x16x32_bf16 v[106:109], v[192:195], v[164:167], v[106:109]
	v_mfma_f32_16x16x32_bf16 v[102:105], v[200:203], v[142:145], v[102:105]
	v_mfma_f32_16x16x32_bf16 v[98:101], v[200:203], v[164:167], v[98:101]
	v_mfma_f32_16x16x32_bf16 v[94:97], v[168:171], v[204:207], v[94:97]
	v_mfma_f32_16x16x32_bf16 v[90:93], v[168:171], v[212:215], v[90:93]
	v_mfma_f32_16x16x32_bf16 v[86:89], v[180:183], v[204:207], v[86:89]
	v_mfma_f32_16x16x32_bf16 v[82:85], v[180:183], v[212:215], v[82:85]
	v_mfma_f32_16x16x32_bf16 v[78:81], v[188:191], v[204:207], v[78:81]
	v_mfma_f32_16x16x32_bf16 v[74:77], v[188:191], v[212:215], v[74:77]
	v_mfma_f32_16x16x32_bf16 v[70:73], v[196:199], v[204:207], v[70:73]
	v_mfma_f32_16x16x32_bf16 v[66:69], v[196:199], v[212:215], v[66:69]
	v_mfma_f32_16x16x32_bf16 v[94:97], v[172:175], v[208:211], v[94:97]
	v_mfma_f32_16x16x32_bf16 v[90:93], v[172:175], v[220:223], v[90:93]
	v_mfma_f32_16x16x32_bf16 v[86:89], v[184:187], v[208:211], v[86:89]
	v_mfma_f32_16x16x32_bf16 v[82:85], v[184:187], v[220:223], v[82:85]
	v_mfma_f32_16x16x32_bf16 v[78:81], v[192:195], v[208:211], v[78:81]
	v_mfma_f32_16x16x32_bf16 v[74:77], v[192:195], v[220:223], v[74:77]
	v_mfma_f32_16x16x32_bf16 v[70:73], v[200:203], v[208:211], v[70:73]
	v_mfma_f32_16x16x32_bf16 v[66:69], v[200:203], v[220:223], v[66:69]
	s_setprio 0
	s_barrier
	ds_read_b128 v[168:171], v134 offset:49152
	ds_read_b128 v[172:175], v134 offset:50176
	ds_read_b128 v[180:183], v134 offset:51200
	ds_read_b128 v[184:187], v134 offset:52224
	ds_read_b128 v[188:191], v134 offset:53248
	ds_read_b128 v[192:195], v134 offset:54272
	ds_read_b128 v[196:199], v134 offset:55296
	ds_read_b128 v[200:203], v134 offset:56320
	s_add_u32 s20, s22, s0
	s_addc_u32 s21, s23, s1
	s_add_u32 s20, s20, 0x180
	s_addc_u32 s21, s21, 0
	s_add_i32 s17, s13, 0x18000
	s_mov_b32 m0, s17
	s_nop 0
	global_load_lds_dwordx4 v136, s[20:21]
	s_add_i32 s17, s13, 0x1a000
	s_mov_b32 m0, s17
	s_nop 0
	global_load_lds_dwordx4 v135, s[20:21]
	s_add_u32 s20, s3, s0
	s_addc_u32 s21, s8, s1
	s_add_u32 s20, s20, 0x180
	s_addc_u32 s21, s21, 0
	s_add_i32 s17, s13, 0x8000
	s_mov_b32 m0, s17
	s_nop 0
	global_load_lds_dwordx4 v136, s[20:21]
	s_add_i32 s17, s13, 0xa000
	s_mov_b32 m0, s17
	s_nop 0
	global_load_lds_dwordx4 v135, s[20:21]
	s_add_u32 s20, s18, s0
	s_addc_u32 s21, s19, s1
	s_add_u32 s20, s20, 0x180
	s_addc_u32 s21, s21, 0
	s_add_i32 s17, s13, 0x1c000
	s_mov_b32 m0, s17
	s_nop 0
	global_load_lds_dwordx4 v136, s[20:21]
	s_add_i32 s17, s13, 0x1e000
	s_mov_b32 m0, s17
	s_nop 0
	global_load_lds_dwordx4 v135, s[20:21]
	s_waitcnt vmcnt(8) lgkmcnt(0)
	s_barrier
	s_setprio 1
	v_mfma_f32_16x16x32_bf16 v[62:65], v[168:171], v[138:141], v[62:65]
	v_mfma_f32_16x16x32_bf16 v[58:61], v[168:171], v[156:159], v[58:61]
	v_mfma_f32_16x16x32_bf16 v[54:57], v[180:183], v[138:141], v[54:57]
	v_mfma_f32_16x16x32_bf16 v[50:53], v[180:183], v[156:159], v[50:53]
	v_mfma_f32_16x16x32_bf16 v[46:49], v[188:191], v[138:141], v[46:49]
	v_mfma_f32_16x16x32_bf16 v[42:45], v[188:191], v[156:159], v[42:45]
	v_mfma_f32_16x16x32_bf16 v[38:41], v[196:199], v[138:141], v[38:41]
	v_mfma_f32_16x16x32_bf16 v[34:37], v[196:199], v[156:159], v[34:37]
	v_mfma_f32_16x16x32_bf16 v[62:65], v[172:175], v[142:145], v[62:65]
	v_mfma_f32_16x16x32_bf16 v[58:61], v[172:175], v[164:167], v[58:61]
	v_mfma_f32_16x16x32_bf16 v[54:57], v[184:187], v[142:145], v[54:57]
	v_mfma_f32_16x16x32_bf16 v[50:53], v[184:187], v[164:167], v[50:53]
	v_mfma_f32_16x16x32_bf16 v[46:49], v[192:195], v[142:145], v[46:49]
	v_mfma_f32_16x16x32_bf16 v[42:45], v[192:195], v[164:167], v[42:45]
	v_mfma_f32_16x16x32_bf16 v[38:41], v[200:203], v[142:145], v[38:41]
	v_mfma_f32_16x16x32_bf16 v[34:37], v[200:203], v[164:167], v[34:37]
	v_mfma_f32_16x16x32_bf16 v[30:33], v[168:171], v[204:207], v[30:33]
	v_mfma_f32_16x16x32_bf16 v[26:29], v[168:171], v[212:215], v[26:29]
	v_mfma_f32_16x16x32_bf16 v[22:25], v[180:183], v[204:207], v[22:25]
	v_mfma_f32_16x16x32_bf16 v[18:21], v[180:183], v[212:215], v[18:21]
	v_mfma_f32_16x16x32_bf16 v[14:17], v[188:191], v[204:207], v[14:17]
	v_mfma_f32_16x16x32_bf16 v[10:13], v[188:191], v[212:215], v[10:13]
	v_mfma_f32_16x16x32_bf16 v[6:9], v[196:199], v[204:207], v[6:9]
	v_mfma_f32_16x16x32_bf16 v[2:5], v[196:199], v[212:215], v[2:5]
	v_mfma_f32_16x16x32_bf16 v[30:33], v[172:175], v[208:211], v[30:33]
	v_mfma_f32_16x16x32_bf16 v[26:29], v[172:175], v[220:223], v[26:29]
	v_mfma_f32_16x16x32_bf16 v[22:25], v[184:187], v[208:211], v[22:25]
	v_mfma_f32_16x16x32_bf16 v[18:21], v[184:187], v[220:223], v[18:21]
	v_mfma_f32_16x16x32_bf16 v[14:17], v[192:195], v[208:211], v[14:17]
	v_mfma_f32_16x16x32_bf16 v[10:13], v[192:195], v[220:223], v[10:13]
	v_mfma_f32_16x16x32_bf16 v[6:9], v[200:203], v[208:211], v[6:9]
	v_mfma_f32_16x16x32_bf16 v[2:5], v[200:203], v[220:223], v[2:5]
	s_setprio 0
	s_barrier
	s_add_i32 s16, s16, 2
	s_add_u32 s0, s0, 0x100
	s_addc_u32 s1, s1, 0
	s_cmp_lt_u32 s16, 40
	s_cbranch_scc1 .Lk_ffn_out

; #define WAIT_V(n) asm volatile("s_waitcnt vmcnt(" #n ")" ::: "memory")
; #define WAIT_L(n) asm volatile("s_waitcnt lgkmcnt(" #n ")" ::: "memory")
; #define BAR __builtin_amdgcn_s_barrier()
; #define SCHED __builtin_amdgcn_sched_barrier(0)
; #define STG_A(b, h, kt) stage_half_s(lds0 + ((b) * 2 + (h)) * HT_B, ((h) ? A1 : Ap) + (kt) * BK, off0, off1)
; #define STG_B(b, h, kt) stage_half_s(lds0 + (4 + (b) * 2 + (h)) * HT_B, ((h) ? B1p : Bp) + (kt) * BK, off0, off1)
; #define STG_A(b, h, kt) stage_half_s(lds0 + ((b) * 2 + (h)) * HT_B, ((h) ? A1 : Ap) + (kt) * BK, off0, off1)
; #define STG_B(b, h, kt) stage_half_s(lds0 + (4 + (b) * 2 + (h)) * HT_B, ((h) ? B1p : Bp) + (kt) * BK, off0, off1)
; #define LDA8(b, h) _Pragma("unroll") for (int m = 0; m < 4; ++m) _Pragma("unroll") for (int k = 0; k < 2; ++k) \
;     At[m][k] = *(const bf16x8*)(SA_(shm, b, h) + abase + (m * 2 + k) * 1024)
; #define LDB8(dst, b, h) _Pragma("unroll") for (int n = 0; n < 2; ++n) _Pragma("unroll") for (int k = 0; k < 2; ++k) \
;     dst[n][k] = *(const bf16x8*)(SB_(shm, b, h) + bbase + (n * 2 + k) * 1024)
; template <bool HS>
; __device__ __forceinline__ void gemm_tile8(const u16* __restrict__ Ap, const u16* __restrict__ Bp, int K,
;                                            f32x4 (&acc)[2][2][4][2], char* shm, const int tid, const float* hsr = nullptr) {
;     ...
;   const int nt = K / BK;
;   WAIT_V(0);
;   if (wr == 1) BAR;
;   BAR;
;   BAR;
;   for (int t = 0; t < nt - 2; t += 2) {
;     if constexpr (HS) {
;       if (t > 0 && (t & 7) == 0) {
;         const float* rt = hsr + ((t >> 3) - 1) * 256 + wr * 64 + fq * 4;
; #pragma unroll
;         for (int ai = 0; ai < 2; ++ai)
; #pragma unroll
;           for (int m = 0; m < 4; ++m) {
;             const f32x4 q4 = *(const f32x4*)(rt + ai * 128 + m * 16);
; #pragma unroll
;             for (int bj = 0; bj < 2; ++bj)
; #pragma unroll
;               for (int n = 0; n < 2; ++n) acc[ai][bj][m][n] *= q4;
;             SCHED;
;           }
;       }
;     }
;     LDB8(B0, 0, 0); SCHED; LDA8(0, 0); STG_A(1, 1, t + 1);
;     WAIT_L(8); BAR; WAIT_L(0); MMA8(0, 0, B0); BAR; SCHED;
;     LDB8(B1, 0, 1); STG_B(0, 0, t + 2);
;     BAR; WAIT_L(0); MMA8(0, 1, B1); BAR;
.Lffn_in_kinit:
	v_readfirstlane_b32 s20, v130
	v_readfirstlane_b32 s21, v131
	v_readfirstlane_b32 s22, v132
	v_readfirstlane_b32 s23, v133
	s_mov_b32 s16, s5
	s_mov_b32 s17, s6
	s_mov_b32 s18, s12
	s_mov_b32 s19, s13
	s_barrier
	s_barrier
	v_add_u32_e32 v158, 0x10000, v145
	ds_read_b128 v[146:149], v158
	ds_read_b128 v[150:153], v158 offset:1024
	ds_read_b128 v[154:157], v158 offset:2048
	ds_read_b128 v[158:161], v158 offset:3072
	ds_read_b128 v[162:165], v142
	ds_read_b128 v[166:169], v142 offset:1024
	ds_read_b128 v[170:173], v142 offset:2048
	ds_read_b128 v[174:177], v142 offset:3072
	ds_read_b128 v[180:183], v142 offset:4096
	ds_read_b128 v[184:187], v142 offset:5120
	ds_read_b128 v[188:191], v142 offset:6144
	ds_read_b128 v[192:195], v142 offset:7168
	v_add_u32_e32 v208, 0x14000, v145
	ds_read_b128 v[196:199], v208
	ds_read_b128 v[200:203], v208 offset:1024
	ds_read_b128 v[204:207], v208 offset:2048
	ds_read_b128 v[208:211], v208 offset:3072
	s_add_u32 s0, s18, 0x80
	s_addc_u32 s1, s19, 0
	s_add_i32 s3, s7, 0xc000
	s_mov_b32 m0, s3
	s_nop 0
	global_load_lds_dwordx4 v144, s[0:1]
	s_add_i32 s3, s7, 0xe000
	s_mov_b32 m0, s3
	s_nop 0
	global_load_lds_dwordx4 v143, s[0:1]
	s_waitcnt vmcnt(8) lgkmcnt(0)
	s_barrier
	s_setprio 1
	v_mfma_f32_16x16x32_bf16 v[126:129], v[162:165], v[146:149], 0
	v_mfma_f32_16x16x32_bf16 v[122:125], v[162:165], v[154:157], 0
	v_mfma_f32_16x16x32_bf16 v[118:121], v[170:173], v[146:149], 0
	v_mfma_f32_16x16x32_bf16 v[114:117], v[170:173], v[154:157], 0
	v_mfma_f32_16x16x32_bf16 v[110:113], v[180:183], v[146:149], 0
	v_mfma_f32_16x16x32_bf16 v[106:109], v[180:183], v[154:157], 0
	v_mfma_f32_16x16x32_bf16 v[102:105], v[188:191], v[146:149], 0
	v_mfma_f32_16x16x32_bf16 v[98:101], v[188:191], v[154:157], 0
	v_mfma_f32_16x16x32_bf16 v[126:129], v[166:169], v[150:153], v[126:129]
	v_mfma_f32_16x16x32_bf16 v[122:125], v[166:169], v[158:161], v[122:125]
	v_mfma_f32_16x16x32_bf16 v[118:121], v[174:177], v[150:153], v[118:121]
	v_mfma_f32_16x16x32_bf16 v[114:117], v[174:177], v[158:161], v[114:117]
	v_mfma_f32_16x16x32_bf16 v[110:113], v[184:187], v[150:153], v[110:113]
	v_mfma_f32_16x16x32_bf16 v[106:109], v[184:187], v[158:161], v[106:109]
	v_mfma_f32_16x16x32_bf16 v[102:105], v[192:195], v[150:153], v[102:105]
	v_mfma_f32_16x16x32_bf16 v[98:101], v[192:195], v[158:161], v[98:101]
	v_mfma_f32_16x16x32_bf16 v[94:97], v[162:165], v[196:199], 0
	v_mfma_f32_16x16x32_bf16 v[90:93], v[162:165], v[204:207], 0
	v_mfma_f32_16x16x32_bf16 v[86:89], v[170:173], v[196:199], 0
	v_mfma_f32_16x16x32_bf16 v[82:85], v[170:173], v[204:207], 0
	v_mfma_f32_16x16x32_bf16 v[78:81], v[180:183], v[196:199], 0
	v_mfma_f32_16x16x32_bf16 v[74:77], v[180:183], v[204:207], 0
	v_mfma_f32_16x16x32_bf16 v[70:73], v[188:191], v[196:199], 0
	v_mfma_f32_16x16x32_bf16 v[66:69], v[188:191], v[204:207], 0
	v_mfma_f32_16x16x32_bf16 v[94:97], v[166:169], v[200:203], v[94:97]
	v_mfma_f32_16x16x32_bf16 v[90:93], v[166:169], v[208:211], v[90:93]
	v_mfma_f32_16x16x32_bf16 v[86:89], v[174:177], v[200:203], v[86:89]
	v_mfma_f32_16x16x32_bf16 v[82:85], v[174:177], v[208:211], v[82:85]
	v_mfma_f32_16x16x32_bf16 v[78:81], v[184:187], v[200:203], v[78:81]
	v_mfma_f32_16x16x32_bf16 v[74:77], v[184:187], v[208:211], v[74:77]
	v_mfma_f32_16x16x32_bf16 v[70:73], v[192:195], v[200:203], v[70:73]
	v_mfma_f32_16x16x32_bf16 v[66:69], v[192:195], v[208:211], v[66:69]
	s_setprio 0
	s_barrier
	ds_read_b128 v[162:165], v142 offset:16384
	ds_read_b128 v[166:169], v142 offset:17408
	ds_read_b128 v[170:173], v142 offset:18432
	ds_read_b128 v[174:177], v142 offset:19456
	ds_read_b128 v[180:183], v142 offset:20480
	ds_read_b128 v[184:187], v142 offset:21504
	ds_read_b128 v[188:191], v142 offset:22528
	ds_read_b128 v[192:195], v142 offset:23552
	s_add_u32 s0, s20, 0x100
	s_addc_u32 s1, s21, 0
	s_add_i32 s3, s7, 0x10000
	s_mov_b32 m0, s3
	s_nop 0
	global_load_lds_dwordx4 v144, s[0:1]
	s_add_i32 s3, s7, 0x12000
	s_mov_b32 m0, s3
	s_nop 0
	global_load_lds_dwordx4 v143, s[0:1]
	s_add_u32 s0, s16, 0x100
	s_addc_u32 s1, s17, 0
	s_mov_b32 m0, s7
	s_nop 0
	global_load_lds_dwordx4 v144, s[0:1]
	s_add_i32 s3, s7, 0x2000
	s_mov_b32 m0, s3
	s_nop 0
	global_load_lds_dwordx4 v143, s[0:1]
	s_add_u32 s0, s22, 0x100
	s_addc_u32 s1, s23, 0
	s_add_i32 s3, s7, 0x14000
	s_mov_b32 m0, s3
	s_nop 0
	global_load_lds_dwordx4 v144, s[0:1]
	s_add_i32 s3, s7, 0x16000
	s_mov_b32 m0, s3
	s_nop 0
	global_load_lds_dwordx4 v143, s[0:1]
	s_waitcnt vmcnt(8) lgkmcnt(0)
	s_barrier
	s_setprio 1
	v_mfma_f32_16x16x32_bf16 v[62:65], v[162:165], v[146:149], 0
	v_mfma_f32_16x16x32_bf16 v[58:61], v[162:165], v[154:157], 0
	v_mfma_f32_16x16x32_bf16 v[54:57], v[170:173], v[146:149], 0
	v_mfma_f32_16x16x32_bf16 v[50:53], v[170:173], v[154:157], 0
	v_mfma_f32_16x16x32_bf16 v[46:49], v[180:183], v[146:149], 0
	v_mfma_f32_16x16x32_bf16 v[42:45], v[180:183], v[154:157], 0
	v_mfma_f32_16x16x32_bf16 v[38:41], v[188:191], v[146:149], 0
	v_mfma_f32_16x16x32_bf16 v[34:37], v[188:191], v[154:157], 0
	v_mfma_f32_16x16x32_bf16 v[62:65], v[166:169], v[150:153], v[62:65]
	v_mfma_f32_16x16x32_bf16 v[58:61], v[166:169], v[158:161], v[58:61]
	v_mfma_f32_16x16x32_bf16 v[54:57], v[174:177], v[150:153], v[54:57]
	v_mfma_f32_16x16x32_bf16 v[50:53], v[174:177], v[158:161], v[50:53]
	v_mfma_f32_16x16x32_bf16 v[46:49], v[184:187], v[150:153], v[46:49]
	v_mfma_f32_16x16x32_bf16 v[42:45], v[184:187], v[158:161], v[42:45]
	v_mfma_f32_16x16x32_bf16 v[38:41], v[192:195], v[150:153], v[38:41]
	v_mfma_f32_16x16x32_bf16 v[34:37], v[192:195], v[158:161], v[34:37]
	v_mfma_f32_16x16x32_bf16 v[30:33], v[162:165], v[196:199], 0
	v_mfma_f32_16x16x32_bf16 v[26:29], v[162:165], v[204:207], 0
	v_mfma_f32_16x16x32_bf16 v[22:25], v[170:173], v[196:199], 0
	v_mfma_f32_16x16x32_bf16 v[18:21], v[170:173], v[204:207], 0
	v_mfma_f32_16x16x32_bf16 v[14:17], v[180:183], v[196:199], 0
	v_mfma_f32_16x16x32_bf16 v[10:13], v[180:183], v[204:207], 0
	v_mfma_f32_16x16x32_bf16 v[6:9], v[188:191], v[196:199], 0
	v_mfma_f32_16x16x32_bf16 v[2:5], v[188:191], v[204:207], 0
	v_mfma_f32_16x16x32_bf16 v[30:33], v[166:169], v[200:203], v[30:33]
	v_mfma_f32_16x16x32_bf16 v[26:29], v[166:169], v[208:211], v[26:29]
	v_mfma_f32_16x16x32_bf16 v[22:25], v[174:177], v[200:203], v[22:25]
	v_mfma_f32_16x16x32_bf16 v[18:21], v[174:177], v[208:211], v[18:21]
	v_mfma_f32_16x16x32_bf16 v[14:17], v[184:187], v[200:203], v[14:17]
	v_mfma_f32_16x16x32_bf16 v[10:13], v[184:187], v[208:211], v[10:13]
	v_mfma_f32_16x16x32_bf16 v[6:9], v[192:195], v[200:203], v[6:9]
	v_mfma_f32_16x16x32_bf16 v[2:5], v[192:195], v[208:211], v[2:5]
	s_setprio 0
	s_barrier
; #define WAIT_V(n) asm volatile("s_waitcnt vmcnt(" #n ")" ::: "memory")
; #define WAIT_L(n) asm volatile("s_waitcnt lgkmcnt(" #n ")" ::: "memory")
; #define BAR __builtin_amdgcn_s_barrier()
; #define SCHED __builtin_amdgcn_sched_barrier(0)
; #define STG_A(b, h, kt) stage_half_s(lds0 + ((b) * 2 + (h)) * HT_B, ((h) ? A1 : Ap) + (kt) * BK, off0, off1)
; #define STG_B(b, h, kt) stage_half_s(lds0 + (4 + (b) * 2 + (h)) * HT_B, ((h) ? B1p : Bp) + (kt) * BK, off0, off1)
; #define STG_A(b, h, kt) stage_half_s(lds0 + ((b) * 2 + (h)) * HT_B, ((h) ? A1 : Ap) + (kt) * BK, off0, off1)
; #define STG_B(b, h, kt) stage_half_s(lds0 + (4 + (b) * 2 + (h)) * HT_B, ((h) ? B1p : Bp) + (kt) * BK, off0, off1)
; #define LDA8(b, h) _Pragma("unroll") for (int m = 0; m < 4; ++m) _Pragma("unroll") for (int k = 0; k < 2; ++k) \
;     At[m][k] = *(const bf16x8*)(SA_(shm, b, h) + abase + (m * 2 + k) * 1024)
; #define LDB8(dst, b, h) _Pragma("unroll") for (int n = 0; n < 2; ++n) _Pragma("unroll") for (int k = 0; k < 2; ++k) \
;     dst[n][k] = *(const bf16x8*)(SB_(shm, b, h) + bbase + (n * 2 + k) * 1024)
; #define MMA8(ai, bj, Bx) do { __builtin_amdgcn_s_setprio(1); \
;     _Pragma("unroll") for (int m = 0; m < 4; ++m) _Pragma("unroll") for (int n = 0; n < 2; ++n) _Pragma("unroll") for (int k = 0; k < 2; ++k) \
;       acc[ai][bj][m][n] = __builtin_amdgcn_mfma_f32_16x16x32_bf16(At[m][k], Bx[n][k], acc[ai][bj][m][n], 0, 0, 0); \
;     __builtin_amdgcn_s_setprio(0); } while (0)
; template <bool HS>
; __device__ __forceinline__ void gemm_tile8(const u16* __restrict__ Ap, const u16* __restrict__ Bp, int K,
;                                            f32x4 (&acc)[2][2][4][2], char* shm, const int tid, const float* hsr = nullptr) {
;     ...
;     LDA8(0, 1); STG_A(0, 0, t + 2);
;     BAR; WAIT_L(0); MMA8(1, 0, B0); BAR; SCHED;
;     STG_B(0, 1, t + 2);
;     WAIT_V(6); BAR; MMA8(1, 1, B1); BAR;
;     LDB8(B0, 1, 0); SCHED; LDA8(1, 0); STG_A(0, 1, t + 2);
;     WAIT_L(8); BAR; WAIT_L(0); MMA8(0, 0, B0); BAR; SCHED;
;     LDB8(B1, 1, 1); STG_B(1, 0, t + 3);
;     BAR; WAIT_L(0); MMA8(0, 1, B1); BAR;
;     LDA8(1, 1); STG_A(1, 0, t + 3);
;     BAR; WAIT_L(0); MMA8(1, 0, B0); BAR; SCHED;
;     STG_B(1, 1, t + 3);
;     WAIT_V(6); BAR; MMA8(1, 1, B1); BAR;
;   }
	v_add_u32_e32 v158, 0x18000, v145
	ds_read_b128 v[146:149], v158
	ds_read_b128 v[150:153], v158 offset:1024
	ds_read_b128 v[154:157], v158 offset:2048
	ds_read_b128 v[158:161], v158 offset:3072
	ds_read_b128 v[162:165], v142 offset:32768
	ds_read_b128 v[166:169], v142 offset:33792
	ds_read_b128 v[170:173], v142 offset:34816
	ds_read_b128 v[174:177], v142 offset:35840
	ds_read_b128 v[180:183], v142 offset:36864
	ds_read_b128 v[184:187], v142 offset:37888
	ds_read_b128 v[188:191], v142 offset:38912
	ds_read_b128 v[192:195], v142 offset:39936
	v_add_u32_e32 v208, 0x1c000, v145
	ds_read_b128 v[196:199], v208
	ds_read_b128 v[200:203], v208 offset:1024
	ds_read_b128 v[204:207], v208 offset:2048
	ds_read_b128 v[208:211], v208 offset:3072
	s_add_u32 s0, s18, 0x100
	s_addc_u32 s1, s19, 0
	s_add_i32 s3, s7, 0x4000
	s_mov_b32 m0, s3
	s_nop 0
	global_load_lds_dwordx4 v144, s[0:1]
	s_add_i32 s3, s7, 0x6000
	s_mov_b32 m0, s3
	s_nop 0
	global_load_lds_dwordx4 v143, s[0:1]
	s_waitcnt vmcnt(8) lgkmcnt(0)
	s_barrier
	s_setprio 1
	v_mfma_f32_16x16x32_bf16 v[126:129], v[162:165], v[146:149], v[126:129]
	v_mfma_f32_16x16x32_bf16 v[122:125], v[162:165], v[154:157], v[122:125]
	v_mfma_f32_16x16x32_bf16 v[118:121], v[170:173], v[146:149], v[118:121]
	v_mfma_f32_16x16x32_bf16 v[114:117], v[170:173], v[154:157], v[114:117]
	v_mfma_f32_16x16x32_bf16 v[110:113], v[180:183], v[146:149], v[110:113]
	v_mfma_f32_16x16x32_bf16 v[106:109], v[180:183], v[154:157], v[106:109]
	v_mfma_f32_16x16x32_bf16 v[102:105], v[188:191], v[146:149], v[102:105]
	v_mfma_f32_16x16x32_bf16 v[98:101], v[188:191], v[154:157], v[98:101]
	v_mfma_f32_16x16x32_bf16 v[126:129], v[166:169], v[150:153], v[126:129]
	v_mfma_f32_16x16x32_bf16 v[122:125], v[166:169], v[158:161], v[122:125]
	v_mfma_f32_16x16x32_bf16 v[118:121], v[174:177], v[150:153], v[118:121]
	v_mfma_f32_16x16x32_bf16 v[114:117], v[174:177], v[158:161], v[114:117]
	v_mfma_f32_16x16x32_bf16 v[110:113], v[184:187], v[150:153], v[110:113]
	v_mfma_f32_16x16x32_bf16 v[106:109], v[184:187], v[158:161], v[106:109]
	v_mfma_f32_16x16x32_bf16 v[102:105], v[192:195], v[150:153], v[102:105]
	v_mfma_f32_16x16x32_bf16 v[98:101], v[192:195], v[158:161], v[98:101]
	v_mfma_f32_16x16x32_bf16 v[94:97], v[162:165], v[196:199], v[94:97]
	v_mfma_f32_16x16x32_bf16 v[90:93], v[162:165], v[204:207], v[90:93]
	v_mfma_f32_16x16x32_bf16 v[86:89], v[170:173], v[196:199], v[86:89]
	v_mfma_f32_16x16x32_bf16 v[82:85], v[170:173], v[204:207], v[82:85]
	v_mfma_f32_16x16x32_bf16 v[78:81], v[180:183], v[196:199], v[78:81]
	v_mfma_f32_16x16x32_bf16 v[74:77], v[180:183], v[204:207], v[74:77]
	v_mfma_f32_16x16x32_bf16 v[70:73], v[188:191], v[196:199], v[70:73]
	v_mfma_f32_16x16x32_bf16 v[66:69], v[188:191], v[204:207], v[66:69]
	v_mfma_f32_16x16x32_bf16 v[94:97], v[166:169], v[200:203], v[94:97]
	v_mfma_f32_16x16x32_bf16 v[90:93], v[166:169], v[208:211], v[90:93]
	v_mfma_f32_16x16x32_bf16 v[86:89], v[174:177], v[200:203], v[86:89]
	v_mfma_f32_16x16x32_bf16 v[82:85], v[174:177], v[208:211], v[82:85]
	v_mfma_f32_16x16x32_bf16 v[78:81], v[184:187], v[200:203], v[78:81]
	v_mfma_f32_16x16x32_bf16 v[74:77], v[184:187], v[208:211], v[74:77]
	v_mfma_f32_16x16x32_bf16 v[70:73], v[192:195], v[200:203], v[70:73]
	v_mfma_f32_16x16x32_bf16 v[66:69], v[192:195], v[208:211], v[66:69]
	s_setprio 0
	s_barrier
	ds_read_b128 v[162:165], v142 offset:49152
	ds_read_b128 v[166:169], v142 offset:50176
	ds_read_b128 v[170:173], v142 offset:51200
	ds_read_b128 v[174:177], v142 offset:52224
	ds_read_b128 v[180:183], v142 offset:53248
	ds_read_b128 v[184:187], v142 offset:54272
	ds_read_b128 v[188:191], v142 offset:55296
	ds_read_b128 v[192:195], v142 offset:56320
	s_add_u32 s0, s20, 0x180
	s_addc_u32 s1, s21, 0
	s_add_i32 s3, s7, 0x18000
	s_mov_b32 m0, s3
	s_nop 0
	global_load_lds_dwordx4 v144, s[0:1]
	s_add_i32 s3, s7, 0x1a000
	s_mov_b32 m0, s3
	s_nop 0
	global_load_lds_dwordx4 v143, s[0:1]
	s_add_u32 s0, s16, 0x180
	s_addc_u32 s1, s17, 0
	s_add_i32 s3, s7, 0x8000
	s_mov_b32 m0, s3
	s_nop 0
	global_load_lds_dwordx4 v144, s[0:1]
	s_add_i32 s3, s7, 0xa000
	s_mov_b32 m0, s3
	s_nop 0
	global_load_lds_dwordx4 v143, s[0:1]
	s_add_u32 s0, s22, 0x180
	s_addc_u32 s1, s23, 0
	s_add_i32 s3, s7, 0x1c000
	s_mov_b32 m0, s3
	s_nop 0
	global_load_lds_dwordx4 v144, s[0:1]
	s_add_i32 s3, s7, 0x1e000
	s_mov_b32 m0, s3
	s_nop 0
	global_load_lds_dwordx4 v143, s[0:1]
	s_waitcnt vmcnt(8) lgkmcnt(0)
	s_barrier
	s_setprio 1
	v_mfma_f32_16x16x32_bf16 v[62:65], v[162:165], v[146:149], v[62:65]
	v_mfma_f32_16x16x32_bf16 v[58:61], v[162:165], v[154:157], v[58:61]
	v_mfma_f32_16x16x32_bf16 v[54:57], v[170:173], v[146:149], v[54:57]
	v_mfma_f32_16x16x32_bf16 v[50:53], v[170:173], v[154:157], v[50:53]
	v_mfma_f32_16x16x32_bf16 v[46:49], v[180:183], v[146:149], v[46:49]
	v_mfma_f32_16x16x32_bf16 v[42:45], v[180:183], v[154:157], v[42:45]
	v_mfma_f32_16x16x32_bf16 v[38:41], v[188:191], v[146:149], v[38:41]
	v_mfma_f32_16x16x32_bf16 v[34:37], v[188:191], v[154:157], v[34:37]
	v_mfma_f32_16x16x32_bf16 v[62:65], v[166:169], v[150:153], v[62:65]
	v_mfma_f32_16x16x32_bf16 v[58:61], v[166:169], v[158:161], v[58:61]
	v_mfma_f32_16x16x32_bf16 v[54:57], v[174:177], v[150:153], v[54:57]
	v_mfma_f32_16x16x32_bf16 v[50:53], v[174:177], v[158:161], v[50:53]
	v_mfma_f32_16x16x32_bf16 v[46:49], v[184:187], v[150:153], v[46:49]
	v_mfma_f32_16x16x32_bf16 v[42:45], v[184:187], v[158:161], v[42:45]
	v_mfma_f32_16x16x32_bf16 v[38:41], v[192:195], v[150:153], v[38:41]
	v_mfma_f32_16x16x32_bf16 v[34:37], v[192:195], v[158:161], v[34:37]
	v_mfma_f32_16x16x32_bf16 v[30:33], v[162:165], v[196:199], v[30:33]
	v_mfma_f32_16x16x32_bf16 v[26:29], v[162:165], v[204:207], v[26:29]
	v_mfma_f32_16x16x32_bf16 v[22:25], v[170:173], v[196:199], v[22:25]
	v_mfma_f32_16x16x32_bf16 v[18:21], v[170:173], v[204:207], v[18:21]
	v_mfma_f32_16x16x32_bf16 v[14:17], v[180:183], v[196:199], v[14:17]
	v_mfma_f32_16x16x32_bf16 v[10:13], v[180:183], v[204:207], v[10:13]
	v_mfma_f32_16x16x32_bf16 v[6:9], v[188:191], v[196:199], v[6:9]
	v_mfma_f32_16x16x32_bf16 v[2:5], v[188:191], v[204:207], v[2:5]
	v_mfma_f32_16x16x32_bf16 v[30:33], v[166:169], v[200:203], v[30:33]
	v_mfma_f32_16x16x32_bf16 v[26:29], v[166:169], v[208:211], v[26:29]
	v_mfma_f32_16x16x32_bf16 v[22:25], v[174:177], v[200:203], v[22:25]
	v_mfma_f32_16x16x32_bf16 v[18:21], v[174:177], v[208:211], v[18:21]
	v_mfma_f32_16x16x32_bf16 v[14:17], v[184:187], v[200:203], v[14:17]
	v_mfma_f32_16x16x32_bf16 v[10:13], v[184:187], v[208:211], v[10:13]
	v_mfma_f32_16x16x32_bf16 v[6:9], v[192:195], v[200:203], v[6:9]
	v_mfma_f32_16x16x32_bf16 v[2:5], v[192:195], v[208:211], v[2:5]
	s_setprio 0
	s_barrier
	s_add_u32 s16, s16, 0x100
	s_addc_u32 s17, s17, 0
	s_add_u32 s18, s18, 0x100
	s_addc_u32 s19, s19, 0
	s_add_u32 s20, s20, 0x100
	s_addc_u32 s21, s21, 0
	s_add_u32 s22, s22, 0x100
	s_addc_u32 s23, s23, 0
	s_mov_b32 s14, 6
; #define WAIT_V(n) asm volatile("s_waitcnt vmcnt(" #n ")" ::: "memory")
; #define WAIT_L(n) asm volatile("s_waitcnt lgkmcnt(" #n ")" ::: "memory")
; #define BAR __builtin_amdgcn_s_barrier()
; #define SCHED __builtin_amdgcn_sched_barrier(0)
; #define STG_A(b, h, kt) stage_half_s(lds0 + ((b) * 2 + (h)) * HT_B, ((h) ? A1 : Ap) + (kt) * BK, off0, off1)
; #define STG_B(b, h, kt) stage_half_s(lds0 + (4 + (b) * 2 + (h)) * HT_B, ((h) ? B1p : Bp) + (kt) * BK, off0, off1)
; #define STG_A(b, h, kt) stage_half_s(lds0 + ((b) * 2 + (h)) * HT_B, ((h) ? A1 : Ap) + (kt) * BK, off0, off1)
; #define STG_B(b, h, kt) stage_half_s(lds0 + (4 + (b) * 2 + (h)) * HT_B, ((h) ? B1p : Bp) + (kt) * BK, off0, off1)
; #define LDA8(b, h) _Pragma("unroll") for (int m = 0; m < 4; ++m) _Pragma("unroll") for (int k = 0; k < 2; ++k) \
;     At[m][k] = *(const bf16x8*)(SA_(shm, b, h) + abase + (m * 2 + k) * 1024)
; #define LDB8(dst, b, h) _Pragma("unroll") for (int n = 0; n < 2; ++n) _Pragma("unroll") for (int k = 0; k < 2; ++k) \
;     dst[n][k] = *(const bf16x8*)(SB_(shm, b, h) + bbase + (n * 2 + k) * 1024)
; #define MMA8(ai, bj, Bx) do { __builtin_amdgcn_s_setprio(1); \
;     _Pragma("unroll") for (int m = 0; m < 4; ++m) _Pragma("unroll") for (int n = 0; n < 2; ++n) _Pragma("unroll") for (int k = 0; k < 2; ++k) \
;       acc[ai][bj][m][n] = __builtin_amdgcn_mfma_f32_16x16x32_bf16(At[m][k], Bx[n][k], acc[ai][bj][m][n], 0, 0, 0); \
;     __builtin_amdgcn_s_setprio(0); } while (0)
; template <bool HS>
; __device__ __forceinline__ void gemm_tile8(const u16* __restrict__ Ap, const u16* __restrict__ Bp, int K,
;                                            f32x4 (&acc)[2][2][4][2], char* shm, const int tid, const float* hsr = nullptr) {
;     ...
;     LDB8(B0, 0, 0); SCHED; LDA8(0, 0); STG_A(1, 1, t + 1);
;     WAIT_L(8); BAR; WAIT_L(0); MMA8(0, 0, B0); BAR; SCHED;
;     LDB8(B1, 0, 1); STG_B(0, 0, t + 2);
;     BAR; WAIT_L(0); MMA8(0, 1, B1); BAR;
;     LDA8(0, 1); STG_A(0, 0, t + 2);
;     BAR; WAIT_L(0); MMA8(1, 0, B0); BAR; SCHED;
;     STG_B(0, 1, t + 2);
;     WAIT_V(6); BAR; MMA8(1, 1, B1); BAR;
.Lk_ffn_in:
	v_add_u32_e32 v158, 0x10000, v145
	ds_read_b128 v[146:149], v158
	ds_read_b128 v[150:153], v158 offset:1024
	ds_read_b128 v[154:157], v158 offset:2048
	ds_read_b128 v[158:161], v158 offset:3072
	ds_read_b128 v[162:165], v142
	ds_read_b128 v[166:169], v142 offset:1024
	ds_read_b128 v[170:173], v142 offset:2048
	ds_read_b128 v[174:177], v142 offset:3072
	ds_read_b128 v[180:183], v142 offset:4096
	ds_read_b128 v[184:187], v142 offset:5120
	ds_read_b128 v[188:191], v142 offset:6144
	ds_read_b128 v[192:195], v142 offset:7168
	v_add_u32_e32 v208, 0x14000, v145
	ds_read_b128 v[196:199], v208
	ds_read_b128 v[200:203], v208 offset:1024
	ds_read_b128 v[204:207], v208 offset:2048
	ds_read_b128 v[208:211], v208 offset:3072
	s_add_u32 s0, s18, 0x80
	s_addc_u32 s1, s19, 0
	s_add_i32 s3, s7, 0xc000
	s_mov_b32 m0, s3
	s_nop 0
	global_load_lds_dwordx4 v144, s[0:1]
	s_add_i32 s3, s7, 0xe000
	s_mov_b32 m0, s3
	s_nop 0
	global_load_lds_dwordx4 v143, s[0:1]
	s_waitcnt vmcnt(8) lgkmcnt(0)
	s_barrier
	s_setprio 1
	v_mfma_f32_16x16x32_bf16 v[126:129], v[162:165], v[146:149], v[126:129]
	v_mfma_f32_16x16x32_bf16 v[122:125], v[162:165], v[154:157], v[122:125]
	v_mfma_f32_16x16x32_bf16 v[118:121], v[170:173], v[146:149], v[118:121]
	v_mfma_f32_16x16x32_bf16 v[114:117], v[170:173], v[154:157], v[114:117]
	v_mfma_f32_16x16x32_bf16 v[110:113], v[180:183], v[146:149], v[110:113]
	v_mfma_f32_16x16x32_bf16 v[106:109], v[180:183], v[154:157], v[106:109]
	v_mfma_f32_16x16x32_bf16 v[102:105], v[188:191], v[146:149], v[102:105]
	v_mfma_f32_16x16x32_bf16 v[98:101], v[188:191], v[154:157], v[98:101]
	v_mfma_f32_16x16x32_bf16 v[126:129], v[166:169], v[150:153], v[126:129]
	v_mfma_f32_16x16x32_bf16 v[122:125], v[166:169], v[158:161], v[122:125]
	v_mfma_f32_16x16x32_bf16 v[118:121], v[174:177], v[150:153], v[118:121]
	v_mfma_f32_16x16x32_bf16 v[114:117], v[174:177], v[158:161], v[114:117]
	v_mfma_f32_16x16x32_bf16 v[110:113], v[184:187], v[150:153], v[110:113]
	v_mfma_f32_16x16x32_bf16 v[106:109], v[184:187], v[158:161], v[106:109]
	v_mfma_f32_16x16x32_bf16 v[102:105], v[192:195], v[150:153], v[102:105]
	v_mfma_f32_16x16x32_bf16 v[98:101], v[192:195], v[158:161], v[98:101]
	v_mfma_f32_16x16x32_bf16 v[94:97], v[162:165], v[196:199], v[94:97]
	v_mfma_f32_16x16x32_bf16 v[90:93], v[162:165], v[204:207], v[90:93]
	v_mfma_f32_16x16x32_bf16 v[86:89], v[170:173], v[196:199], v[86:89]
	v_mfma_f32_16x16x32_bf16 v[82:85], v[170:173], v[204:207], v[82:85]
	v_mfma_f32_16x16x32_bf16 v[78:81], v[180:183], v[196:199], v[78:81]
	v_mfma_f32_16x16x32_bf16 v[74:77], v[180:183], v[204:207], v[74:77]
	v_mfma_f32_16x16x32_bf16 v[70:73], v[188:191], v[196:199], v[70:73]
	v_mfma_f32_16x16x32_bf16 v[66:69], v[188:191], v[204:207], v[66:69]
	v_mfma_f32_16x16x32_bf16 v[94:97], v[166:169], v[200:203], v[94:97]
	v_mfma_f32_16x16x32_bf16 v[90:93], v[166:169], v[208:211], v[90:93]
	v_mfma_f32_16x16x32_bf16 v[86:89], v[174:177], v[200:203], v[86:89]
	v_mfma_f32_16x16x32_bf16 v[82:85], v[174:177], v[208:211], v[82:85]
	v_mfma_f32_16x16x32_bf16 v[78:81], v[184:187], v[200:203], v[78:81]
	v_mfma_f32_16x16x32_bf16 v[74:77], v[184:187], v[208:211], v[74:77]
	v_mfma_f32_16x16x32_bf16 v[70:73], v[192:195], v[200:203], v[70:73]
	v_mfma_f32_16x16x32_bf16 v[66:69], v[192:195], v[208:211], v[66:69]
	s_setprio 0
	s_barrier
	ds_read_b128 v[162:165], v142 offset:16384
	ds_read_b128 v[166:169], v142 offset:17408
	ds_read_b128 v[170:173], v142 offset:18432
	ds_read_b128 v[174:177], v142 offset:19456
	ds_read_b128 v[180:183], v142 offset:20480
	ds_read_b128 v[184:187], v142 offset:21504
	ds_read_b128 v[188:191], v142 offset:22528
	ds_read_b128 v[192:195], v142 offset:23552
	s_add_u32 s0, s20, 0x100
	s_addc_u32 s1, s21, 0
	s_add_i32 s3, s7, 0x10000
	s_mov_b32 m0, s3
	s_nop 0
	global_load_lds_dwordx4 v144, s[0:1]
	s_add_i32 s3, s7, 0x12000
	s_mov_b32 m0, s3
	s_nop 0
	global_load_lds_dwordx4 v143, s[0:1]
	s_add_u32 s0, s16, 0x100
	s_addc_u32 s1, s17, 0
	s_mov_b32 m0, s7
	s_nop 0
	global_load_lds_dwordx4 v144, s[0:1]
	s_add_i32 s3, s7, 0x2000
	s_mov_b32 m0, s3
	s_nop 0
	global_load_lds_dwordx4 v143, s[0:1]
	s_add_u32 s0, s22, 0x100
	s_addc_u32 s1, s23, 0
	s_add_i32 s3, s7, 0x14000
	s_mov_b32 m0, s3
	s_nop 0
	global_load_lds_dwordx4 v144, s[0:1]
	s_add_i32 s3, s7, 0x16000
	s_mov_b32 m0, s3
	s_nop 0
	global_load_lds_dwordx4 v143, s[0:1]
	s_waitcnt vmcnt(8) lgkmcnt(0)
	s_barrier
	s_setprio 1
	v_mfma_f32_16x16x32_bf16 v[62:65], v[162:165], v[146:149], v[62:65]
	v_mfma_f32_16x16x32_bf16 v[58:61], v[162:165], v[154:157], v[58:61]
	v_mfma_f32_16x16x32_bf16 v[54:57], v[170:173], v[146:149], v[54:57]
	v_mfma_f32_16x16x32_bf16 v[50:53], v[170:173], v[154:157], v[50:53]
	v_mfma_f32_16x16x32_bf16 v[46:49], v[180:183], v[146:149], v[46:49]
	v_mfma_f32_16x16x32_bf16 v[42:45], v[180:183], v[154:157], v[42:45]
	v_mfma_f32_16x16x32_bf16 v[38:41], v[188:191], v[146:149], v[38:41]
	v_mfma_f32_16x16x32_bf16 v[34:37], v[188:191], v[154:157], v[34:37]
	v_mfma_f32_16x16x32_bf16 v[62:65], v[166:169], v[150:153], v[62:65]
	v_mfma_f32_16x16x32_bf16 v[58:61], v[166:169], v[158:161], v[58:61]
	v_mfma_f32_16x16x32_bf16 v[54:57], v[174:177], v[150:153], v[54:57]
	v_mfma_f32_16x16x32_bf16 v[50:53], v[174:177], v[158:161], v[50:53]
	v_mfma_f32_16x16x32_bf16 v[46:49], v[184:187], v[150:153], v[46:49]
	v_mfma_f32_16x16x32_bf16 v[42:45], v[184:187], v[158:161], v[42:45]
	v_mfma_f32_16x16x32_bf16 v[38:41], v[192:195], v[150:153], v[38:41]
	v_mfma_f32_16x16x32_bf16 v[34:37], v[192:195], v[158:161], v[34:37]
	v_mfma_f32_16x16x32_bf16 v[30:33], v[162:165], v[196:199], v[30:33]
	v_mfma_f32_16x16x32_bf16 v[26:29], v[162:165], v[204:207], v[26:29]
	v_mfma_f32_16x16x32_bf16 v[22:25], v[170:173], v[196:199], v[22:25]
	v_mfma_f32_16x16x32_bf16 v[18:21], v[170:173], v[204:207], v[18:21]
	v_mfma_f32_16x16x32_bf16 v[14:17], v[180:183], v[196:199], v[14:17]
	v_mfma_f32_16x16x32_bf16 v[10:13], v[180:183], v[204:207], v[10:13]
	v_mfma_f32_16x16x32_bf16 v[6:9], v[188:191], v[196:199], v[6:9]
	v_mfma_f32_16x16x32_bf16 v[2:5], v[188:191], v[204:207], v[2:5]
	v_mfma_f32_16x16x32_bf16 v[30:33], v[166:169], v[200:203], v[30:33]
	v_mfma_f32_16x16x32_bf16 v[26:29], v[166:169], v[208:211], v[26:29]
	v_mfma_f32_16x16x32_bf16 v[22:25], v[174:177], v[200:203], v[22:25]
	v_mfma_f32_16x16x32_bf16 v[18:21], v[174:177], v[208:211], v[18:21]
	v_mfma_f32_16x16x32_bf16 v[14:17], v[184:187], v[200:203], v[14:17]
	v_mfma_f32_16x16x32_bf16 v[10:13], v[184:187], v[208:211], v[10:13]
	v_mfma_f32_16x16x32_bf16 v[6:9], v[192:195], v[200:203], v[6:9]
	v_mfma_f32_16x16x32_bf16 v[2:5], v[192:195], v[208:211], v[2:5]
	s_setprio 0
	s_barrier
; #define WAIT_V(n) asm volatile("s_waitcnt vmcnt(" #n ")" ::: "memory")
; #define WAIT_L(n) asm volatile("s_waitcnt lgkmcnt(" #n ")" ::: "memory")
; #define BAR __builtin_amdgcn_s_barrier()
; #define SCHED __builtin_amdgcn_sched_barrier(0)
; #define STG_A(b, h, kt) stage_half_s(lds0 + ((b) * 2 + (h)) * HT_B, ((h) ? A1 : Ap) + (kt) * BK, off0, off1)
; #define STG_B(b, h, kt) stage_half_s(lds0 + (4 + (b) * 2 + (h)) * HT_B, ((h) ? B1p : Bp) + (kt) * BK, off0, off1)
; #define STG_A(b, h, kt) stage_half_s(lds0 + ((b) * 2 + (h)) * HT_B, ((h) ? A1 : Ap) + (kt) * BK, off0, off1)
; #define STG_B(b, h, kt) stage_half_s(lds0 + (4 + (b) * 2 + (h)) * HT_B, ((h) ? B1p : Bp) + (kt) * BK, off0, off1)
; #define LDA8(b, h) _Pragma("unroll") for (int m = 0; m < 4; ++m) _Pragma("unroll") for (int k = 0; k < 2; ++k) \
;     At[m][k] = *(const bf16x8*)(SA_(shm, b, h) + abase + (m * 2 + k) * 1024)
; #define LDB8(dst, b, h) _Pragma("unroll") for (int n = 0; n < 2; ++n) _Pragma("unroll") for (int k = 0; k < 2; ++k) \
;     dst[n][k] = *(const bf16x8*)(SB_(shm, b, h) + bbase + (n * 2 + k) * 1024)
; #define MMA8(ai, bj, Bx) do { __builtin_amdgcn_s_setprio(1); \
;     _Pragma("unroll") for (int m = 0; m < 4; ++m) _Pragma("unroll") for (int n = 0; n < 2; ++n) _Pragma("unroll") for (int k = 0; k < 2; ++k) \
;       acc[ai][bj][m][n] = __builtin_amdgcn_mfma_f32_16x16x32_bf16(At[m][k], Bx[n][k], acc[ai][bj][m][n], 0, 0, 0); \
;     __builtin_amdgcn_s_setprio(0); } while (0)
; template <bool HS>
; __device__ __forceinline__ void gemm_tile8(const u16* __restrict__ Ap, const u16* __restrict__ Bp, int K,
;                                            f32x4 (&acc)[2][2][4][2], char* shm, const int tid, const float* hsr = nullptr) {
;     ...
;     LDB8(B0, 1, 0); SCHED; LDA8(1, 0); STG_A(0, 1, t + 2);
;     WAIT_L(8); BAR; WAIT_L(0); MMA8(0, 0, B0); BAR; SCHED;
;     LDB8(B1, 1, 1); STG_B(1, 0, t + 3);
;     BAR; WAIT_L(0); MMA8(0, 1, B1); BAR;
;     LDA8(1, 1); STG_A(1, 0, t + 3);
;     BAR; WAIT_L(0); MMA8(1, 0, B0); BAR; SCHED;
;     STG_B(1, 1, t + 3);
;     WAIT_V(6); BAR; MMA8(1, 1, B1); BAR;
	v_add_u32_e32 v158, 0x18000, v145
	ds_read_b128 v[146:149], v158
	ds_read_b128 v[150:153], v158 offset:1024
	ds_read_b128 v[154:157], v158 offset:2048
	ds_read_b128 v[158:161], v158 offset:3072
	ds_read_b128 v[162:165], v142 offset:32768
	ds_read_b128 v[166:169], v142 offset:33792
	ds_read_b128 v[170:173], v142 offset:34816
	ds_read_b128 v[174:177], v142 offset:35840
	ds_read_b128 v[180:183], v142 offset:36864
	ds_read_b128 v[184:187], v142 offset:37888
	ds_read_b128 v[188:191], v142 offset:38912
	ds_read_b128 v[192:195], v142 offset:39936
	v_add_u32_e32 v208, 0x1c000, v145
	ds_read_b128 v[196:199], v208
	ds_read_b128 v[200:203], v208 offset:1024
	ds_read_b128 v[204:207], v208 offset:2048
	ds_read_b128 v[208:211], v208 offset:3072
	s_add_u32 s0, s18, 0x100
	s_addc_u32 s1, s19, 0
	s_add_i32 s3, s7, 0x4000
	s_mov_b32 m0, s3
	s_nop 0
	global_load_lds_dwordx4 v144, s[0:1]
	s_add_i32 s3, s7, 0x6000
	s_mov_b32 m0, s3
	s_nop 0
	global_load_lds_dwordx4 v143, s[0:1]
	s_waitcnt vmcnt(8) lgkmcnt(0)
	s_barrier
	s_setprio 1
	v_mfma_f32_16x16x32_bf16 v[126:129], v[162:165], v[146:149], v[126:129]
	v_mfma_f32_16x16x32_bf16 v[122:125], v[162:165], v[154:157], v[122:125]
	v_mfma_f32_16x16x32_bf16 v[118:121], v[170:173], v[146:149], v[118:121]
	v_mfma_f32_16x16x32_bf16 v[114:117], v[170:173], v[154:157], v[114:117]
	v_mfma_f32_16x16x32_bf16 v[110:113], v[180:183], v[146:149], v[110:113]
	v_mfma_f32_16x16x32_bf16 v[106:109], v[180:183], v[154:157], v[106:109]
	v_mfma_f32_16x16x32_bf16 v[102:105], v[188:191], v[146:149], v[102:105]
	v_mfma_f32_16x16x32_bf16 v[98:101], v[188:191], v[154:157], v[98:101]
	v_mfma_f32_16x16x32_bf16 v[126:129], v[166:169], v[150:153], v[126:129]
	v_mfma_f32_16x16x32_bf16 v[122:125], v[166:169], v[158:161], v[122:125]
	v_mfma_f32_16x16x32_bf16 v[118:121], v[174:177], v[150:153], v[118:121]
	v_mfma_f32_16x16x32_bf16 v[114:117], v[174:177], v[158:161], v[114:117]
	v_mfma_f32_16x16x32_bf16 v[110:113], v[184:187], v[150:153], v[110:113]
	v_mfma_f32_16x16x32_bf16 v[106:109], v[184:187], v[158:161], v[106:109]
	v_mfma_f32_16x16x32_bf16 v[102:105], v[192:195], v[150:153], v[102:105]
	v_mfma_f32_16x16x32_bf16 v[98:101], v[192:195], v[158:161], v[98:101]
	v_mfma_f32_16x16x32_bf16 v[94:97], v[162:165], v[196:199], v[94:97]
	v_mfma_f32_16x16x32_bf16 v[90:93], v[162:165], v[204:207], v[90:93]
	v_mfma_f32_16x16x32_bf16 v[86:89], v[170:173], v[196:199], v[86:89]
	v_mfma_f32_16x16x32_bf16 v[82:85], v[170:173], v[204:207], v[82:85]
	v_mfma_f32_16x16x32_bf16 v[78:81], v[180:183], v[196:199], v[78:81]
	v_mfma_f32_16x16x32_bf16 v[74:77], v[180:183], v[204:207], v[74:77]
	v_mfma_f32_16x16x32_bf16 v[70:73], v[188:191], v[196:199], v[70:73]
	v_mfma_f32_16x16x32_bf16 v[66:69], v[188:191], v[204:207], v[66:69]
	v_mfma_f32_16x16x32_bf16 v[94:97], v[166:169], v[200:203], v[94:97]
	v_mfma_f32_16x16x32_bf16 v[90:93], v[166:169], v[208:211], v[90:93]
	v_mfma_f32_16x16x32_bf16 v[86:89], v[174:177], v[200:203], v[86:89]
	v_mfma_f32_16x16x32_bf16 v[82:85], v[174:177], v[208:211], v[82:85]
	v_mfma_f32_16x16x32_bf16 v[78:81], v[184:187], v[200:203], v[78:81]
	v_mfma_f32_16x16x32_bf16 v[74:77], v[184:187], v[208:211], v[74:77]
	v_mfma_f32_16x16x32_bf16 v[70:73], v[192:195], v[200:203], v[70:73]
	v_mfma_f32_16x16x32_bf16 v[66:69], v[192:195], v[208:211], v[66:69]
	s_setprio 0
	s_barrier
	ds_read_b128 v[162:165], v142 offset:49152
	ds_read_b128 v[166:169], v142 offset:50176
	ds_read_b128 v[170:173], v142 offset:51200
	ds_read_b128 v[174:177], v142 offset:52224
	ds_read_b128 v[180:183], v142 offset:53248
	ds_read_b128 v[184:187], v142 offset:54272
	ds_read_b128 v[188:191], v142 offset:55296
	ds_read_b128 v[192:195], v142 offset:56320
	s_add_u32 s0, s20, 0x180
	s_addc_u32 s1, s21, 0
	s_add_i32 s3, s7, 0x18000
	s_mov_b32 m0, s3
	s_nop 0
	global_load_lds_dwordx4 v144, s[0:1]
	s_add_i32 s3, s7, 0x1a000
	s_mov_b32 m0, s3
	s_nop 0
	global_load_lds_dwordx4 v143, s[0:1]
	s_add_u32 s0, s16, 0x180
	s_addc_u32 s1, s17, 0
	s_add_i32 s3, s7, 0x8000
	s_mov_b32 m0, s3
	s_nop 0
	global_load_lds_dwordx4 v144, s[0:1]
	s_add_i32 s3, s7, 0xa000
	s_mov_b32 m0, s3
	s_nop 0
	global_load_lds_dwordx4 v143, s[0:1]
	s_add_u32 s0, s22, 0x180
	s_addc_u32 s1, s23, 0
	s_add_i32 s3, s7, 0x1c000
	s_mov_b32 m0, s3
	s_nop 0
	global_load_lds_dwordx4 v144, s[0:1]
	s_add_i32 s3, s7, 0x1e000
	s_mov_b32 m0, s3
	s_nop 0
	global_load_lds_dwordx4 v143, s[0:1]
	s_waitcnt vmcnt(8) lgkmcnt(0)
	s_barrier
	s_setprio 1
	v_mfma_f32_16x16x32_bf16 v[62:65], v[162:165], v[146:149], v[62:65]
	v_mfma_f32_16x16x32_bf16 v[58:61], v[162:165], v[154:157], v[58:61]
	v_mfma_f32_16x16x32_bf16 v[54:57], v[170:173], v[146:149], v[54:57]
	v_mfma_f32_16x16x32_bf16 v[50:53], v[170:173], v[154:157], v[50:53]
	v_mfma_f32_16x16x32_bf16 v[46:49], v[180:183], v[146:149], v[46:49]
	v_mfma_f32_16x16x32_bf16 v[42:45], v[180:183], v[154:157], v[42:45]
	v_mfma_f32_16x16x32_bf16 v[38:41], v[188:191], v[146:149], v[38:41]
	v_mfma_f32_16x16x32_bf16 v[34:37], v[188:191], v[154:157], v[34:37]
	v_mfma_f32_16x16x32_bf16 v[62:65], v[166:169], v[150:153], v[62:65]
	v_mfma_f32_16x16x32_bf16 v[58:61], v[166:169], v[158:161], v[58:61]
	v_mfma_f32_16x16x32_bf16 v[54:57], v[174:177], v[150:153], v[54:57]
	v_mfma_f32_16x16x32_bf16 v[50:53], v[174:177], v[158:161], v[50:53]
	v_mfma_f32_16x16x32_bf16 v[46:49], v[184:187], v[150:153], v[46:49]
	v_mfma_f32_16x16x32_bf16 v[42:45], v[184:187], v[158:161], v[42:45]
	v_mfma_f32_16x16x32_bf16 v[38:41], v[192:195], v[150:153], v[38:41]
	v_mfma_f32_16x16x32_bf16 v[34:37], v[192:195], v[158:161], v[34:37]
	v_mfma_f32_16x16x32_bf16 v[30:33], v[162:165], v[196:199], v[30:33]
	v_mfma_f32_16x16x32_bf16 v[26:29], v[162:165], v[204:207], v[26:29]
	v_mfma_f32_16x16x32_bf16 v[22:25], v[170:173], v[196:199], v[22:25]
	v_mfma_f32_16x16x32_bf16 v[18:21], v[170:173], v[204:207], v[18:21]
	v_mfma_f32_16x16x32_bf16 v[14:17], v[180:183], v[196:199], v[14:17]
	v_mfma_f32_16x16x32_bf16 v[10:13], v[180:183], v[204:207], v[10:13]
	v_mfma_f32_16x16x32_bf16 v[6:9], v[188:191], v[196:199], v[6:9]
	v_mfma_f32_16x16x32_bf16 v[2:5], v[188:191], v[204:207], v[2:5]
	v_mfma_f32_16x16x32_bf16 v[30:33], v[166:169], v[200:203], v[30:33]
	v_mfma_f32_16x16x32_bf16 v[26:29], v[166:169], v[208:211], v[26:29]
	v_mfma_f32_16x16x32_bf16 v[22:25], v[174:177], v[200:203], v[22:25]
	v_mfma_f32_16x16x32_bf16 v[18:21], v[174:177], v[208:211], v[18:21]
	v_mfma_f32_16x16x32_bf16 v[14:17], v[184:187], v[200:203], v[14:17]
	v_mfma_f32_16x16x32_bf16 v[10:13], v[184:187], v[208:211], v[10:13]
	v_mfma_f32_16x16x32_bf16 v[6:9], v[192:195], v[200:203], v[6:9]
	v_mfma_f32_16x16x32_bf16 v[2:5], v[192:195], v[208:211], v[2:5]
	s_setprio 0
	s_barrier
; #define WAIT_V(n) asm volatile("s_waitcnt vmcnt(" #n ")" ::: "memory")
; #define WAIT_L(n) asm volatile("s_waitcnt lgkmcnt(" #n ")" ::: "memory")
; #define BAR __builtin_amdgcn_s_barrier()
; #define STG_A(b, h, kt) stage_half_s(lds0 + ((b) * 2 + (h)) * HT_B, ((h) ? A1 : Ap) + (kt) * BK, off0, off1)
; #define STG_A(b, h, kt) stage_half_s(lds0 + ((b) * 2 + (h)) * HT_B, ((h) ? A1 : Ap) + (kt) * BK, off0, off1)
; #define LDA8(b, h) _Pragma("unroll") for (int m = 0; m < 4; ++m) _Pragma("unroll") for (int k = 0; k < 2; ++k) \
;     At[m][k] = *(const bf16x8*)(SA_(shm, b, h) + abase + (m * 2 + k) * 1024)
; #define LDB8(dst, b, h) _Pragma("unroll") for (int n = 0; n < 2; ++n) _Pragma("unroll") for (int k = 0; k < 2; ++k) \
;     dst[n][k] = *(const bf16x8*)(SB_(shm, b, h) + bbase + (n * 2 + k) * 1024)
; #define MMA8(ai, bj, Bx) do { __builtin_amdgcn_s_setprio(1); \
;     _Pragma("unroll") for (int m = 0; m < 4; ++m) _Pragma("unroll") for (int n = 0; n < 2; ++n) _Pragma("unroll") for (int k = 0; k < 2; ++k) \
;       acc[ai][bj][m][n] = __builtin_amdgcn_mfma_f32_16x16x32_bf16(At[m][k], Bx[n][k], acc[ai][bj][m][n], 0, 0, 0); \
;     __builtin_amdgcn_s_setprio(0); } while (0)
; template <bool HS>
; __device__ __forceinline__ void gemm_tile8(const u16* __restrict__ Ap, const u16* __restrict__ Bp, int K,
;                                            f32x4 (&acc)[2][2][4][2], char* shm, const int tid, const float* hsr = nullptr) {
;     ...
;     WAIT_V(6); BAR; MMA8(1, 1, B1); BAR;
;   }
;   { LDB8(B0, 0, 0); LDA8(0, 0); STG_A(1, 1, nt - 1);
;     BAR; WAIT_L(0); MMA8(0, 0, B0); BAR;
;     LDB8(B1, 0, 1); BAR; WAIT_L(0); MMA8(0, 1, B1); BAR;
;     LDA8(0, 1); WAIT_V(4); BAR; WAIT_L(0); MMA8(1, 0, B0); MMA8(1, 1, B1); BAR; }
	s_add_u32 s16, s16, 0x100
	s_addc_u32 s17, s17, 0
	s_add_u32 s18, s18, 0x100
	s_addc_u32 s19, s19, 0
	s_add_u32 s20, s20, 0x100
	s_addc_u32 s21, s21, 0
	s_add_u32 s22, s22, 0x100
	s_addc_u32 s23, s23, 0
	s_sub_i32 s14, s14, 1
	s_cmp_lg_u32 s14, 0
	s_cbranch_scc1 .Lk_ffn_in
	v_add_u32_e32 v158, 0x10000, v145
	ds_read_b128 v[146:149], v158
	ds_read_b128 v[150:153], v158 offset:1024
	ds_read_b128 v[154:157], v158 offset:2048
	ds_read_b128 v[158:161], v158 offset:3072
	ds_read_b128 v[162:165], v142
	ds_read_b128 v[166:169], v142 offset:1024
	ds_read_b128 v[170:173], v142 offset:2048
	ds_read_b128 v[174:177], v142 offset:3072
	ds_read_b128 v[180:183], v142 offset:4096
	ds_read_b128 v[184:187], v142 offset:5120
	ds_read_b128 v[188:191], v142 offset:6144
	ds_read_b128 v[192:195], v142 offset:7168
	v_add_u32_e32 v208, 0x14000, v145
	ds_read_b128 v[196:199], v208
	ds_read_b128 v[200:203], v208 offset:1024
	ds_read_b128 v[204:207], v208 offset:2048
	ds_read_b128 v[208:211], v208 offset:3072
	s_add_u32 s0, s18, 0x80
	s_addc_u32 s1, s19, 0
	s_add_i32 s3, s7, 0xc000
	s_mov_b32 m0, s3
	s_nop 0
	global_load_lds_dwordx4 v144, s[0:1]
	s_add_i32 s3, s7, 0xe000
	s_mov_b32 m0, s3
	s_nop 0
	global_load_lds_dwordx4 v143, s[0:1]
	s_waitcnt vmcnt(8) lgkmcnt(0)
	s_barrier
	s_setprio 1
	v_mfma_f32_16x16x32_bf16 v[126:129], v[162:165], v[146:149], v[126:129]
	v_mfma_f32_16x16x32_bf16 v[122:125], v[162:165], v[154:157], v[122:125]
	v_mfma_f32_16x16x32_bf16 v[118:121], v[170:173], v[146:149], v[118:121]
	v_mfma_f32_16x16x32_bf16 v[114:117], v[170:173], v[154:157], v[114:117]
	v_mfma_f32_16x16x32_bf16 v[110:113], v[180:183], v[146:149], v[110:113]
	v_mfma_f32_16x16x32_bf16 v[106:109], v[180:183], v[154:157], v[106:109]
	v_mfma_f32_16x16x32_bf16 v[102:105], v[188:191], v[146:149], v[102:105]
	v_mfma_f32_16x16x32_bf16 v[98:101], v[188:191], v[154:157], v[98:101]
	v_mfma_f32_16x16x32_bf16 v[126:129], v[166:169], v[150:153], v[126:129]
	v_mfma_f32_16x16x32_bf16 v[122:125], v[166:169], v[158:161], v[122:125]
	v_mfma_f32_16x16x32_bf16 v[118:121], v[174:177], v[150:153], v[118:121]
	v_mfma_f32_16x16x32_bf16 v[114:117], v[174:177], v[158:161], v[114:117]
	v_mfma_f32_16x16x32_bf16 v[110:113], v[184:187], v[150:153], v[110:113]
	v_mfma_f32_16x16x32_bf16 v[106:109], v[184:187], v[158:161], v[106:109]
	v_mfma_f32_16x16x32_bf16 v[102:105], v[192:195], v[150:153], v[102:105]
	v_mfma_f32_16x16x32_bf16 v[98:101], v[192:195], v[158:161], v[98:101]
	v_mfma_f32_16x16x32_bf16 v[94:97], v[162:165], v[196:199], v[94:97]
	v_mfma_f32_16x16x32_bf16 v[90:93], v[162:165], v[204:207], v[90:93]
	v_mfma_f32_16x16x32_bf16 v[86:89], v[170:173], v[196:199], v[86:89]
	v_mfma_f32_16x16x32_bf16 v[82:85], v[170:173], v[204:207], v[82:85]
	v_mfma_f32_16x16x32_bf16 v[78:81], v[180:183], v[196:199], v[78:81]
	v_mfma_f32_16x16x32_bf16 v[74:77], v[180:183], v[204:207], v[74:77]
	v_mfma_f32_16x16x32_bf16 v[70:73], v[188:191], v[196:199], v[70:73]
	v_mfma_f32_16x16x32_bf16 v[66:69], v[188:191], v[204:207], v[66:69]
	v_mfma_f32_16x16x32_bf16 v[94:97], v[166:169], v[200:203], v[94:97]
	v_mfma_f32_16x16x32_bf16 v[90:93], v[166:169], v[208:211], v[90:93]
	v_mfma_f32_16x16x32_bf16 v[86:89], v[174:177], v[200:203], v[86:89]
	v_mfma_f32_16x16x32_bf16 v[82:85], v[174:177], v[208:211], v[82:85]
	v_mfma_f32_16x16x32_bf16 v[78:81], v[184:187], v[200:203], v[78:81]
	v_mfma_f32_16x16x32_bf16 v[74:77], v[184:187], v[208:211], v[74:77]
	v_mfma_f32_16x16x32_bf16 v[70:73], v[192:195], v[200:203], v[70:73]
	v_mfma_f32_16x16x32_bf16 v[66:69], v[192:195], v[208:211], v[66:69]
	s_setprio 0
	s_barrier
	ds_read_b128 v[162:165], v142 offset:16384
	ds_read_b128 v[166:169], v142 offset:17408
	ds_read_b128 v[170:173], v142 offset:18432
	ds_read_b128 v[174:177], v142 offset:19456
	ds_read_b128 v[180:183], v142 offset:20480
	ds_read_b128 v[184:187], v142 offset:21504
	ds_read_b128 v[188:191], v142 offset:22528
	ds_read_b128 v[192:195], v142 offset:23552
	s_waitcnt vmcnt(2) lgkmcnt(0)
	s_barrier
	s_setprio 1
	v_mfma_f32_16x16x32_bf16 v[62:65], v[162:165], v[146:149], v[62:65]
	v_mfma_f32_16x16x32_bf16 v[58:61], v[162:165], v[154:157], v[58:61]
	v_mfma_f32_16x16x32_bf16 v[54:57], v[170:173], v[146:149], v[54:57]
	v_mfma_f32_16x16x32_bf16 v[50:53], v[170:173], v[154:157], v[50:53]
	v_mfma_f32_16x16x32_bf16 v[46:49], v[180:183], v[146:149], v[46:49]
	v_mfma_f32_16x16x32_bf16 v[42:45], v[180:183], v[154:157], v[42:45]
	v_mfma_f32_16x16x32_bf16 v[38:41], v[188:191], v[146:149], v[38:41]
	v_mfma_f32_16x16x32_bf16 v[34:37], v[188:191], v[154:157], v[34:37]
	v_mfma_f32_16x16x32_bf16 v[62:65], v[166:169], v[150:153], v[62:65]
	v_mfma_f32_16x16x32_bf16 v[58:61], v[166:169], v[158:161], v[58:61]
	v_mfma_f32_16x16x32_bf16 v[54:57], v[174:177], v[150:153], v[54:57]
	v_mfma_f32_16x16x32_bf16 v[50:53], v[174:177], v[158:161], v[50:53]
	v_mfma_f32_16x16x32_bf16 v[46:49], v[184:187], v[150:153], v[46:49]
	v_mfma_f32_16x16x32_bf16 v[42:45], v[184:187], v[158:161], v[42:45]
	v_mfma_f32_16x16x32_bf16 v[38:41], v[192:195], v[150:153], v[38:41]
	v_mfma_f32_16x16x32_bf16 v[34:37], v[192:195], v[158:161], v[34:37]
	v_mfma_f32_16x16x32_bf16 v[30:33], v[162:165], v[196:199], v[30:33]
	v_mfma_f32_16x16x32_bf16 v[26:29], v[162:165], v[204:207], v[26:29]
	v_mfma_f32_16x16x32_bf16 v[22:25], v[170:173], v[196:199], v[22:25]
	v_mfma_f32_16x16x32_bf16 v[18:21], v[170:173], v[204:207], v[18:21]
	v_mfma_f32_16x16x32_bf16 v[14:17], v[180:183], v[196:199], v[14:17]
	v_mfma_f32_16x16x32_bf16 v[10:13], v[180:183], v[204:207], v[10:13]
	v_mfma_f32_16x16x32_bf16 v[6:9], v[188:191], v[196:199], v[6:9]
	v_mfma_f32_16x16x32_bf16 v[2:5], v[188:191], v[204:207], v[2:5]
	v_mfma_f32_16x16x32_bf16 v[30:33], v[166:169], v[200:203], v[30:33]
	v_mfma_f32_16x16x32_bf16 v[26:29], v[166:169], v[208:211], v[26:29]
	v_mfma_f32_16x16x32_bf16 v[22:25], v[174:177], v[200:203], v[22:25]
	v_mfma_f32_16x16x32_bf16 v[18:21], v[174:177], v[208:211], v[18:21]
	v_mfma_f32_16x16x32_bf16 v[14:17], v[184:187], v[200:203], v[14:17]
	v_mfma_f32_16x16x32_bf16 v[10:13], v[184:187], v[208:211], v[10:13]
	v_mfma_f32_16x16x32_bf16 v[6:9], v[192:195], v[200:203], v[6:9]
	v_mfma_f32_16x16x32_bf16 v[2:5], v[192:195], v[208:211], v[2:5]
	s_setprio 0
	s_barrier
; #define WAIT_V(n) asm volatile("s_waitcnt vmcnt(" #n ")" ::: "memory")
; #define WAIT_L(n) asm volatile("s_waitcnt lgkmcnt(" #n ")" ::: "memory")
; #define BAR __builtin_amdgcn_s_barrier()
; #define LDA8(b, h) _Pragma("unroll") for (int m = 0; m < 4; ++m) _Pragma("unroll") for (int k = 0; k < 2; ++k) \
;     At[m][k] = *(const bf16x8*)(SA_(shm, b, h) + abase + (m * 2 + k) * 1024)
; #define LDB8(dst, b, h) _Pragma("unroll") for (int n = 0; n < 2; ++n) _Pragma("unroll") for (int k = 0; k < 2; ++k) \
;     dst[n][k] = *(const bf16x8*)(SB_(shm, b, h) + bbase + (n * 2 + k) * 1024)
; #define MMA8(ai, bj, Bx) do { __builtin_amdgcn_s_setprio(1); \
;     _Pragma("unroll") for (int m = 0; m < 4; ++m) _Pragma("unroll") for (int n = 0; n < 2; ++n) _Pragma("unroll") for (int k = 0; k < 2; ++k) \
;       acc[ai][bj][m][n] = __builtin_amdgcn_mfma_f32_16x16x32_bf16(At[m][k], Bx[n][k], acc[ai][bj][m][n], 0, 0, 0); \
;     __builtin_amdgcn_s_setprio(0); } while (0)
; template <bool HS>
; __device__ __forceinline__ void gemm_tile8(const u16* __restrict__ Ap, const u16* __restrict__ Bp, int K,
;                                            f32x4 (&acc)[2][2][4][2], char* shm, const int tid, const float* hsr = nullptr) {
;     ...
;   { LDB8(B0, 1, 0); LDA8(1, 0); WAIT_V(2); BAR; WAIT_L(0); MMA8(0, 0, B0); BAR;
;     LDB8(B1, 1, 1); WAIT_V(0); BAR; WAIT_L(0); MMA8(0, 1, B1); BAR;
;     LDA8(1, 1); BAR; WAIT_L(0); MMA8(1, 0, B0); MMA8(1, 1, B1); BAR; }
;   if (wr == 0) BAR;
	v_add_u32_e32 v158, 0x18000, v145
	ds_read_b128 v[146:149], v158
	ds_read_b128 v[150:153], v158 offset:1024
	ds_read_b128 v[154:157], v158 offset:2048
	ds_read_b128 v[158:161], v158 offset:3072
	ds_read_b128 v[162:165], v142 offset:32768
	ds_read_b128 v[166:169], v142 offset:33792
	ds_read_b128 v[170:173], v142 offset:34816
	ds_read_b128 v[174:177], v142 offset:35840
	ds_read_b128 v[180:183], v142 offset:36864
	ds_read_b128 v[184:187], v142 offset:37888
	ds_read_b128 v[188:191], v142 offset:38912
	ds_read_b128 v[192:195], v142 offset:39936
	v_add_u32_e32 v208, 0x1c000, v145
	ds_read_b128 v[196:199], v208
	ds_read_b128 v[200:203], v208 offset:1024
	ds_read_b128 v[204:207], v208 offset:2048
	ds_read_b128 v[208:211], v208 offset:3072
	s_waitcnt vmcnt(0) lgkmcnt(0)
	s_barrier
	s_setprio 1
	v_mfma_f32_16x16x32_bf16 v[126:129], v[162:165], v[146:149], v[126:129]
	v_mfma_f32_16x16x32_bf16 v[122:125], v[162:165], v[154:157], v[122:125]
	v_mfma_f32_16x16x32_bf16 v[118:121], v[170:173], v[146:149], v[118:121]
	v_mfma_f32_16x16x32_bf16 v[114:117], v[170:173], v[154:157], v[114:117]
	v_mfma_f32_16x16x32_bf16 v[110:113], v[180:183], v[146:149], v[110:113]
	v_mfma_f32_16x16x32_bf16 v[106:109], v[180:183], v[154:157], v[106:109]
	v_mfma_f32_16x16x32_bf16 v[102:105], v[188:191], v[146:149], v[102:105]
	v_mfma_f32_16x16x32_bf16 v[98:101], v[188:191], v[154:157], v[98:101]
	v_mfma_f32_16x16x32_bf16 v[126:129], v[166:169], v[150:153], v[126:129]
	v_mfma_f32_16x16x32_bf16 v[122:125], v[166:169], v[158:161], v[122:125]
	v_mfma_f32_16x16x32_bf16 v[118:121], v[174:177], v[150:153], v[118:121]
	v_mfma_f32_16x16x32_bf16 v[114:117], v[174:177], v[158:161], v[114:117]
	v_mfma_f32_16x16x32_bf16 v[110:113], v[184:187], v[150:153], v[110:113]
	v_mfma_f32_16x16x32_bf16 v[106:109], v[184:187], v[158:161], v[106:109]
	v_mfma_f32_16x16x32_bf16 v[102:105], v[192:195], v[150:153], v[102:105]
	v_mfma_f32_16x16x32_bf16 v[98:101], v[192:195], v[158:161], v[98:101]
	v_mfma_f32_16x16x32_bf16 v[94:97], v[162:165], v[196:199], v[94:97]
	v_mfma_f32_16x16x32_bf16 v[90:93], v[162:165], v[204:207], v[90:93]
	v_mfma_f32_16x16x32_bf16 v[86:89], v[170:173], v[196:199], v[86:89]
	v_mfma_f32_16x16x32_bf16 v[82:85], v[170:173], v[204:207], v[82:85]
	v_mfma_f32_16x16x32_bf16 v[78:81], v[180:183], v[196:199], v[78:81]
	v_mfma_f32_16x16x32_bf16 v[74:77], v[180:183], v[204:207], v[74:77]
	v_mfma_f32_16x16x32_bf16 v[70:73], v[188:191], v[196:199], v[70:73]
	v_mfma_f32_16x16x32_bf16 v[66:69], v[188:191], v[204:207], v[66:69]
	v_mfma_f32_16x16x32_bf16 v[94:97], v[166:169], v[200:203], v[94:97]
	v_mfma_f32_16x16x32_bf16 v[90:93], v[166:169], v[208:211], v[90:93]
	v_mfma_f32_16x16x32_bf16 v[86:89], v[174:177], v[200:203], v[86:89]
	v_mfma_f32_16x16x32_bf16 v[82:85], v[174:177], v[208:211], v[82:85]
	v_mfma_f32_16x16x32_bf16 v[78:81], v[184:187], v[200:203], v[78:81]
	v_mfma_f32_16x16x32_bf16 v[74:77], v[184:187], v[208:211], v[74:77]
	v_mfma_f32_16x16x32_bf16 v[70:73], v[192:195], v[200:203], v[70:73]
	v_mfma_f32_16x16x32_bf16 v[66:69], v[192:195], v[208:211], v[66:69]
	s_setprio 0
	s_barrier
	ds_read_b128 v[162:165], v142 offset:49152
	ds_read_b128 v[166:169], v142 offset:50176
	ds_read_b128 v[170:173], v142 offset:51200
	ds_read_b128 v[174:177], v142 offset:52224
	ds_read_b128 v[180:183], v142 offset:53248
	ds_read_b128 v[184:187], v142 offset:54272
	ds_read_b128 v[188:191], v142 offset:55296
	ds_read_b128 v[192:195], v142 offset:56320
	s_waitcnt lgkmcnt(0)
	s_barrier
	s_setprio 1
	v_mfma_f32_16x16x32_bf16 v[62:65], v[162:165], v[146:149], v[62:65]
	v_mfma_f32_16x16x32_bf16 v[58:61], v[162:165], v[154:157], v[58:61]
	v_mfma_f32_16x16x32_bf16 v[54:57], v[170:173], v[146:149], v[54:57]
	v_mfma_f32_16x16x32_bf16 v[50:53], v[170:173], v[154:157], v[50:53]
	v_mfma_f32_16x16x32_bf16 v[46:49], v[180:183], v[146:149], v[46:49]
	v_mfma_f32_16x16x32_bf16 v[42:45], v[180:183], v[154:157], v[42:45]
	v_mfma_f32_16x16x32_bf16 v[38:41], v[188:191], v[146:149], v[38:41]
	v_mfma_f32_16x16x32_bf16 v[34:37], v[188:191], v[154:157], v[34:37]
	v_mfma_f32_16x16x32_bf16 v[62:65], v[166:169], v[150:153], v[62:65]
	v_mfma_f32_16x16x32_bf16 v[58:61], v[166:169], v[158:161], v[58:61]
	v_mfma_f32_16x16x32_bf16 v[54:57], v[174:177], v[150:153], v[54:57]
	v_mfma_f32_16x16x32_bf16 v[50:53], v[174:177], v[158:161], v[50:53]
	v_mfma_f32_16x16x32_bf16 v[46:49], v[184:187], v[150:153], v[46:49]
	v_mfma_f32_16x16x32_bf16 v[42:45], v[184:187], v[158:161], v[42:45]
	v_mfma_f32_16x16x32_bf16 v[38:41], v[192:195], v[150:153], v[38:41]
	v_mfma_f32_16x16x32_bf16 v[34:37], v[192:195], v[158:161], v[34:37]
	v_mfma_f32_16x16x32_bf16 v[30:33], v[162:165], v[196:199], v[30:33]
	v_mfma_f32_16x16x32_bf16 v[26:29], v[162:165], v[204:207], v[26:29]
	v_mfma_f32_16x16x32_bf16 v[22:25], v[170:173], v[196:199], v[22:25]
	v_mfma_f32_16x16x32_bf16 v[18:21], v[170:173], v[204:207], v[18:21]
	v_mfma_f32_16x16x32_bf16 v[14:17], v[180:183], v[196:199], v[14:17]
	v_mfma_f32_16x16x32_bf16 v[10:13], v[180:183], v[204:207], v[10:13]
	v_mfma_f32_16x16x32_bf16 v[6:9], v[188:191], v[196:199], v[6:9]
	v_mfma_f32_16x16x32_bf16 v[2:5], v[188:191], v[204:207], v[2:5]
	v_mfma_f32_16x16x32_bf16 v[30:33], v[166:169], v[200:203], v[30:33]
	v_mfma_f32_16x16x32_bf16 v[26:29], v[166:169], v[208:211], v[26:29]
	v_mfma_f32_16x16x32_bf16 v[22:25], v[174:177], v[200:203], v[22:25]
	v_mfma_f32_16x16x32_bf16 v[18:21], v[174:177], v[208:211], v[18:21]
	v_mfma_f32_16x16x32_bf16 v[14:17], v[184:187], v[200:203], v[14:17]
	v_mfma_f32_16x16x32_bf16 v[10:13], v[184:187], v[208:211], v[10:13]
	v_mfma_f32_16x16x32_bf16 v[6:9], v[192:195], v[200:203], v[6:9]
	v_mfma_f32_16x16x32_bf16 v[2:5], v[192:195], v[208:211], v[2:5]
	s_setprio 0
	s_movk_i32 s0, 0x100
	v_cmp_gt_u32_e32 vcc, s0, v0
	s_barrier
	s_and_saveexec_b64 s[0:1], vcc
	s_cbranch_execz .LBB0_862
	s_barrier
